# full stack: attn loop + scan gates + qkv up-proj LDS prefetch ring + scan/GEMM counted vmcnt + pipelined P6 epilogue
# speedup vs baseline: 1.0047x; 1.0047x over previous
; template <class Epi, class Sched, bool ALIGN_EPI>
; __device__ __forceinline__ void gemm_phase(PG8_LAS unsigned char* lds, const Gemm g, const Sched& S, const Epi& E) {
;     ...
;             if constexpr (Epi::MID_T >= 0) { if (t == Epi::MID_T) E.mid(acc, cur, wr, fr); }
;     __device__ __forceinline__ void mid(f32x4 (&)[2][2][4][2], const Unit& u, int wr, int fr) const {
;         int row0 = u.pm * BM + wr * 64 + fr; asm volatile("" : "+v"(row0));
; #pragma unroll
;         for (int ai = 0; ai < 2; ++ai)
; #pragma unroll
;             for (int m = 0; m < 4; ++m) pre[ai * 4 + m] = rs1[row0 + ai * HALF + m * 16];
;     }
.LBB0_149:
	s_cmp_eq_u32 s79, 12
	s_cselect_b64 s[8:9], -1, 0
	s_cmp_lg_u32 s79, 12
	s_cbranch_scc1 .LBB0_148
	s_waitcnt vmcnt(8)
	v_mov_b32_e32 v144, v156
	s_nop 0
	v_ashrrev_i32_e32 v145, 31, v144
	v_lshl_add_u64 v[158:159], v[144:145], 2, s[34:35]
	global_load_dword v144, v[158:159], off
	global_load_dword v146, v[158:159], off offset:64
	global_load_dword v148, v[158:159], off offset:128
	global_load_dword v150, v[158:159], off offset:192
	global_load_dword v152, v[158:159], off offset:512
	global_load_dword v153, v[158:159], off offset:576
	global_load_dword v154, v[158:159], off offset:640
	global_load_dword v155, v[158:159], off offset:704
	s_branch .LBB0_148

; __device__ __forceinline__ unsigned cvt_pk(float lo, float hi) { unsigned r; asm("v_cvt_pk_bf16_f32 %0, %1, %2" : "=v"(r) : "v"(lo), "v"(hi)); return r; }
; __device__ __forceinline__ void fadd_atomic(float* p, float v) { __hip_atomic_fetch_add(p, v, __ATOMIC_RELAXED, __HIP_MEMORY_SCOPE_AGENT); }
;     __device__ __forceinline__ void operator()(const f32x4 (&acc)[2][2][4][2], const Unit& u, int wr, int wc, int fr, int fq) const {
;     ...
;             for (int m = 0; m < 4; ++m) { const int row = row0 + ai * HALF + m * 16; const float s = pre[ai * 4 + m];
; #pragma unroll
;                 for (int bj = 0; bj < 2; ++bj) { const int hc = u.pn * 2 + bj; const int col = u.pn * BM + bj * HALF + wc * 32 + 8 * fq;
;                     const f32x4 v0 = acc[ai][bj][m][0] * s, v1 = acc[ai][bj][m][1] * s;
;                     u32x4 w; w.x = cvt_pk(v0[0], v0[1]); w.y = cvt_pk(v0[2], v0[3]); w.z = cvt_pk(v1[0], v1[1]); w.w = cvt_pk(v1[2], v1[3]);
;                     *(u32x4*)(P + (size_t)row * INP + col) = w;
;                     if (hc < 5) { float q = (v0[0] * v0[0] + v0[1] * v0[1]) + (v0[2] * v0[2] + v0[3] * v0[3]) + (v1[0] * v1[0] + v1[1] * v1[1]) + (v1[2] * v1[2] + v1[3] * v1[3]);
;                         q += __shfl_xor(q, 16); q += __shfl_xor(q, 32);
;                         if (fq == 0) fadd_atomic((hc < 3 ? ss_cq : ss_ckv) + row, q); } } }
.LBB0_153:
	v_lshl_or_b32 v158, s14, 8, v166
	s_waitcnt vmcnt(8)
	v_pk_mul_f32 v[160:161], v[124:125], v[144:145] op_sel_hi:[1,0]
	v_pk_mul_f32 v[124:125], v[120:121], v[144:145] op_sel_hi:[1,0]
	v_mov_b64_e32 v[120:121], s[30:31]
	v_ashrrev_i32_e32 v159, 31, v158
	v_mad_i64_i32 v[120:121], s[0:1], v156, s73, v[120:121]
	s_cmp_lt_i32 s14, 3
	v_ashrrev_i32_e32 v157, 31, v156
	v_pk_mul_f32 v[126:127], v[126:127], v[144:145] op_sel_hi:[1,0]
	v_pk_mul_f32 v[122:123], v[122:123], v[144:145] op_sel_hi:[1,0]
	v_lshl_add_u64 v[120:121], v[158:159], 1, v[120:121]
	s_cselect_b64 s[8:9], -1, 0
	s_cmp_gt_i32 s14, 2
	v_cvt_pk_bf16_f32 v170, v160, v161
	v_cvt_pk_bf16_f32 v171, v126, v127
	v_cvt_pk_bf16_f32 v172, v124, v125
	v_cvt_pk_bf16_f32 v173, v122, v123
	global_store_dwordx4 v[120:121], v[170:173], off
	s_cbranch_scc1 .LBB0_157
	v_mul_f32_e32 v145, v161, v161
	v_mul_f32_e32 v127, v127, v127
	v_fmac_f32_e32 v145, v160, v160
	v_fmac_f32_e32 v127, v126, v126
	v_mul_f32_e32 v125, v125, v125
	v_add_f32_e32 v126, v145, v127
	v_fmac_f32_e32 v125, v124, v124
	v_mul_f32_e32 v123, v123, v123
	v_add_f32_e32 v124, v125, v126
	v_fmac_f32_e32 v123, v122, v122
	v_add_f32_e32 v122, v123, v124
	v_and_b32_e32 v124, 64, v168
	v_xor_b32_e32 v123, 16, v168
	v_add_u32_e32 v124, 64, v124
	v_cmp_lt_i32_e32 vcc, v123, v124
	s_nop 1
	v_cndmask_b32_e32 v123, v168, v123, vcc
	v_lshlrev_b32_e32 v123, 2, v123
	ds_bpermute_b32 v123, v123, v122
	s_waitcnt lgkmcnt(0)
	v_add_f32_e32 v122, v122, v123
	v_xor_b32_e32 v123, 32, v168
	v_cmp_lt_i32_e32 vcc, v123, v124
	s_nop 1
	v_cndmask_b32_e32 v123, v168, v123, vcc
	v_lshlrev_b32_e32 v123, 2, v123
	ds_bpermute_b32 v123, v123, v122
	s_and_saveexec_b64 s[0:1], s[2:3]
	s_cbranch_execz .LBB0_156
	s_cmp_eq_u32 s14, 2
	s_cselect_b32 s65, s19, s23
	s_cselect_b32 s74, s97, s22
	v_mov_b32_e32 v124, s74
	v_mov_b32_e32 v125, s65
	v_lshl_add_u64 v[124:125], v[156:157], 2, v[124:125]
	s_waitcnt lgkmcnt(0)
	v_add_f32_e32 v122, v122, v123
	global_atomic_add_f32 v[124:125], v122, off

; #define LAS __attribute__((address_space(3)))
; #define MFMA16(a, b, c) __builtin_amdgcn_mfma_f32_16x16x32_bf16((a), (b), (c), 0, 0, 0)
; __device__ __forceinline__ void qkv_head_unit(const Params& p, LAS unsigned char* lds, int h, int blk_begin, int blk_end) {
;     ...
;         for (int pb = blk_begin + 2 * w; pb < blk_end; pb += 16) {
;             const bool two = (pb + 1) < blk_end;
;             const int blk1 = two ? pb + 1 : pb;
;             const int rowm[2] = {16 * pb + fr, 16 * blk1 + fr};
;             bf16x8 af[2][12]; float ssv[2];
; #pragma unroll
;             for (int m = 0; m < 2; ++m) { ssv[m] = ss_cq[rowm[m]];
; #pragma unroll
;                 for (int ks = 0; ks < 12; ++ks) af[m][ks] = *(const bf16x8*)(P + (size_t)rowm[m] * INP + 32 * ks + 8 * fq); }
;             f32x4 acc[2][6];
; #pragma unroll
;             for (int m = 0; m < 2; ++m)
; #pragma unroll
;                 for (int n = 0; n < 6; ++n) acc[m][n] = (f32x4){0.f, 0.f, 0.f, 0.f};
; #pragma unroll
;             for (int ks = 0; ks < 12; ++ks)
; #pragma unroll
;                 for (int n = 0; n < 6; ++n) { const bf16x8 bw = *(const LAS bf16x8*)(wl + (16 * n + fr) * WQS + 32 * ks + 8 * fq);
;                     acc[0][n] = MFMA16(bw, af[0][ks], acc[0][n]); acc[1][n] = MFMA16(bw, af[1][ks], acc[1][n]); }
.LBB0_506:
	v_add_u32_e32 v0, 1, v176
	v_cmp_gt_i32_e64 s[2:3], s12, v0
	v_add_u32_e32 v126, s14, v175
	v_ashrrev_i32_e32 v127, 31, v126
	v_cndmask_b32_e64 v0, v176, v0, s[2:3]
	v_lshlrev_b32_e32 v177, 4, v0
	v_or_b32_e32 v124, v177, v158
	v_lshl_add_u64 v[26:27], v[126:127], 2, s[22:23]
	v_ashrrev_i32_e32 v125, 31, v124
	global_load_dword v0, v[26:27], off
	v_mad_i64_i32 v[26:27], s[0:1], v126, s89, v[116:117]
	v_lshl_add_u64 v[30:31], v[124:125], 2, s[22:23]
	global_load_dwordx4 v[178:181], v[26:27], off
	global_load_dwordx4 v[106:109], v[26:27], off offset:64
	global_load_dwordx4 v[98:101], v[26:27], off offset:128
	global_load_dwordx4 v[90:93], v[26:27], off offset:192
	global_load_dwordx4 v[82:85], v[26:27], off offset:256
	global_load_dwordx4 v[74:77], v[26:27], off offset:320
	global_load_dwordx4 v[66:69], v[26:27], off offset:384
	global_load_dwordx4 v[58:61], v[26:27], off offset:448
	global_load_dwordx4 v[50:53], v[26:27], off offset:512
	global_load_dwordx4 v[42:45], v[26:27], off offset:576
	global_load_dwordx4 v[34:37], v[26:27], off offset:640
	s_nop 0
	global_load_dwordx4 v[26:29], v[26:27], off offset:704
	global_load_dword v125, v[30:31], off
	v_mad_i64_i32 v[30:31], s[0:1], v124, s89, v[116:117]
	global_load_dwordx4 v[182:185], v[30:31], off
	global_load_dwordx4 v[110:113], v[30:31], off offset:64
	global_load_dwordx4 v[102:105], v[30:31], off offset:128
	global_load_dwordx4 v[94:97], v[30:31], off offset:192
	global_load_dwordx4 v[86:89], v[30:31], off offset:256
	global_load_dwordx4 v[78:81], v[30:31], off offset:320
	global_load_dwordx4 v[70:73], v[30:31], off offset:384
	global_load_dwordx4 v[62:65], v[30:31], off offset:448
	global_load_dwordx4 v[54:57], v[30:31], off offset:512
	global_load_dwordx4 v[46:49], v[30:31], off offset:576
	global_load_dwordx4 v[38:41], v[30:31], off offset:640
	s_nop 0
	global_load_dwordx4 v[30:33], v[30:31], off offset:704
	ds_read_b128 v[226:229], v165 offset:0
	ds_read_b128 v[230:233], v165 offset:12544
	ds_read_b128 v[234:237], v165 offset:25088
	ds_read_b128 v[238:241], v165 offset:37632
	s_waitcnt lgkmcnt(3)
	s_waitcnt vmcnt(24)
	v_mfma_f32_16x16x32_bf16 v[186:189], v[226:229], v[178:181], 0
	v_fmamk_f32 v0, v0, 0x3b2aaaab, v140
	v_rsq_f32_e32 v0, v0
	s_waitcnt vmcnt(11)
	v_mfma_f32_16x16x32_bf16 v[190:193], v[226:229], v[182:185], 0
	ds_read_b128 v[226:229], v165 offset:50176
	s_waitcnt lgkmcnt(3)
	v_mfma_f32_16x16x32_bf16 v[194:197], v[230:233], v[178:181], 0
	v_mfma_f32_16x16x32_bf16 v[198:201], v[230:233], v[182:185], 0
	ds_read_b128 v[230:233], v165 offset:62720
	s_waitcnt lgkmcnt(3)
	v_mfma_f32_16x16x32_bf16 v[202:205], v[234:237], v[178:181], 0
	v_mfma_f32_16x16x32_bf16 v[206:209], v[234:237], v[182:185], 0
	ds_read_b128 v[234:237], v165 offset:64
	s_waitcnt lgkmcnt(3)
	v_mfma_f32_16x16x32_bf16 v[210:213], v[238:241], v[178:181], 0
	v_mfma_f32_16x16x32_bf16 v[214:217], v[238:241], v[182:185], 0
	ds_read_b128 v[238:241], v165 offset:12608
	s_waitcnt lgkmcnt(3)
	v_mfma_f32_16x16x32_bf16 v[218:221], v[226:229], v[178:181], 0
	v_mfma_f32_16x16x32_bf16 v[222:225], v[226:229], v[182:185], 0
	ds_read_b128 v[226:229], v165 offset:25152
	s_waitcnt lgkmcnt(3)
	v_mfma_f32_16x16x32_bf16 v[178:181], v[230:233], v[178:181], 0
	v_mfma_f32_16x16x32_bf16 v[182:185], v[230:233], v[182:185], 0
	ds_read_b128 v[230:233], v165 offset:37696
	s_waitcnt lgkmcnt(3)
	s_waitcnt vmcnt(10)
	v_mfma_f32_16x16x32_bf16 v[186:189], v[234:237], v[106:109], v[186:189]
	v_mfma_f32_16x16x32_bf16 v[190:193], v[234:237], v[110:113], v[190:193]
	ds_read_b128 v[234:237], v165 offset:50240
	s_waitcnt lgkmcnt(3)
	v_mfma_f32_16x16x32_bf16 v[194:197], v[238:241], v[106:109], v[194:197]
	v_mfma_f32_16x16x32_bf16 v[198:201], v[238:241], v[110:113], v[198:201]
	ds_read_b128 v[238:241], v165 offset:62784
	s_waitcnt lgkmcnt(3)
	v_mfma_f32_16x16x32_bf16 v[202:205], v[226:229], v[106:109], v[202:205]
	v_mfma_f32_16x16x32_bf16 v[206:209], v[226:229], v[110:113], v[206:209]
	ds_read_b128 v[226:229], v165 offset:128
	s_waitcnt lgkmcnt(3)
	v_mfma_f32_16x16x32_bf16 v[210:213], v[230:233], v[106:109], v[210:213]
	v_mfma_f32_16x16x32_bf16 v[214:217], v[230:233], v[110:113], v[214:217]
	ds_read_b128 v[230:233], v165 offset:12672
	s_waitcnt lgkmcnt(3)
	v_mfma_f32_16x16x32_bf16 v[218:221], v[234:237], v[106:109], v[218:221]
	v_mfma_f32_16x16x32_bf16 v[222:225], v[234:237], v[110:113], v[222:225]
	ds_read_b128 v[234:237], v165 offset:25216
	s_waitcnt lgkmcnt(3)
	v_mfma_f32_16x16x32_bf16 v[178:181], v[238:241], v[106:109], v[178:181]
	v_mfma_f32_16x16x32_bf16 v[182:185], v[238:241], v[110:113], v[182:185]
	ds_read_b128 v[238:241], v165 offset:37760
	s_waitcnt lgkmcnt(3)
	s_waitcnt vmcnt(9)
	v_mfma_f32_16x16x32_bf16 v[186:189], v[226:229], v[98:101], v[186:189]
	v_mfma_f32_16x16x32_bf16 v[190:193], v[226:229], v[102:105], v[190:193]
	ds_read_b128 v[226:229], v165 offset:50304
	s_waitcnt lgkmcnt(3)
	v_mfma_f32_16x16x32_bf16 v[194:197], v[230:233], v[98:101], v[194:197]
	v_mfma_f32_16x16x32_bf16 v[198:201], v[230:233], v[102:105], v[198:201]
	ds_read_b128 v[230:233], v165 offset:62848
	s_waitcnt lgkmcnt(3)
	v_mfma_f32_16x16x32_bf16 v[202:205], v[234:237], v[98:101], v[202:205]
	v_mfma_f32_16x16x32_bf16 v[206:209], v[234:237], v[102:105], v[206:209]
	ds_read_b128 v[234:237], v165 offset:192
	s_waitcnt lgkmcnt(3)
	v_mfma_f32_16x16x32_bf16 v[210:213], v[238:241], v[98:101], v[210:213]
	v_mfma_f32_16x16x32_bf16 v[214:217], v[238:241], v[102:105], v[214:217]
	ds_read_b128 v[238:241], v165 offset:12736
	s_waitcnt lgkmcnt(3)
	v_mfma_f32_16x16x32_bf16 v[218:221], v[226:229], v[98:101], v[218:221]
	v_mfma_f32_16x16x32_bf16 v[222:225], v[226:229], v[102:105], v[222:225]
	ds_read_b128 v[226:229], v165 offset:25280
	s_waitcnt lgkmcnt(3)
; #define LAS __attribute__((address_space(3)))
; #define MFMA16(a, b, c) __builtin_amdgcn_mfma_f32_16x16x32_bf16((a), (b), (c), 0, 0, 0)
; __device__ __forceinline__ void qkv_head_unit(const Params& p, LAS unsigned char* lds, int h, int blk_begin, int blk_end) {
;     ...
;             for (int ks = 0; ks < 12; ++ks)
; #pragma unroll
;                 for (int n = 0; n < 6; ++n) { const bf16x8 bw = *(const LAS bf16x8*)(wl + (16 * n + fr) * WQS + 32 * ks + 8 * fq);
;                     acc[0][n] = MFMA16(bw, af[0][ks], acc[0][n]); acc[1][n] = MFMA16(bw, af[1][ks], acc[1][n]); }
	v_mfma_f32_16x16x32_bf16 v[178:181], v[230:233], v[98:101], v[178:181]
	v_mfma_f32_16x16x32_bf16 v[182:185], v[230:233], v[102:105], v[182:185]
	ds_read_b128 v[230:233], v165 offset:37824
	s_waitcnt lgkmcnt(3)
	s_waitcnt vmcnt(8)
	v_mfma_f32_16x16x32_bf16 v[186:189], v[234:237], v[90:93], v[186:189]
	v_mfma_f32_16x16x32_bf16 v[190:193], v[234:237], v[94:97], v[190:193]
	ds_read_b128 v[234:237], v165 offset:50368
	s_waitcnt lgkmcnt(3)
	v_mfma_f32_16x16x32_bf16 v[194:197], v[238:241], v[90:93], v[194:197]
	v_mfma_f32_16x16x32_bf16 v[198:201], v[238:241], v[94:97], v[198:201]
	ds_read_b128 v[238:241], v165 offset:62912
	s_waitcnt lgkmcnt(3)
	v_mfma_f32_16x16x32_bf16 v[202:205], v[226:229], v[90:93], v[202:205]
	v_mfma_f32_16x16x32_bf16 v[206:209], v[226:229], v[94:97], v[206:209]
	ds_read_b128 v[226:229], v165 offset:256
	s_waitcnt lgkmcnt(3)
	v_mfma_f32_16x16x32_bf16 v[210:213], v[230:233], v[90:93], v[210:213]
	v_mfma_f32_16x16x32_bf16 v[214:217], v[230:233], v[94:97], v[214:217]
	ds_read_b128 v[230:233], v165 offset:12800
	s_waitcnt lgkmcnt(3)
	v_mfma_f32_16x16x32_bf16 v[218:221], v[234:237], v[90:93], v[218:221]
	v_mfma_f32_16x16x32_bf16 v[222:225], v[234:237], v[94:97], v[222:225]
	ds_read_b128 v[234:237], v165 offset:25344
	s_waitcnt lgkmcnt(3)
	v_mfma_f32_16x16x32_bf16 v[178:181], v[238:241], v[90:93], v[178:181]
	v_mfma_f32_16x16x32_bf16 v[182:185], v[238:241], v[94:97], v[182:185]
	ds_read_b128 v[238:241], v165 offset:37888
	s_waitcnt lgkmcnt(3)
	s_waitcnt vmcnt(7)
	v_mfma_f32_16x16x32_bf16 v[186:189], v[226:229], v[82:85], v[186:189]
	v_mfma_f32_16x16x32_bf16 v[190:193], v[226:229], v[86:89], v[190:193]
	ds_read_b128 v[226:229], v165 offset:50432
	s_waitcnt lgkmcnt(3)
	v_mfma_f32_16x16x32_bf16 v[194:197], v[230:233], v[82:85], v[194:197]
	v_mfma_f32_16x16x32_bf16 v[198:201], v[230:233], v[86:89], v[198:201]
	ds_read_b128 v[230:233], v165 offset:62976
	s_waitcnt lgkmcnt(3)
	v_mfma_f32_16x16x32_bf16 v[202:205], v[234:237], v[82:85], v[202:205]
	v_mfma_f32_16x16x32_bf16 v[206:209], v[234:237], v[86:89], v[206:209]
	ds_read_b128 v[234:237], v165 offset:320
	s_waitcnt lgkmcnt(3)
	v_mfma_f32_16x16x32_bf16 v[210:213], v[238:241], v[82:85], v[210:213]
	v_mfma_f32_16x16x32_bf16 v[214:217], v[238:241], v[86:89], v[214:217]
	ds_read_b128 v[238:241], v165 offset:12864
	s_waitcnt lgkmcnt(3)
	v_mfma_f32_16x16x32_bf16 v[218:221], v[226:229], v[82:85], v[218:221]
	v_mfma_f32_16x16x32_bf16 v[222:225], v[226:229], v[86:89], v[222:225]
	ds_read_b128 v[226:229], v165 offset:25408
	s_waitcnt lgkmcnt(3)
	v_mfma_f32_16x16x32_bf16 v[178:181], v[230:233], v[82:85], v[178:181]
	v_mfma_f32_16x16x32_bf16 v[182:185], v[230:233], v[86:89], v[182:185]
	ds_read_b128 v[230:233], v165 offset:37952
	s_waitcnt lgkmcnt(3)
	s_waitcnt vmcnt(6)
	v_mfma_f32_16x16x32_bf16 v[186:189], v[234:237], v[74:77], v[186:189]
	v_mfma_f32_16x16x32_bf16 v[190:193], v[234:237], v[78:81], v[190:193]
	ds_read_b128 v[234:237], v165 offset:50496
	s_waitcnt lgkmcnt(3)
	v_mfma_f32_16x16x32_bf16 v[194:197], v[238:241], v[74:77], v[194:197]
	v_mfma_f32_16x16x32_bf16 v[198:201], v[238:241], v[78:81], v[198:201]
	ds_read_b128 v[238:241], v165 offset:63040
	s_waitcnt lgkmcnt(3)
	v_mfma_f32_16x16x32_bf16 v[202:205], v[226:229], v[74:77], v[202:205]
	v_mfma_f32_16x16x32_bf16 v[206:209], v[226:229], v[78:81], v[206:209]
	ds_read_b128 v[226:229], v165 offset:384
	s_waitcnt lgkmcnt(3)
	v_mfma_f32_16x16x32_bf16 v[210:213], v[230:233], v[74:77], v[210:213]
	v_mfma_f32_16x16x32_bf16 v[214:217], v[230:233], v[78:81], v[214:217]
	ds_read_b128 v[230:233], v165 offset:12928
	s_waitcnt lgkmcnt(3)
	v_mfma_f32_16x16x32_bf16 v[218:221], v[234:237], v[74:77], v[218:221]
	v_mfma_f32_16x16x32_bf16 v[222:225], v[234:237], v[78:81], v[222:225]
	ds_read_b128 v[234:237], v165 offset:25472
	s_waitcnt lgkmcnt(3)
	v_mfma_f32_16x16x32_bf16 v[178:181], v[238:241], v[74:77], v[178:181]
	v_mfma_f32_16x16x32_bf16 v[182:185], v[238:241], v[78:81], v[182:185]
	ds_read_b128 v[238:241], v165 offset:38016
	s_waitcnt lgkmcnt(3)
	s_waitcnt vmcnt(5)
	v_mfma_f32_16x16x32_bf16 v[186:189], v[226:229], v[66:69], v[186:189]
	v_mfma_f32_16x16x32_bf16 v[190:193], v[226:229], v[70:73], v[190:193]
	ds_read_b128 v[226:229], v165 offset:50560
	s_waitcnt lgkmcnt(3)
	v_mfma_f32_16x16x32_bf16 v[194:197], v[230:233], v[66:69], v[194:197]
	v_mfma_f32_16x16x32_bf16 v[198:201], v[230:233], v[70:73], v[198:201]
	ds_read_b128 v[230:233], v165 offset:63104
	s_waitcnt lgkmcnt(3)
	v_mfma_f32_16x16x32_bf16 v[202:205], v[234:237], v[66:69], v[202:205]
	v_mfma_f32_16x16x32_bf16 v[206:209], v[234:237], v[70:73], v[206:209]
	ds_read_b128 v[234:237], v165 offset:448
	s_waitcnt lgkmcnt(3)
	v_mfma_f32_16x16x32_bf16 v[210:213], v[238:241], v[66:69], v[210:213]
	v_mfma_f32_16x16x32_bf16 v[214:217], v[238:241], v[70:73], v[214:217]
	ds_read_b128 v[238:241], v165 offset:12992
	s_waitcnt lgkmcnt(3)
	v_mfma_f32_16x16x32_bf16 v[218:221], v[226:229], v[66:69], v[218:221]
	v_mfma_f32_16x16x32_bf16 v[222:225], v[226:229], v[70:73], v[222:225]
	ds_read_b128 v[226:229], v165 offset:25536
	s_waitcnt lgkmcnt(3)
	v_mfma_f32_16x16x32_bf16 v[178:181], v[230:233], v[66:69], v[178:181]
	v_mfma_f32_16x16x32_bf16 v[182:185], v[230:233], v[70:73], v[182:185]
	ds_read_b128 v[230:233], v165 offset:38080
	s_waitcnt lgkmcnt(3)
	s_waitcnt vmcnt(4)
	v_mfma_f32_16x16x32_bf16 v[186:189], v[234:237], v[58:61], v[186:189]
	v_mfma_f32_16x16x32_bf16 v[190:193], v[234:237], v[62:65], v[190:193]
	ds_read_b128 v[234:237], v165 offset:50624
	s_waitcnt lgkmcnt(3)
	v_mfma_f32_16x16x32_bf16 v[194:197], v[238:241], v[58:61], v[194:197]
	v_mfma_f32_16x16x32_bf16 v[198:201], v[238:241], v[62:65], v[198:201]
	ds_read_b128 v[238:241], v165 offset:63168
	s_waitcnt lgkmcnt(3)
; #define LAS __attribute__((address_space(3)))
; #define MFMA16(a, b, c) __builtin_amdgcn_mfma_f32_16x16x32_bf16((a), (b), (c), 0, 0, 0)
; __device__ __forceinline__ void qkv_head_unit(const Params& p, LAS unsigned char* lds, int h, int blk_begin, int blk_end) {
;     ...
;             for (int ks = 0; ks < 12; ++ks)
; #pragma unroll
;                 for (int n = 0; n < 6; ++n) { const bf16x8 bw = *(const LAS bf16x8*)(wl + (16 * n + fr) * WQS + 32 * ks + 8 * fq);
;                     acc[0][n] = MFMA16(bw, af[0][ks], acc[0][n]); acc[1][n] = MFMA16(bw, af[1][ks], acc[1][n]); }
	v_mfma_f32_16x16x32_bf16 v[202:205], v[226:229], v[58:61], v[202:205]
	v_mfma_f32_16x16x32_bf16 v[206:209], v[226:229], v[62:65], v[206:209]
	ds_read_b128 v[226:229], v165 offset:512
	s_waitcnt lgkmcnt(3)
	v_mfma_f32_16x16x32_bf16 v[210:213], v[230:233], v[58:61], v[210:213]
	v_mfma_f32_16x16x32_bf16 v[214:217], v[230:233], v[62:65], v[214:217]
	ds_read_b128 v[230:233], v165 offset:13056
	s_waitcnt lgkmcnt(3)
	v_mfma_f32_16x16x32_bf16 v[218:221], v[234:237], v[58:61], v[218:221]
	v_mfma_f32_16x16x32_bf16 v[222:225], v[234:237], v[62:65], v[222:225]
	ds_read_b128 v[234:237], v165 offset:25600
	s_waitcnt lgkmcnt(3)
	v_mfma_f32_16x16x32_bf16 v[178:181], v[238:241], v[58:61], v[178:181]
	v_mfma_f32_16x16x32_bf16 v[182:185], v[238:241], v[62:65], v[182:185]
	ds_read_b128 v[238:241], v165 offset:38144
	s_waitcnt lgkmcnt(3)
	s_waitcnt vmcnt(3)
	v_mfma_f32_16x16x32_bf16 v[186:189], v[226:229], v[50:53], v[186:189]
	v_mfma_f32_16x16x32_bf16 v[190:193], v[226:229], v[54:57], v[190:193]
	ds_read_b128 v[226:229], v165 offset:50688
	s_waitcnt lgkmcnt(3)
	v_mfma_f32_16x16x32_bf16 v[194:197], v[230:233], v[50:53], v[194:197]
	v_mfma_f32_16x16x32_bf16 v[198:201], v[230:233], v[54:57], v[198:201]
	ds_read_b128 v[230:233], v165 offset:63232
	s_waitcnt lgkmcnt(3)
	v_mfma_f32_16x16x32_bf16 v[202:205], v[234:237], v[50:53], v[202:205]
	v_mfma_f32_16x16x32_bf16 v[206:209], v[234:237], v[54:57], v[206:209]
	ds_read_b128 v[234:237], v165 offset:576
	s_waitcnt lgkmcnt(3)
	v_mfma_f32_16x16x32_bf16 v[210:213], v[238:241], v[50:53], v[210:213]
	v_mfma_f32_16x16x32_bf16 v[214:217], v[238:241], v[54:57], v[214:217]
	ds_read_b128 v[238:241], v165 offset:13120
	s_waitcnt lgkmcnt(3)
	v_mfma_f32_16x16x32_bf16 v[218:221], v[226:229], v[50:53], v[218:221]
	v_mfma_f32_16x16x32_bf16 v[222:225], v[226:229], v[54:57], v[222:225]
	ds_read_b128 v[226:229], v165 offset:25664
	s_waitcnt lgkmcnt(3)
	v_mfma_f32_16x16x32_bf16 v[178:181], v[230:233], v[50:53], v[178:181]
	v_mfma_f32_16x16x32_bf16 v[182:185], v[230:233], v[54:57], v[182:185]
	ds_read_b128 v[230:233], v165 offset:38208
	s_waitcnt lgkmcnt(3)
	s_waitcnt vmcnt(2)
	v_mfma_f32_16x16x32_bf16 v[186:189], v[234:237], v[42:45], v[186:189]
	v_mfma_f32_16x16x32_bf16 v[190:193], v[234:237], v[46:49], v[190:193]
	ds_read_b128 v[234:237], v165 offset:50752
	s_waitcnt lgkmcnt(3)
	v_mfma_f32_16x16x32_bf16 v[194:197], v[238:241], v[42:45], v[194:197]
	v_mfma_f32_16x16x32_bf16 v[198:201], v[238:241], v[46:49], v[198:201]
	ds_read_b128 v[238:241], v165 offset:63296
	s_waitcnt lgkmcnt(3)
	v_mfma_f32_16x16x32_bf16 v[202:205], v[226:229], v[42:45], v[202:205]
	v_mfma_f32_16x16x32_bf16 v[206:209], v[226:229], v[46:49], v[206:209]
	ds_read_b128 v[226:229], v165 offset:640
	s_waitcnt lgkmcnt(3)
	v_mfma_f32_16x16x32_bf16 v[210:213], v[230:233], v[42:45], v[210:213]
	v_mfma_f32_16x16x32_bf16 v[214:217], v[230:233], v[46:49], v[214:217]
	ds_read_b128 v[230:233], v165 offset:13184
	s_waitcnt lgkmcnt(3)
	v_mfma_f32_16x16x32_bf16 v[218:221], v[234:237], v[42:45], v[218:221]
	v_mfma_f32_16x16x32_bf16 v[222:225], v[234:237], v[46:49], v[222:225]
	ds_read_b128 v[234:237], v165 offset:25728
	s_waitcnt lgkmcnt(3)
	v_mfma_f32_16x16x32_bf16 v[178:181], v[238:241], v[42:45], v[178:181]
	v_mfma_f32_16x16x32_bf16 v[182:185], v[238:241], v[46:49], v[182:185]
	ds_read_b128 v[238:241], v165 offset:38272
	s_waitcnt lgkmcnt(3)
	s_waitcnt vmcnt(1)
	v_mfma_f32_16x16x32_bf16 v[186:189], v[226:229], v[34:37], v[186:189]
	v_mfma_f32_16x16x32_bf16 v[190:193], v[226:229], v[38:41], v[190:193]
	ds_read_b128 v[226:229], v165 offset:50816
	s_waitcnt lgkmcnt(3)
	v_mfma_f32_16x16x32_bf16 v[194:197], v[230:233], v[34:37], v[194:197]
	v_mfma_f32_16x16x32_bf16 v[198:201], v[230:233], v[38:41], v[198:201]
	ds_read_b128 v[230:233], v165 offset:63360
	s_waitcnt lgkmcnt(3)
	v_mfma_f32_16x16x32_bf16 v[202:205], v[234:237], v[34:37], v[202:205]
	v_mfma_f32_16x16x32_bf16 v[206:209], v[234:237], v[38:41], v[206:209]
	ds_read_b128 v[234:237], v165 offset:704
	s_waitcnt lgkmcnt(3)
	v_mfma_f32_16x16x32_bf16 v[210:213], v[238:241], v[34:37], v[210:213]
	v_mfma_f32_16x16x32_bf16 v[214:217], v[238:241], v[38:41], v[214:217]
	ds_read_b128 v[238:241], v165 offset:13248
	s_waitcnt lgkmcnt(3)
	v_mfma_f32_16x16x32_bf16 v[218:221], v[226:229], v[34:37], v[218:221]
	v_mfma_f32_16x16x32_bf16 v[222:225], v[226:229], v[38:41], v[222:225]
	ds_read_b128 v[226:229], v165 offset:25792
	s_waitcnt lgkmcnt(3)
	v_mfma_f32_16x16x32_bf16 v[178:181], v[230:233], v[34:37], v[178:181]
	v_mfma_f32_16x16x32_bf16 v[182:185], v[230:233], v[38:41], v[182:185]
	ds_read_b128 v[230:233], v165 offset:38336
	s_waitcnt lgkmcnt(3)
	s_waitcnt vmcnt(0)
	v_mfma_f32_16x16x32_bf16 v[54:57], v[234:237], v[26:29], v[186:189]
	v_mfma_f32_16x16x32_bf16 v[34:37], v[234:237], v[30:33], v[190:193]
	ds_read_b128 v[234:237], v165 offset:50880
	s_waitcnt lgkmcnt(3)
	v_mfma_f32_16x16x32_bf16 v[62:65], v[238:241], v[26:29], v[194:197]
	v_mfma_f32_16x16x32_bf16 v[46:49], v[238:241], v[30:33], v[198:201]
	ds_read_b128 v[238:241], v165 offset:63424
	s_waitcnt lgkmcnt(3)
	v_mfma_f32_16x16x32_bf16 v[58:61], v[226:229], v[26:29], v[202:205]
	v_mfma_f32_16x16x32_bf16 v[50:53], v[226:229], v[30:33], v[206:209]
	s_waitcnt lgkmcnt(2)
	v_mfma_f32_16x16x32_bf16 v[66:69], v[230:233], v[26:29], v[210:213]
	v_mfma_f32_16x16x32_bf16 v[42:45], v[230:233], v[30:33], v[214:217]
	s_waitcnt lgkmcnt(1)
	v_mfma_f32_16x16x32_bf16 v[70:73], v[234:237], v[26:29], v[218:221]
	v_mfma_f32_16x16x32_bf16 v[38:41], v[234:237], v[30:33], v[222:225]
	s_waitcnt lgkmcnt(0)
; #define LAS __attribute__((address_space(3)))
; __device__ __forceinline__ float frsq(float x) { return __builtin_amdgcn_rsqf(x); }
; #define MFMA16(a, b, c) __builtin_amdgcn_mfma_f32_16x16x32_bf16((a), (b), (c), 0, 0, 0)
; __device__ __forceinline__ void qkv_head_unit(const Params& p, LAS unsigned char* lds, int h, int blk_begin, int blk_end) {
;     ...
;             for (int ks = 0; ks < 12; ++ks)
; #pragma unroll
;                 for (int n = 0; n < 6; ++n) { const bf16x8 bw = *(const LAS bf16x8*)(wl + (16 * n + fr) * WQS + 32 * ks + 8 * fq);
;                     acc[0][n] = MFMA16(bw, af[0][ks], acc[0][n]); acc[1][n] = MFMA16(bw, af[1][ks], acc[1][n]); }
; #pragma unroll
;             for (int mi = 0; mi < 2; ++mi) {
;                 const bool valid = (mi == 0) || two;
;                 const int t = rowm[mi] % TT;
;                 const float sc = frsq(ssv[mi] * (1.0f / 384.0f) + EPS);
;                 float ssq = 0.f;
; #pragma unroll
;                 for (int n = 0; n < 6; ++n) { acc[mi][n] *= sc; ssq += (acc[mi][n][0] * acc[mi][n][0] + acc[mi][n][1] * acc[mi][n][1]) + (acc[mi][n][2] * acc[mi][n][2] + acc[mi][n][3] * acc[mi][n][3]); }
;                 ssq += __shfl_xor(ssq, 16); ssq += __shfl_xor(ssq, 32);
	v_mfma_f32_16x16x32_bf16 v[78:81], v[238:241], v[26:29], v[178:181]
	v_mfma_f32_16x16x32_bf16 v[26:29], v[238:241], v[30:33], v[182:185]
	s_nop 7
	v_pk_mul_f32 v[68:69], v[0:1], v[68:69] op_sel_hi:[0,1]
	v_pk_mul_f32 v[66:67], v[0:1], v[66:67] op_sel_hi:[0,1]
	v_mul_f32_e64 v72, v0, v72
	v_mul_f32_e64 v73, v0, v73
	v_pk_mul_f32 v[70:71], v[0:1], v[70:71] op_sel_hi:[0,1]
	v_mul_f32_e64 v32, v0, v54
	v_mul_f32_e64 v33, v0, v55
	v_pk_mul_f32 v[76:77], v[0:1], v[58:59] op_sel_hi:[0,1]
	v_mul_f32_e32 v58, v33, v33
	v_pk_mul_f32 v[30:31], v[0:1], v[56:57] op_sel_hi:[0,1]
	v_pk_mul_f32 v[74:75], v[0:1], v[60:61] op_sel_hi:[0,1]
	v_mul_f32_e32 v60, v76, v76
	v_pk_fma_f32 v[58:59], v[32:33], v[32:33], v[58:59] op_sel_hi:[1,1,0]
	v_pk_mul_f32 v[56:57], v[0:1], v[62:63] op_sel_hi:[0,1]
	v_mov_b32_e32 v59, v60
	v_mul_f32_e32 v60, v31, v31
	v_mul_f32_e32 v62, v77, v77
	v_pk_fma_f32 v[60:61], v[30:31], v[30:31], v[60:61] op_sel_hi:[1,1,0]
	v_pk_mul_f32 v[54:55], v[0:1], v[64:65] op_sel_hi:[0,1]
	v_mov_b32_e32 v61, v62
	v_pk_add_f32 v[58:59], v[58:59], v[60:61]
	v_mul_f32_e32 v60, v57, v57
	v_mul_f32_e32 v63, v74, v74
	v_pk_fma_f32 v[60:61], v[56:57], v[56:57], v[60:61] op_sel_hi:[1,1,0]
	v_mul_f32_e32 v62, v55, v55
	v_mul_f32_e32 v64, v75, v75
	v_mov_b32_e32 v61, v63
	v_pk_fma_f32 v[62:63], v[54:55], v[54:55], v[62:63] op_sel_hi:[1,1,0]
	v_pk_mul_f32 v[78:79], v[0:1], v[78:79] op_sel_hi:[0,1]
	v_mov_b32_e32 v63, v64
	v_pk_add_f32 v[60:61], v[60:61], v[62:63]
	v_pk_mul_f32 v[62:63], v[68:69], v[68:69]
	v_pk_add_f32 v[58:59], v[58:59], v[60:61]
	v_pk_mul_f32 v[60:61], v[66:67], v[66:67]
	v_pk_mul_f32 v[80:81], v[0:1], v[80:81] op_sel_hi:[0,1]
	v_pk_mov_b32 v[64:65], v[60:61], v[62:63] op_sel:[1,0]
	v_mov_b32_e32 v61, v63
	v_pk_add_f32 v[60:61], v[64:65], v[60:61]
	v_mul_f32_e32 v0, v78, v78
	v_mul_f32_e32 v62, v79, v79
	v_pk_add_f32 v[58:59], v[58:59], v[58:59] op_sel:[0,1] op_sel_hi:[1,0]
	v_pk_add_f32 v[60:61], v[60:61], v[60:61] op_sel:[0,1] op_sel_hi:[1,0]
	v_mov_b32_e32 v59, v0
	v_mov_b32_e32 v61, v62
	v_mul_f32_e32 v0, v71, v71
	v_mul_f32_e32 v63, v80, v80
	v_pk_add_f32 v[58:59], v[58:59], v[60:61]
	v_pk_fma_f32 v[60:61], v[70:71], v[70:71], v[0:1] op_sel_hi:[1,1,0]
	v_mul_f32_e32 v0, v73, v73
	v_mul_f32_e32 v64, v81, v81
	v_mov_b32_e32 v61, v63
	v_pk_fma_f32 v[62:63], v[72:73], v[72:73], v[0:1] op_sel_hi:[1,1,0]
	s_nop 0
	v_mov_b32_e32 v63, v64
	v_pk_add_f32 v[60:61], v[60:61], v[62:63]
	s_nop 0
	v_pk_add_f32 v[58:59], v[58:59], v[60:61]
	s_nop 0
	v_add_f32_e32 v0, v58, v59
	ds_bpermute_b32 v58, v161, v0
	s_waitcnt lgkmcnt(0)
	v_add_f32_e32 v0, v0, v58
	ds_bpermute_b32 v58, v164, v0
	s_waitcnt lgkmcnt(0)
; #define LAS __attribute__((address_space(3)))
; __device__ __forceinline__ unsigned cvt_pk(float lo, float hi) { unsigned r; asm("v_cvt_pk_bf16_f32 %0, %1, %2" : "=v"(r) : "v"(lo), "v"(hi)); return r; }
; __device__ __forceinline__ float frsq(float x) { return __builtin_amdgcn_rsqf(x); }
; __device__ __forceinline__ void qkv_head_unit(const Params& p, LAS unsigned char* lds, int h, int blk_begin, int blk_end) {
;     ...
;                 const float rq = frsq(ssq * (1.0f / 96.0f) + EPS);
; #pragma unroll
;                 for (int n = 0; n < 6; ++n) acc[mi][n] = acc[mi][n] * rq * gvv[n];
; #pragma unroll
;                 for (int i = 0; i < 4; ++i) { float sn, cs; sincos_rr((float)t * frq[i], sn, cs);
;                     const float x1 = acc[mi][4][i], x2 = acc[mi][5][i]; acc[mi][4][i] = x1 * cs - x2 * sn; acc[mi][5][i] = x1 * sn + x2 * cs; }
; #pragma unroll
;                 for (int n = 0; n < 6; ++n) { u32x2 wv; wv.x = cvt_pk(acc[mi][n][0] * QSCALE, acc[mi][n][1] * QSCALE); wv.y = cvt_pk(acc[mi][n][2] * QSCALE, acc[mi][n][3] * QSCALE); *(LAS u32x2*)(stg + fr * 104 + 16 * n + 4 * fq) = wv; }
;                 asm volatile("s_waitcnt lgkmcnt(0)" ::: "memory");
; #pragma unroll
;                 for (int j = 0; j < 3; ++j) { const int c = lane + 64 * j, rw = c / 12, cc = c % 12; const int row2 = 16 * (mi ? blk1 : pb) + rw, b2 = row2 / TT, t2 = row2 % TT;
;                     const u32x4 v = *(const LAS u32x4*)(stg + rw * 104 + 8 * cc);
;                     if (valid && t2 >= NMETA) *(u32x4*)(Q + (((size_t)(b2 * NH + h)) * SEQ + (t2 - NMETA)) * QKH + 8 * cc) = v; }
	v_add_f32_e32 v0, v0, v58
	v_fmamk_f32 v0, v0, 0x3c2aaaab, v140
	v_rsq_f32_e32 v0, v0
	s_nop 0
	v_pk_mul_f32 v[32:33], v[32:33], v[0:1] op_sel_hi:[1,0]
	v_pk_mul_f32 v[30:31], v[30:31], v[0:1] op_sel_hi:[1,0]
	v_pk_mul_f32 v[64:65], v[2:3], v[32:33]
	v_pk_mul_f32 v[32:33], v[54:55], v[0:1] op_sel_hi:[1,0]
	v_pk_mul_f32 v[62:63], v[4:5], v[30:31]
	v_pk_mul_f32 v[30:31], v[56:57], v[0:1] op_sel_hi:[1,0]
	v_pk_mul_f32 v[58:59], v[8:9], v[32:33]
	v_pk_mul_f32 v[32:33], v[74:75], v[0:1] op_sel_hi:[1,0]
	v_pk_mul_f32 v[60:61], v[6:7], v[30:31]
	v_pk_mul_f32 v[30:31], v[76:77], v[0:1] op_sel_hi:[1,0]
	v_pk_mul_f32 v[54:55], v[12:13], v[32:33]
	v_pk_mul_f32 v[32:33], v[66:67], v[0:1] op_sel_hi:[1,0]
	v_pk_mul_f32 v[66:67], v[70:71], v[0:1] op_sel_hi:[1,0]
	v_pk_mul_f32 v[56:57], v[10:11], v[30:31]
	v_pk_mul_f32 v[30:31], v[68:69], v[0:1] op_sel_hi:[1,0]
	v_pk_mul_f32 v[68:69], v[72:73], v[0:1] op_sel_hi:[1,0]
	v_pk_mul_f32 v[72:73], v[18:19], v[66:67]
	v_pk_mul_f32 v[70:71], v[78:79], v[0:1] op_sel_hi:[1,0]
	v_pk_mul_f32 v[66:67], v[80:81], v[0:1] op_sel_hi:[1,0]
	v_mul_hi_i32 v0, v126, s90
	v_lshrrev_b32_e32 v74, 31, v0
	v_ashrrev_i32_e32 v0, 7, v0
	v_add_u32_e32 v0, v0, v74
	v_mul_lo_u32 v0, v0, s86
	v_sub_u32_e32 v0, v126, v0
	v_cvt_f32_i32_e32 v0, v0
	v_pk_mul_f32 v[70:71], v[22:23], v[70:71]
	v_mov_b32_e32 v76, v72
	v_mov_b32_e32 v77, v70
	v_mul_f32_e32 v74, v154, v0
	v_mul_f32_e32 v75, 0.15915494, v74
	v_rndne_f32_e32 v75, v75
	v_fmac_f32_e32 v74, 0xc0c90fdb, v75
	v_fmac_f32_e32 v74, 0x343bbd2e, v75
	v_mul_f32_e32 v74, 0.15915494, v74
	v_sin_f32_e32 v75, v74
	v_cos_f32_e32 v74, v74
	v_mul_f32_e32 v70, v155, v0
	v_mul_f32_e32 v72, 0.15915494, v70
	v_rndne_f32_e32 v72, v72
	v_pk_mul_f32 v[78:79], v[74:75], v[76:77]
	v_fmac_f32_e32 v70, 0xc0c90fdb, v72
	v_sub_f32_e32 v80, v78, v79
	v_mov_b32_e32 v78, v75
	v_mov_b32_e32 v79, v74
	v_fmac_f32_e32 v70, 0x343bbd2e, v72
	v_pk_mul_f32 v[74:75], v[78:79], v[76:77]
	v_mul_f32_e32 v70, 0.15915494, v70
	v_add_f32_e32 v76, v74, v75
	v_sin_f32_e32 v75, v70
	v_cos_f32_e32 v74, v70
	v_mov_b32_e32 v70, v73
	v_pk_mul_f32 v[66:67], v[24:25], v[66:67]
	v_pk_mul_f32 v[68:69], v[20:21], v[68:69]
	v_pk_mul_f32 v[72:73], v[74:75], v[70:71]
	v_pk_mul_f32 v[30:31], v[16:17], v[30:31]
	v_sub_f32_e32 v77, v72, v73
	v_mov_b32_e32 v72, v75
	v_mov_b32_e32 v73, v74
	v_pk_mul_f32 v[70:71], v[72:73], v[70:71]
	v_mov_b32_e32 v73, v66
	v_add_f32_e32 v78, v70, v71
	v_mul_f32_e32 v70, v156, v0
	v_mul_f32_e32 v71, 0.15915494, v70
	v_rndne_f32_e32 v71, v71
	v_fmac_f32_e32 v70, 0xc0c90fdb, v71
	v_fmac_f32_e32 v70, 0x343bbd2e, v71
	v_mul_f32_e32 v70, 0.15915494, v70
	v_sin_f32_e32 v71, v70
	v_cos_f32_e32 v70, v70
	v_mul_f32_e32 v0, v157, v0
	v_mul_f32_e32 v66, 0.15915494, v0
	v_mov_b32_e32 v72, v68
	v_rndne_f32_e32 v66, v66
	v_pk_mul_f32 v[74:75], v[70:71], v[72:73]
	v_fmac_f32_e32 v0, 0xc0c90fdb, v66
	v_sub_f32_e32 v79, v74, v75
	v_mov_b32_e32 v74, v71
	v_mov_b32_e32 v75, v70
	v_fmac_f32_e32 v0, 0x343bbd2e, v66
	v_pk_mul_f32 v[70:71], v[74:75], v[72:73]
	v_mul_f32_e32 v0, 0.15915494, v0
	v_add_f32_e32 v72, v70, v71
	v_sin_f32_e32 v71, v0
	v_cos_f32_e32 v70, v0
	v_pk_mul_f32 v[32:33], v[14:15], v[32:33]
	v_mov_b32_e32 v66, v69
	v_mul_f32_e32 v32, 0x3e16c740, v32
	v_pk_mul_f32 v[68:69], v[70:71], v[66:67]
	v_mul_f32_e32 v33, 0x3e16c740, v33
	v_mul_f32_e32 v30, 0x3e16c740, v30
	v_mul_f32_e32 v31, 0x3e16c740, v31
	v_sub_f32_e32 v0, v68, v69
	v_mov_b32_e32 v68, v71
	v_mov_b32_e32 v69, v70
	v_mul_f32_e32 v64, 0x3e16c740, v64
	v_mul_f32_e32 v65, 0x3e16c740, v65
	v_mul_f32_e32 v62, 0x3e16c740, v62
	v_cvt_pk_bf16_f32 v32, v32, v33
	v_cvt_pk_bf16_f32 v33, v30, v31
	v_mul_f32_e32 v30, 0x3e16c740, v80
	v_mul_f32_e32 v31, 0x3e16c740, v77
	v_pk_mul_f32 v[66:67], v[68:69], v[66:67]
	v_cvt_pk_bf16_f32 v64, v64, v65
	v_mul_f32_e32 v63, 0x3e16c740, v63
	v_cvt_pk_bf16_f32 v65, v62, v63
	v_add_u32_e32 v62, v160, v114
	v_mul_f32_e32 v56, 0x3e16c740, v56
	v_mul_f32_e32 v57, 0x3e16c740, v57
	v_cvt_pk_bf16_f32 v30, v30, v31
	v_mul_f32_e32 v31, 0x3e16c740, v79
	v_mul_f32_e32 v0, 0x3e16c740, v0
	v_add_f32_e32 v66, v66, v67
	v_cvt_pk_bf16_f32 v56, v56, v57
	v_mul_f32_e32 v54, 0x3e16c740, v54
	v_mul_f32_e32 v55, 0x3e16c740, v55
	v_cvt_pk_bf16_f32 v57, v54, v55
	ds_write2_b64 v62, v[56:57], v[32:33] offset0:8 offset1:12
	v_cvt_pk_bf16_f32 v31, v31, v0
	v_mul_f32_e32 v0, 0x3e16c740, v76
	v_mul_f32_e32 v32, 0x3e16c740, v78
	v_cvt_pk_bf16_f32 v32, v0, v32
	v_mul_f32_e32 v0, 0x3e16c740, v72
	v_mul_f32_e32 v33, 0x3e16c740, v66
	v_cvt_pk_bf16_f32 v33, v0, v33
	v_add_u32_e32 v0, s14, v174
	ds_write2_b64 v62, v[30:31], v[32:33] offset0:16 offset1:20
	v_mul_hi_i32 v30, v0, s90
	v_mul_f32_e32 v60, 0x3e16c740, v60
	v_mul_f32_e32 v61, 0x3e16c740, v61
	v_lshrrev_b32_e32 v31, 31, v30
	v_ashrrev_i32_e32 v30, 7, v30
	v_cvt_pk_bf16_f32 v60, v60, v61
	v_mul_f32_e32 v58, 0x3e16c740, v58
	v_mul_f32_e32 v59, 0x3e16c740, v59
	v_cvt_pk_bf16_f32 v61, v58, v59
	ds_write2_b64 v62, v[64:65], v[60:61] offset1:4
	v_add_u32_e32 v30, v30, v31
	s_waitcnt lgkmcnt(0)
	v_mul_i32_i24_e32 v31, 0x810, v30
	v_sub_u32_e32 v0, v0, v31
	v_cmp_lt_i32_e64 s[0:1], 15, v0
	s_and_saveexec_b64 s[10:11], s[0:1]
	s_cbranch_execz .LBB0_508
	v_lshl_or_b32 v30, v30, 3, s16
	ds_read_b128 v[54:57], v167
	v_ashrrev_i32_e32 v31, 31, v30
	v_lshlrev_b64 v[30:31], 11, v[30:31]
	v_add_u32_e32 v0, -16, v0
	v_lshl_add_u64 v[30:31], v[30:31], 0, v[0:1]
	v_mad_u64_u32 v[32:33], s[0:1], v30, s91, v[118:119]
	v_mad_i32_i24 v33, v31, s91, v33
	s_waitcnt lgkmcnt(0)
	global_store_dwordx4 v[32:33], v[54:57], off

; #define LAS __attribute__((address_space(3)))
; #define MFMA16(a, b, c) __builtin_amdgcn_mfma_f32_16x16x32_bf16((a), (b), (c), 0, 0, 0)
; __device__ __forceinline__ void qkv_head_unit(const Params& p, LAS unsigned char* lds, int h, int blk_begin, int blk_end) {
;     ...
;         for (int pb = blk_begin + 2 * w; pb < blk_end; pb += 16) {
;             const bool two = (pb + 1) < blk_end;
;             const int blk1 = two ? pb + 1 : pb;
;             const int rowm[2] = {16 * pb + fr, 16 * blk1 + fr};
;             bf16x8 af[2][8]; float ssv[2]; u32x2 k1v[2], k2v[2];
; #pragma unroll
;             for (int m = 0; m < 2; ++m) { ssv[m] = ss_ckv[rowm[m]]; k1v[m] = *(const u32x2*)(P + (size_t)rowm[m] * INP + C_KR + 4 * fq); k2v[m] = *(const u32x2*)(P + (size_t)rowm[m] * INP + C_KR + 16 + 4 * fq);
; #pragma unroll
;                 for (int ks = 0; ks < 8; ++ks) af[m][ks] = *(const bf16x8*)(P + (size_t)rowm[m] * INP + C_CKV + 32 * ks + 8 * fq); }
;             {
;                 f32x4 acc[2][4];
; #pragma unroll
;                 for (int m = 0; m < 2; ++m)
; #pragma unroll
;                     for (int n = 0; n < 4; ++n) acc[m][n] = (f32x4){0.f, 0.f, 0.f, 0.f};
; #pragma unroll
;                 for (int ks = 0; ks < 8; ++ks)
; #pragma unroll
;                     for (int n = 0; n < 4; ++n) { const bf16x8 bw = *(const LAS bf16x8*)(wl + (16 * n + fr) * WKS + 32 * ks + 8 * fq);
;                         acc[0][n] = MFMA16(bw, af[0][ks], acc[0][n]); acc[1][n] = MFMA16(bw, af[1][ks], acc[1][n]); }
.LBB0_524:
	v_add_u32_e32 v177, 1, v159
	v_cmp_gt_i32_e32 vcc, s12, v177
	v_add_u32_e32 v126, v158, v161
	v_ashrrev_i32_e32 v127, 31, v126
	v_cndmask_b32_e32 v0, v159, v177, vcc
	v_lshlrev_b32_e32 v178, 4, v0
	v_or_b32_e32 v120, v178, v158
	v_lshl_add_u64 v[22:23], v[126:127], 2, s[42:43]
	v_mov_b64_e32 v[26:27], s[40:41]
	global_load_dword v127, v[22:23], off
	v_mad_i64_i32 v[22:23], s[4:5], v126, s89, v[26:27]
	v_lshlrev_b32_e32 v0, 1, v115
	v_lshlrev_b32_e32 v28, 1, v114
	v_mov_b32_e32 v29, v1
	v_ashrrev_i32_e32 v121, 31, v120
	v_lshl_add_u64 v[24:25], v[22:23], 0, v[0:1]
	v_lshl_add_u64 v[22:23], v[22:23], 0, v[28:29]
	v_lshl_add_u64 v[34:35], v[120:121], 2, s[42:43]
	v_mad_i64_i32 v[26:27], s[4:5], v120, s89, v[26:27]
	global_load_dwordx2 v[130:131], v[24:25], off offset:1280
	global_load_dwordx2 v[128:129], v[24:25], off offset:1312
	global_load_dwordx4 v[78:81], v[22:23], off offset:768
	global_load_dwordx4 v[66:69], v[22:23], off offset:832
	global_load_dwordx4 v[62:65], v[22:23], off offset:896
	global_load_dwordx4 v[50:53], v[22:23], off offset:960
	global_load_dwordx4 v[46:49], v[22:23], off offset:1024
	global_load_dwordx4 v[38:41], v[22:23], off offset:1088
	global_load_dwordx4 v[30:33], v[22:23], off offset:1152
	s_nop 0
	global_load_dwordx4 v[22:25], v[22:23], off offset:1216
	s_nop 0
	global_load_dword v121, v[34:35], off
	v_lshl_add_u64 v[34:35], v[26:27], 0, v[0:1]
	v_lshl_add_u64 v[26:27], v[26:27], 0, v[28:29]
	global_load_dwordx2 v[124:125], v[34:35], off offset:1280
	global_load_dwordx2 v[122:123], v[34:35], off offset:1312
	global_load_dwordx4 v[82:85], v[26:27], off offset:768
	global_load_dwordx4 v[74:77], v[26:27], off offset:832
	global_load_dwordx4 v[70:73], v[26:27], off offset:896
	global_load_dwordx4 v[58:61], v[26:27], off offset:960
	global_load_dwordx4 v[54:57], v[26:27], off offset:1024
	global_load_dwordx4 v[42:45], v[26:27], off offset:1088
	global_load_dwordx4 v[34:37], v[26:27], off offset:1152
	s_nop 0
	global_load_dwordx4 v[26:29], v[26:27], off offset:1216
	ds_read_b128 v[230:233], v164 offset:0
	ds_read_b128 v[234:237], v164 offset:8448
	ds_read_b128 v[238:241], v164 offset:16896
	ds_read_b128 v[180:183], v164 offset:25344
	s_waitcnt lgkmcnt(3)
	s_waitcnt vmcnt(18)
	v_mfma_f32_16x16x32_bf16 v[188:191], v[230:233], v[78:81], 0
	v_fmamk_f32 v0, v127, 0x3b800000, v140
	v_rsq_f32_e32 v0, v0
	s_waitcnt vmcnt(7)
	v_mfma_f32_16x16x32_bf16 v[98:101], v[230:233], v[82:85], 0
	ds_read_b128 v[230:233], v164 offset:64
	s_waitcnt lgkmcnt(3)
	v_mfma_f32_16x16x32_bf16 v[192:195], v[234:237], v[78:81], 0
	v_mfma_f32_16x16x32_bf16 v[86:89], v[234:237], v[82:85], 0
	ds_read_b128 v[234:237], v164 offset:8512
	s_waitcnt lgkmcnt(3)
	v_mfma_f32_16x16x32_bf16 v[196:199], v[238:241], v[78:81], 0
	v_mfma_f32_16x16x32_bf16 v[94:97], v[238:241], v[82:85], 0
	ds_read_b128 v[238:241], v164 offset:16960
	s_waitcnt lgkmcnt(3)
	v_mfma_f32_16x16x32_bf16 v[184:187], v[180:183], v[78:81], 0
	v_mfma_f32_16x16x32_bf16 v[90:93], v[180:183], v[82:85], 0
	ds_read_b128 v[180:183], v164 offset:25408
	s_waitcnt lgkmcnt(3)
	s_waitcnt vmcnt(6)
	v_mfma_f32_16x16x32_bf16 v[188:191], v[230:233], v[66:69], v[188:191]
	v_mfma_f32_16x16x32_bf16 v[98:101], v[230:233], v[74:77], v[98:101]
	ds_read_b128 v[230:233], v164 offset:128
	s_waitcnt lgkmcnt(3)
	v_mfma_f32_16x16x32_bf16 v[192:195], v[234:237], v[66:69], v[192:195]
	v_mfma_f32_16x16x32_bf16 v[86:89], v[234:237], v[74:77], v[86:89]
	ds_read_b128 v[234:237], v164 offset:8576
	s_waitcnt lgkmcnt(3)
	v_mfma_f32_16x16x32_bf16 v[196:199], v[238:241], v[66:69], v[196:199]
	v_mfma_f32_16x16x32_bf16 v[94:97], v[238:241], v[74:77], v[94:97]
	ds_read_b128 v[238:241], v164 offset:17024
	s_waitcnt lgkmcnt(3)
	v_mfma_f32_16x16x32_bf16 v[184:187], v[180:183], v[66:69], v[184:187]
	v_mfma_f32_16x16x32_bf16 v[90:93], v[180:183], v[74:77], v[90:93]
	ds_read_b128 v[180:183], v164 offset:25472
	s_waitcnt lgkmcnt(3)
	s_waitcnt vmcnt(5)
	v_mfma_f32_16x16x32_bf16 v[188:191], v[230:233], v[62:65], v[188:191]
	v_mfma_f32_16x16x32_bf16 v[98:101], v[230:233], v[70:73], v[98:101]
	ds_read_b128 v[230:233], v164 offset:192
	s_waitcnt lgkmcnt(3)
	v_mfma_f32_16x16x32_bf16 v[192:195], v[234:237], v[62:65], v[192:195]
	v_mfma_f32_16x16x32_bf16 v[86:89], v[234:237], v[70:73], v[86:89]
	ds_read_b128 v[234:237], v164 offset:8640
	s_waitcnt lgkmcnt(3)
	v_mfma_f32_16x16x32_bf16 v[196:199], v[238:241], v[62:65], v[196:199]
	v_mfma_f32_16x16x32_bf16 v[94:97], v[238:241], v[70:73], v[94:97]
	ds_read_b128 v[238:241], v164 offset:17088
	s_waitcnt lgkmcnt(3)
	v_mfma_f32_16x16x32_bf16 v[184:187], v[180:183], v[62:65], v[184:187]
	v_mfma_f32_16x16x32_bf16 v[90:93], v[180:183], v[70:73], v[90:93]
	ds_read_b128 v[180:183], v164 offset:25536
	s_waitcnt lgkmcnt(3)
	s_waitcnt vmcnt(4)
	v_mfma_f32_16x16x32_bf16 v[188:191], v[230:233], v[50:53], v[188:191]
	v_mfma_f32_16x16x32_bf16 v[98:101], v[230:233], v[58:61], v[98:101]
	ds_read_b128 v[230:233], v164 offset:256
	s_waitcnt lgkmcnt(3)
	v_mfma_f32_16x16x32_bf16 v[192:195], v[234:237], v[50:53], v[192:195]
	v_mfma_f32_16x16x32_bf16 v[86:89], v[234:237], v[58:61], v[86:89]
	ds_read_b128 v[234:237], v164 offset:8704
	s_waitcnt lgkmcnt(3)
	v_mfma_f32_16x16x32_bf16 v[196:199], v[238:241], v[50:53], v[196:199]
	v_mfma_f32_16x16x32_bf16 v[94:97], v[238:241], v[58:61], v[94:97]
	ds_read_b128 v[238:241], v164 offset:17152
	s_waitcnt lgkmcnt(3)
	v_mfma_f32_16x16x32_bf16 v[184:187], v[180:183], v[50:53], v[184:187]
	v_mfma_f32_16x16x32_bf16 v[90:93], v[180:183], v[58:61], v[90:93]
	ds_read_b128 v[180:183], v164 offset:25600
	s_waitcnt lgkmcnt(3)
	s_waitcnt vmcnt(3)
; #define LAS __attribute__((address_space(3)))
; __device__ __forceinline__ float bflo(unsigned w) { return __uint_as_float(w << 16); }
; __device__ __forceinline__ float bfhi(unsigned w) { return __uint_as_float(w & 0xffff0000u); }
; __device__ __forceinline__ float frsq(float x) { return __builtin_amdgcn_rsqf(x); }
; #define MFMA16(a, b, c) __builtin_amdgcn_mfma_f32_16x16x32_bf16((a), (b), (c), 0, 0, 0)
; __device__ __forceinline__ void qkv_head_unit(const Params& p, LAS unsigned char* lds, int h, int blk_begin, int blk_end) {
;     ...
;                 for (int ks = 0; ks < 8; ++ks)
; #pragma unroll
;                     for (int n = 0; n < 4; ++n) { const bf16x8 bw = *(const LAS bf16x8*)(wl + (16 * n + fr) * WKS + 32 * ks + 8 * fq);
;                         acc[0][n] = MFMA16(bw, af[0][ks], acc[0][n]); acc[1][n] = MFMA16(bw, af[1][ks], acc[1][n]); }
; #pragma unroll
;                 for (int mi = 0; mi < 2; ++mi) {
;                     const bool valid = (mi == 0) || two;
;                     const int t = rowm[mi] % TT;
;                     const float sc = frsq(ssv[mi] * (1.0f / 256.0f) + EPS);
;                     const u32x2 k1 = k1v[mi], k2 = k2v[mi];
;                     f32x4 kr1 = (f32x4){bflo(k1.x), bfhi(k1.x), bflo(k1.y), bfhi(k1.y)}, kr2 = (f32x4){bflo(k2.x), bfhi(k2.x), bflo(k2.y), bfhi(k2.y)};
;                     float ssq = (kr1[0] * kr1[0] + kr1[1] * kr1[1]) + (kr1[2] * kr1[2] + kr1[3] * kr1[3]) + (kr2[0] * kr2[0] + kr2[1] * kr2[1]) + (kr2[2] * kr2[2] + kr2[3] * kr2[3]);
; #pragma unroll
;                     for (int n = 0; n < 4; ++n) { acc[mi][n] *= sc; ssq += (acc[mi][n][0] * acc[mi][n][0] + acc[mi][n][1] * acc[mi][n][1]) + (acc[mi][n][2] * acc[mi][n][2] + acc[mi][n][3] * acc[mi][n][3]); }
;                     ssq += __shfl_xor(ssq, 16); ssq += __shfl_xor(ssq, 32);
	v_mfma_f32_16x16x32_bf16 v[188:191], v[230:233], v[46:49], v[188:191]
	v_mfma_f32_16x16x32_bf16 v[98:101], v[230:233], v[54:57], v[98:101]
	ds_read_b128 v[230:233], v164 offset:320
	s_waitcnt lgkmcnt(3)
	v_mfma_f32_16x16x32_bf16 v[192:195], v[234:237], v[46:49], v[192:195]
	v_mfma_f32_16x16x32_bf16 v[86:89], v[234:237], v[54:57], v[86:89]
	ds_read_b128 v[234:237], v164 offset:8768
	s_waitcnt lgkmcnt(3)
	v_mfma_f32_16x16x32_bf16 v[196:199], v[238:241], v[46:49], v[196:199]
	v_mfma_f32_16x16x32_bf16 v[94:97], v[238:241], v[54:57], v[94:97]
	ds_read_b128 v[238:241], v164 offset:17216
	s_waitcnt lgkmcnt(3)
	v_mfma_f32_16x16x32_bf16 v[184:187], v[180:183], v[46:49], v[184:187]
	v_mfma_f32_16x16x32_bf16 v[90:93], v[180:183], v[54:57], v[90:93]
	ds_read_b128 v[180:183], v164 offset:25664
	s_waitcnt lgkmcnt(3)
	s_waitcnt vmcnt(2)
	v_mfma_f32_16x16x32_bf16 v[188:191], v[230:233], v[38:41], v[188:191]
	v_mfma_f32_16x16x32_bf16 v[98:101], v[230:233], v[42:45], v[98:101]
	ds_read_b128 v[230:233], v164 offset:384
	s_waitcnt lgkmcnt(3)
	v_mfma_f32_16x16x32_bf16 v[192:195], v[234:237], v[38:41], v[192:195]
	v_mfma_f32_16x16x32_bf16 v[86:89], v[234:237], v[42:45], v[86:89]
	ds_read_b128 v[234:237], v164 offset:8832
	s_waitcnt lgkmcnt(3)
	v_mfma_f32_16x16x32_bf16 v[196:199], v[238:241], v[38:41], v[196:199]
	v_mfma_f32_16x16x32_bf16 v[94:97], v[238:241], v[42:45], v[94:97]
	ds_read_b128 v[238:241], v164 offset:17280
	s_waitcnt lgkmcnt(3)
	v_mfma_f32_16x16x32_bf16 v[184:187], v[180:183], v[38:41], v[184:187]
	v_mfma_f32_16x16x32_bf16 v[90:93], v[180:183], v[42:45], v[90:93]
	ds_read_b128 v[180:183], v164 offset:25728
	s_waitcnt lgkmcnt(3)
	s_waitcnt vmcnt(1)
	v_mfma_f32_16x16x32_bf16 v[188:191], v[230:233], v[30:33], v[188:191]
	v_mfma_f32_16x16x32_bf16 v[98:101], v[230:233], v[34:37], v[98:101]
	ds_read_b128 v[230:233], v164 offset:448
	s_waitcnt lgkmcnt(3)
	v_mfma_f32_16x16x32_bf16 v[192:195], v[234:237], v[30:33], v[192:195]
	v_mfma_f32_16x16x32_bf16 v[86:89], v[234:237], v[34:37], v[86:89]
	ds_read_b128 v[234:237], v164 offset:8896
	s_waitcnt lgkmcnt(3)
	v_mfma_f32_16x16x32_bf16 v[196:199], v[238:241], v[30:33], v[196:199]
	v_mfma_f32_16x16x32_bf16 v[94:97], v[238:241], v[34:37], v[94:97]
	ds_read_b128 v[238:241], v164 offset:17344
	s_waitcnt lgkmcnt(3)
	v_mfma_f32_16x16x32_bf16 v[184:187], v[180:183], v[30:33], v[184:187]
	v_mfma_f32_16x16x32_bf16 v[90:93], v[180:183], v[34:37], v[90:93]
	ds_read_b128 v[180:183], v164 offset:25792
	s_waitcnt lgkmcnt(3)
	s_waitcnt vmcnt(0)
	v_mfma_f32_16x16x32_bf16 v[188:191], v[230:233], v[22:25], v[188:191]
	v_mfma_f32_16x16x32_bf16 v[98:101], v[230:233], v[26:29], v[98:101]
	s_waitcnt lgkmcnt(2)
	v_mfma_f32_16x16x32_bf16 v[192:195], v[234:237], v[22:25], v[192:195]
	v_mfma_f32_16x16x32_bf16 v[86:89], v[234:237], v[26:29], v[86:89]
	s_waitcnt lgkmcnt(1)
	v_mfma_f32_16x16x32_bf16 v[196:199], v[238:241], v[22:25], v[196:199]
	v_mfma_f32_16x16x32_bf16 v[94:97], v[238:241], v[26:29], v[94:97]
	s_waitcnt lgkmcnt(0)
	v_mfma_f32_16x16x32_bf16 v[184:187], v[180:183], v[22:25], v[184:187]
	v_mfma_f32_16x16x32_bf16 v[90:93], v[180:183], v[26:29], v[90:93]
	v_lshlrev_b32_e32 v137, 16, v131
	v_lshlrev_b32_e32 v136, 16, v130
	v_and_b32_e32 v131, 0xffff0000, v131
	v_and_b32_e32 v130, 0xffff0000, v130
	v_pk_mul_f32 v[138:139], v[130:131], v[130:131]
	v_lshlrev_b32_e32 v132, 16, v129
	v_and_b32_e32 v134, 0xffff0000, v129
	s_nop 7
	v_pk_mul_f32 v[196:197], v[0:1], v[196:197] op_sel_hi:[0,1]
	v_mul_f32_e64 v184, v0, v184
	v_mul_f32_e64 v185, v0, v185
	v_pk_mul_f32 v[186:187], v[0:1], v[186:187] op_sel_hi:[0,1]
	v_pk_fma_f32 v[180:181], v[136:137], v[136:137], v[138:139]
	v_and_b32_e32 v139, 0xffff0000, v128
	v_lshlrev_b32_e32 v138, 16, v128
	v_pk_mul_f32 v[128:129], v[0:1], v[190:191] op_sel_hi:[0,1]
	v_pk_mul_f32 v[182:183], v[0:1], v[188:189] op_sel_hi:[0,1]
	v_mul_f32_e32 v190, v139, v139
	v_mul_f32_e32 v127, v128, v128
	v_mul_f32_e32 v179, v129, v129
	v_mov_b32_e32 v135, v183
	v_pk_add_f32 v[180:181], v[180:181], v[180:181] op_sel:[0,1] op_sel_hi:[1,0]
	v_pk_fma_f32 v[190:191], v[138:139], v[138:139], v[190:191] op_sel_hi:[1,1,0]
	v_mov_b32_e32 v133, v182
	v_pk_mul_f32 v[188:189], v[134:135], v[134:135]
	v_mov_b32_e32 v181, v127
	v_mov_b32_e32 v191, v179
	v_pk_fma_f32 v[188:189], v[132:133], v[132:133], v[188:189]
	v_pk_add_f32 v[180:181], v[180:181], v[190:191]
	v_pk_mul_f32 v[190:191], v[0:1], v[192:193] op_sel_hi:[0,1]
	v_pk_add_f32 v[180:181], v[188:189], v[180:181]
	v_pk_mul_f32 v[188:189], v[0:1], v[194:195] op_sel_hi:[0,1]
	v_pk_mul_f32 v[192:193], v[188:189], v[188:189]
	v_pk_mul_f32 v[194:195], v[190:191], v[190:191]
	v_mul_f32_e32 v127, v184, v184
	v_pk_mov_b32 v[200:201], v[194:195], v[192:193] op_sel:[1,0]
	v_mov_b32_e32 v195, v193
	v_pk_add_f32 v[192:193], v[200:201], v[194:195]
	v_mul_f32_e32 v133, v185, v185
	v_pk_add_f32 v[180:181], v[180:181], v[180:181] op_sel:[0,1] op_sel_hi:[1,0]
	v_pk_add_f32 v[192:193], v[192:193], v[192:193] op_sel:[0,1] op_sel_hi:[1,0]
	v_pk_mul_f32 v[194:195], v[0:1], v[198:199] op_sel_hi:[0,1]
	v_mov_b32_e32 v181, v127
	v_mov_b32_e32 v193, v133
	v_pk_add_f32 v[180:181], v[180:181], v[192:193]
	v_mul_f32_e32 v192, v197, v197
	v_mul_f32_e32 v198, v195, v195
	v_mul_f32_e32 v135, v186, v186
	v_mul_f32_e32 v179, v187, v187
	v_pk_fma_f32 v[192:193], v[196:197], v[196:197], v[192:193] op_sel_hi:[1,1,0]
	v_pk_fma_f32 v[198:199], v[194:195], v[194:195], v[198:199] op_sel_hi:[1,1,0]
	v_mov_b32_e32 v193, v135
	v_mov_b32_e32 v199, v179
	v_pk_add_f32 v[192:193], v[192:193], v[198:199]
	s_nop 0
	v_pk_add_f32 v[180:181], v[180:181], v[192:193]
	s_nop 0
	v_add_f32_e32 v127, v180, v181
	ds_bpermute_b32 v133, v103, v127
	s_waitcnt lgkmcnt(0)
; #define LAS __attribute__((address_space(3)))
; __device__ __forceinline__ unsigned cvt_pk(float lo, float hi) { unsigned r; asm("v_cvt_pk_bf16_f32 %0, %1, %2" : "=v"(r) : "v"(lo), "v"(hi)); return r; }
; __device__ __forceinline__ float frsq(float x) { return __builtin_amdgcn_rsqf(x); }
; __device__ __forceinline__ void qkv_head_unit(const Params& p, LAS unsigned char* lds, int h, int blk_begin, int blk_end) {
;     ...
;                     const float rk = frsq(ssq * (1.0f / 96.0f) + EPS);
;                     LAS bf16_t* dstk = stg + fr * 104 + 4 * fq;
; #pragma unroll
;                     for (int n = 0; n < 4; ++n) { const f32x4 v = acc[mi][n] * rk * gvv[n]; u32x2 wv; wv.x = cvt_pk(v[0], v[1]); wv.y = cvt_pk(v[2], v[3]); *(LAS u32x2*)(dstk + 16 * n) = wv; }
;                     { kr1 = kr1 * rk * gvv[4]; kr2 = kr2 * rk * gvv[5];
;                       f32x4 o1, o2;
; #pragma unroll
;                       for (int i = 0; i < 4; ++i) { float sn, cs; sincos_rr((float)t * frq[i], sn, cs);
;                           o1[i] = kr1[i] * cs - kr2[i] * sn; o2[i] = kr1[i] * sn + kr2[i] * cs; }
;                       u32x2 wv; wv.x = cvt_pk(o1[0], o1[1]); wv.y = cvt_pk(o1[2], o1[3]); *(LAS u32x2*)(dstk + 64) = wv; wv.x = cvt_pk(o2[0], o2[1]); wv.y = cvt_pk(o2[2], o2[3]); *(LAS u32x2*)(dstk + 80) = wv; }
;                     asm volatile("s_waitcnt lgkmcnt(0)" ::: "memory");
; #pragma unroll
;                     for (int j = 0; j < 3; ++j) { const int c = lane + 64 * j, rw = c / 12, cc = c % 12; const int row2 = 16 * (mi ? blk1 : pb) + rw, b2 = row2 / TT, t2 = row2 % TT;
;                         const u32x4 v = *(const LAS u32x4*)(stg + rw * 104 + 8 * cc);
;                         if (valid) __builtin_nontemporal_store(v, (u32x4*)(Kb + (((size_t)(b2 * NH + h)) * TKP + t2) * QKH + 8 * cc)); }
	v_add_f32_e32 v127, v127, v133
	ds_bpermute_b32 v133, v105, v127
	s_waitcnt lgkmcnt(0)
	v_add_f32_e32 v127, v127, v133
	v_fmamk_f32 v127, v127, 0x3c2aaaab, v140
	v_rsq_f32_e32 v180, v127
	v_add_u32_e32 v127, v160, v114
	v_mov_b32_e32 v133, v134
	v_pk_mul_f32 v[182:183], v[182:183], v[180:181] op_sel_hi:[1,0]
	v_pk_mul_f32 v[128:129], v[128:129], v[180:181] op_sel_hi:[1,0]
	v_pk_mul_f32 v[182:183], v[6:7], v[182:183]
	v_pk_mul_f32 v[128:129], v[8:9], v[128:129]
	v_cvt_pk_bf16_f32 v182, v182, v183
	v_pk_mul_f32 v[188:189], v[188:189], v[180:181] op_sel_hi:[1,0]
	v_cvt_pk_bf16_f32 v183, v128, v129
	v_pk_mul_f32 v[128:129], v[190:191], v[180:181] op_sel_hi:[1,0]
	v_pk_mul_f32 v[188:189], v[12:13], v[188:189]
	v_pk_mul_f32 v[128:129], v[10:11], v[128:129]
	v_pk_mul_f32 v[134:135], v[138:139], v[180:181] op_sel_hi:[1,0]
	v_cvt_pk_bf16_f32 v128, v128, v129
	v_cvt_pk_bf16_f32 v129, v188, v189
	ds_write2_b64 v127, v[182:183], v[128:129] offset1:4
	v_pk_mul_f32 v[128:129], v[196:197], v[180:181] op_sel_hi:[1,0]
	v_pk_mul_f32 v[182:183], v[194:195], v[180:181] op_sel_hi:[1,0]
	v_pk_mul_f32 v[128:129], v[14:15], v[128:129]
	v_pk_mul_f32 v[182:183], v[16:17], v[182:183]
	v_cvt_pk_bf16_f32 v128, v128, v129
	v_mov_b32_e32 v139, v134
	v_cvt_pk_bf16_f32 v129, v182, v183
	v_pk_mul_f32 v[182:183], v[184:185], v[180:181] op_sel_hi:[1,0]
	v_pk_mul_f32 v[184:185], v[186:187], v[180:181] op_sel_hi:[1,0]
	v_pk_mul_f32 v[182:183], v[18:19], v[182:183]
	v_pk_mul_f32 v[184:185], v[20:21], v[184:185]
	v_cvt_pk_bf16_f32 v182, v182, v183
	v_pk_mul_f32 v[132:133], v[132:133], v[180:181] op_sel_hi:[1,0]
	v_cvt_pk_bf16_f32 v183, v184, v185
	ds_write2_b64 v127, v[128:129], v[182:183] offset0:8 offset1:12
	v_mul_hi_i32 v128, v126, s90
	v_lshrrev_b32_e32 v129, 31, v128
	v_ashrrev_i32_e32 v128, 7, v128
	v_add_u32_e32 v128, v128, v129
	v_mul_lo_u32 v128, v128, s86
	v_sub_u32_e32 v126, v126, v128
	v_cvt_f32_i32_e32 v126, v126
	v_mov_b32_e32 v128, v137
	v_mov_b32_e32 v137, v130
	v_mov_b32_e32 v129, v131
	v_pk_mul_f32 v[130:131], v[180:181], v[136:137] op_sel_hi:[0,1]
	v_mul_f32_e32 v136, v154, v126
	v_mul_f32_e32 v137, 0.15915494, v136
	v_rndne_f32_e32 v137, v137
	v_fmac_f32_e32 v136, 0xc0c90fdb, v137
	v_fmac_f32_e32 v136, 0x343bbd2e, v137
	v_mul_f32_e32 v136, 0.15915494, v136
	v_sin_f32_e32 v137, v136
	v_cos_f32_e32 v136, v136
	v_mov_b32_e32 v138, v130
	v_mul_f32_e32 v130, v155, v126
	v_mul_f32_e32 v134, 0.15915494, v130
	v_pk_mul_f32 v[138:139], v[118:119], v[138:139]
	v_rndne_f32_e32 v134, v134
	v_pk_mul_f32 v[128:129], v[180:181], v[128:129] op_sel_hi:[0,1]
	v_pk_mul_f32 v[180:181], v[136:137], v[138:139]
	v_fmac_f32_e32 v130, 0xc0c90fdb, v134
	v_sub_f32_e32 v179, v180, v181
	v_mov_b32_e32 v180, v137
	v_mov_b32_e32 v181, v136
	v_fmac_f32_e32 v130, 0x343bbd2e, v134
	v_pk_mul_f32 v[136:137], v[180:181], v[138:139]
	v_mul_f32_e32 v130, 0.15915494, v130
	v_add_f32_e32 v138, v136, v137
	v_sin_f32_e32 v137, v130
	v_cos_f32_e32 v136, v130
	v_mov_b32_e32 v134, v131
	v_pk_mul_f32 v[130:131], v[2:3], v[134:135]
	s_nop 0
	v_pk_mul_f32 v[134:135], v[136:137], v[130:131]
	s_nop 0
	v_sub_f32_e32 v139, v134, v135
	v_mov_b32_e32 v134, v137
	v_mov_b32_e32 v135, v136
	v_pk_mul_f32 v[130:131], v[134:135], v[130:131]
	v_mov_b32_e32 v134, v128
	v_add_f32_e32 v180, v130, v131
	v_mul_f32_e32 v130, v156, v126
	v_mul_f32_e32 v131, 0.15915494, v130
	v_rndne_f32_e32 v131, v131
	v_fmac_f32_e32 v130, 0xc0c90fdb, v131
	v_fmac_f32_e32 v130, 0x343bbd2e, v131
	v_mul_f32_e32 v130, 0.15915494, v130
	v_sin_f32_e32 v131, v130
	v_cos_f32_e32 v130, v130
	v_mul_f32_e32 v126, v157, v126
	v_mov_b32_e32 v135, v132
	v_mul_f32_e32 v128, 0.15915494, v126
	v_pk_mul_f32 v[134:135], v[116:117], v[134:135]
	v_rndne_f32_e32 v128, v128
	v_pk_mul_f32 v[136:137], v[130:131], v[134:135]
	v_fmac_f32_e32 v126, 0xc0c90fdb, v128
	v_sub_f32_e32 v181, v136, v137
	v_mov_b32_e32 v136, v131
	v_mov_b32_e32 v137, v130
	v_fmac_f32_e32 v126, 0x343bbd2e, v128
	v_pk_mul_f32 v[130:131], v[136:137], v[134:135]
	v_mul_f32_e32 v126, 0.15915494, v126
	v_add_f32_e32 v134, v130, v131
	v_sin_f32_e32 v131, v126
	v_cos_f32_e32 v130, v126
	v_mov_b32_e32 v132, v129
	v_pk_mul_f32 v[128:129], v[4:5], v[132:133]
	s_nop 0
	v_pk_mul_f32 v[132:133], v[130:131], v[128:129]
	s_nop 0
	v_sub_f32_e32 v126, v132, v133
	v_mov_b32_e32 v132, v131
	v_mov_b32_e32 v133, v130
	v_pk_mul_f32 v[128:129], v[132:133], v[128:129]
	v_cvt_pk_bf16_f32 v130, v138, v180
	s_nop 0
	v_add_f32_e32 v131, v128, v129
	v_cvt_pk_bf16_f32 v129, v181, v126
	v_add_u32_e32 v126, v107, v161
	v_mul_hi_i32 v132, v126, s90
	v_lshrrev_b32_e32 v133, 31, v132
	v_ashrrev_i32_e32 v132, 7, v132
	v_add_u32_e32 v133, v132, v133
	v_mul_i32_i24_e32 v132, 0x810, v133
	v_sub_u32_e32 v132, v126, v132
	v_lshl_or_b32 v126, v133, 3, s16
	v_cvt_pk_bf16_f32 v131, v134, v131
	v_mul_hi_i32_i24_e32 v135, 0x840, v126
	v_mul_i32_i24_e32 v134, 0x840, v126
	v_ashrrev_i32_e32 v133, 31, v132
	v_lshl_add_u64 v[132:133], v[134:135], 0, v[132:133]
	v_mad_u64_u32 v[134:135], s[4:5], v132, s91, v[108:109]
	v_cvt_pk_bf16_f32 v128, v179, v139
	ds_write2_b64 v127, v[128:129], v[130:131] offset0:16 offset1:20
	v_mov_b32_e32 v126, v135
	s_waitcnt lgkmcnt(0)
	v_mad_u64_u32 v[132:133], s[4:5], v133, s91, v[126:127]
	v_add_u32_e32 v126, v170, v161
	ds_read_b128 v[128:131], v173
	v_mov_b32_e32 v135, v132
	v_mul_hi_i32 v132, v126, s90
	v_lshrrev_b32_e32 v133, 31, v132
	v_ashrrev_i32_e32 v132, 7, v132
	v_add_u32_e32 v133, v132, v133
	v_mul_i32_i24_e32 v132, 0x810, v133
	v_sub_u32_e32 v132, v126, v132
	v_lshl_or_b32 v126, v133, 3, s16
	s_waitcnt lgkmcnt(0)
; #define LAS __attribute__((address_space(3)))
; __device__ __forceinline__ void qkv_head_unit(const Params& p, LAS unsigned char* lds, int h, int blk_begin, int blk_end) {
;     ...
;                 for (int mi = 0; mi < 2; ++mi) {
;                     const bool valid = (mi == 0) || two;
;                     const int t = rowm[mi] % TT;
;                     const float sc = frsq(ssv[mi] * (1.0f / 256.0f) + EPS);
;                     const u32x2 k1 = k1v[mi], k2 = k2v[mi];
;                     f32x4 kr1 = (f32x4){bflo(k1.x), bfhi(k1.x), bflo(k1.y), bfhi(k1.y)}, kr2 = (f32x4){bflo(k2.x), bfhi(k2.x), bflo(k2.y), bfhi(k2.y)};
;                     float ssq = (kr1[0] * kr1[0] + kr1[1] * kr1[1]) + (kr1[2] * kr1[2] + kr1[3] * kr1[3]) + (kr2[0] * kr2[0] + kr2[1] * kr2[1]) + (kr2[2] * kr2[2] + kr2[3] * kr2[3]);
; #pragma unroll
;                     for (int n = 0; n < 4; ++n) { acc[mi][n] *= sc; ssq += (acc[mi][n][0] * acc[mi][n][0] + acc[mi][n][1] * acc[mi][n][1]) + (acc[mi][n][2] * acc[mi][n][2] + acc[mi][n][3] * acc[mi][n][3]); }
;                     ssq += __shfl_xor(ssq, 16); ssq += __shfl_xor(ssq, 32);
;                     const float rk = frsq(ssq * (1.0f / 96.0f) + EPS);
;                     LAS bf16_t* dstk = stg + fr * 104 + 4 * fq;
; #pragma unroll
;                     for (int n = 0; n < 4; ++n) { const f32x4 v = acc[mi][n] * rk * gvv[n]; u32x2 wv; wv.x = cvt_pk(v[0], v[1]); wv.y = cvt_pk(v[2], v[3]); *(LAS u32x2*)(dstk + 16 * n) = wv; }
;                     { kr1 = kr1 * rk * gvv[4]; kr2 = kr2 * rk * gvv[5];
;                       f32x4 o1, o2;
; #pragma unroll
;                       for (int i = 0; i < 4; ++i) { float sn, cs; sincos_rr((float)t * frq[i], sn, cs);
;                           o1[i] = kr1[i] * cs - kr2[i] * sn; o2[i] = kr1[i] * sn + kr2[i] * cs; }
;                       u32x2 wv; wv.x = cvt_pk(o1[0], o1[1]); wv.y = cvt_pk(o1[2], o1[3]); *(LAS u32x2*)(dstk + 64) = wv; wv.x = cvt_pk(o2[0], o2[1]); wv.y = cvt_pk(o2[2], o2[3]); *(LAS u32x2*)(dstk + 80) = wv; }
;                     asm volatile("s_waitcnt lgkmcnt(0)" ::: "memory");
; #pragma unroll
;                     for (int j = 0; j < 3; ++j) { const int c = lane + 64 * j, rw = c / 12, cc = c % 12; const int row2 = 16 * (mi ? blk1 : pb) + rw, b2 = row2 / TT, t2 = row2 % TT;
;                         const u32x4 v = *(const LAS u32x4*)(stg + rw * 104 + 8 * cc);
	global_store_dwordx4 v[134:135], v[128:131], off nt
	v_mul_hi_i32_i24_e32 v135, 0x840, v126
	v_mul_i32_i24_e32 v134, 0x840, v126
	v_ashrrev_i32_e32 v133, 31, v132
	v_lshl_add_u64 v[132:133], v[134:135], 0, v[132:133]
	v_mad_u64_u32 v[134:135], s[4:5], v132, s91, v[110:111]
	v_mov_b32_e32 v126, v135
	v_mad_u64_u32 v[132:133], s[4:5], v133, s91, v[126:127]
	v_add_u32_e32 v126, v171, v161
	ds_read_b128 v[128:131], v174
	v_mov_b32_e32 v135, v132
	v_mul_hi_i32 v132, v126, s90
	v_lshrrev_b32_e32 v133, 31, v132
	v_ashrrev_i32_e32 v132, 7, v132
	v_add_u32_e32 v133, v132, v133
	v_mul_i32_i24_e32 v132, 0x810, v133
	v_sub_u32_e32 v132, v126, v132
	v_lshl_or_b32 v126, v133, 3, s16
	s_waitcnt lgkmcnt(0)
	global_store_dwordx4 v[134:135], v[128:131], off nt
	v_mul_hi_i32_i24_e32 v135, 0x840, v126
	v_mul_i32_i24_e32 v134, 0x840, v126
	v_ashrrev_i32_e32 v133, 31, v132
	ds_read_b128 v[128:131], v175
	v_lshl_add_u64 v[132:133], v[134:135], 0, v[132:133]
	v_mad_u64_u32 v[134:135], s[4:5], v132, s91, v[112:113]
	v_mov_b32_e32 v126, v135
	v_mad_u64_u32 v[132:133], s[4:5], v133, s91, v[126:127]
	v_mov_b32_e32 v135, v132
	s_waitcnt lgkmcnt(0)
	global_store_dwordx4 v[134:135], v[128:131], off nt
	s_waitcnt lgkmcnt(0)
	v_fmamk_f32 v121, v121, 0x3b800000, v140
	v_rsq_f32_e32 v126, v121
	v_lshlrev_b32_e32 v133, 16, v125
	v_lshlrev_b32_e32 v132, 16, v124
	v_and_b32_e32 v125, 0xffff0000, v125
	v_and_b32_e32 v124, 0xffff0000, v124
	v_pk_mul_f32 v[134:135], v[124:125], v[124:125]
	v_and_b32_e32 v137, 0xffff0000, v122
	v_pk_fma_f32 v[134:135], v[132:133], v[132:133], v[134:135]
	v_lshlrev_b32_e32 v136, 16, v122
	v_pk_mul_f32 v[98:99], v[126:127], v[98:99] op_sel_hi:[0,1]
	v_pk_mul_f32 v[100:101], v[126:127], v[100:101] op_sel_hi:[0,1]
	v_mul_f32_e32 v138, v137, v137
	v_and_b32_e32 v130, 0xffff0000, v123
	v_mul_f32_e32 v121, v100, v100
	v_mul_f32_e32 v179, v101, v101
	v_mov_b32_e32 v131, v99
	v_pk_add_f32 v[134:135], v[134:135], v[134:135] op_sel:[0,1] op_sel_hi:[1,0]
	v_pk_fma_f32 v[138:139], v[136:137], v[136:137], v[138:139] op_sel_hi:[1,1,0]
	v_lshlrev_b32_e32 v128, 16, v123
	v_mov_b32_e32 v129, v98
	v_pk_mul_f32 v[122:123], v[130:131], v[130:131]
	v_mov_b32_e32 v135, v121
	v_mov_b32_e32 v139, v179
	v_pk_fma_f32 v[122:123], v[128:129], v[128:129], v[122:123]
	v_pk_add_f32 v[134:135], v[134:135], v[138:139]
	v_pk_mul_f32 v[88:89], v[126:127], v[88:89] op_sel_hi:[0,1]
	v_pk_mul_f32 v[86:87], v[126:127], v[86:87] op_sel_hi:[0,1]
	v_pk_add_f32 v[122:123], v[122:123], v[134:135]
	v_pk_mul_f32 v[134:135], v[86:87], v[86:87]
	v_pk_mul_f32 v[138:139], v[88:89], v[88:89]
	v_pk_mul_f32 v[90:91], v[126:127], v[90:91] op_sel_hi:[0,1]
	v_pk_mov_b32 v[180:181], v[134:135], v[138:139] op_sel:[1,0]
	v_mov_b32_e32 v135, v139
	v_pk_add_f32 v[134:135], v[180:181], v[134:135]
	v_mul_f32_e32 v121, v90, v90
	v_mul_f32_e32 v129, v91, v91
	v_pk_add_f32 v[122:123], v[122:123], v[122:123] op_sel:[0,1] op_sel_hi:[1,0]
	v_pk_add_f32 v[134:135], v[134:135], v[134:135] op_sel:[0,1] op_sel_hi:[1,0]
	v_pk_mul_f32 v[96:97], v[126:127], v[96:97] op_sel_hi:[0,1]
	v_pk_mul_f32 v[94:95], v[126:127], v[94:95] op_sel_hi:[0,1]
	v_mov_b32_e32 v123, v121
	v_mov_b32_e32 v135, v129
	v_pk_mul_f32 v[92:93], v[126:127], v[92:93] op_sel_hi:[0,1]
	v_pk_add_f32 v[122:123], v[122:123], v[134:135]
	v_mul_f32_e32 v134, v95, v95
	v_mul_f32_e32 v138, v97, v97
	v_mul_f32_e32 v131, v92, v92
	v_mul_f32_e32 v179, v93, v93
	v_pk_fma_f32 v[134:135], v[94:95], v[94:95], v[134:135] op_sel_hi:[1,1,0]
	v_pk_fma_f32 v[138:139], v[96:97], v[96:97], v[138:139] op_sel_hi:[1,1,0]
	v_mov_b32_e32 v135, v131
	v_mov_b32_e32 v139, v179
	v_pk_add_f32 v[134:135], v[134:135], v[138:139]
	v_mov_b32_e32 v129, v130
	v_pk_add_f32 v[122:123], v[122:123], v[134:135]
	s_nop 0
	v_add_f32_e32 v121, v122, v123
	ds_bpermute_b32 v122, v103, v121
	s_waitcnt lgkmcnt(0)
	v_add_f32_e32 v121, v121, v122
	ds_bpermute_b32 v122, v105, v121
	s_waitcnt lgkmcnt(0)
	v_add_f32_e32 v121, v121, v122
	v_fmamk_f32 v121, v121, 0x3c2aaaab, v140
	v_rsq_f32_e32 v122, v121
	s_nop 0
	v_pk_mul_f32 v[86:87], v[86:87], v[122:123] op_sel_hi:[1,0]
	v_pk_mul_f32 v[98:99], v[98:99], v[122:123] op_sel_hi:[1,0]
	v_pk_mul_f32 v[88:89], v[88:89], v[122:123] op_sel_hi:[1,0]
	v_pk_mul_f32 v[86:87], v[10:11], v[86:87]
	v_pk_mul_f32 v[100:101], v[100:101], v[122:123] op_sel_hi:[1,0]
	v_pk_mul_f32 v[98:99], v[6:7], v[98:99]
	v_pk_mul_f32 v[88:89], v[12:13], v[88:89]
	v_cvt_pk_bf16_f32 v86, v86, v87
	v_pk_mul_f32 v[100:101], v[8:9], v[100:101]
	v_cvt_pk_bf16_f32 v87, v88, v89
	v_cvt_pk_bf16_f32 v98, v98, v99
	v_pk_mul_f32 v[88:89], v[96:97], v[122:123] op_sel_hi:[1,0]
	v_cvt_pk_bf16_f32 v99, v100, v101
	ds_write2_b64 v127, v[98:99], v[86:87] offset1:4
	v_pk_mul_f32 v[86:87], v[94:95], v[122:123] op_sel_hi:[1,0]
	v_pk_mul_f32 v[88:89], v[16:17], v[88:89]
	v_pk_mul_f32 v[86:87], v[14:15], v[86:87]
	s_nop 0
	v_cvt_pk_bf16_f32 v86, v86, v87
	v_cvt_pk_bf16_f32 v87, v88, v89
	v_pk_mul_f32 v[88:89], v[90:91], v[122:123] op_sel_hi:[1,0]
	v_pk_mul_f32 v[90:91], v[92:93], v[122:123] op_sel_hi:[1,0]
	v_pk_mul_f32 v[88:89], v[18:19], v[88:89]
	v_pk_mul_f32 v[90:91], v[20:21], v[90:91]
	v_cvt_pk_bf16_f32 v88, v88, v89
	v_pk_mul_f32 v[92:93], v[136:137], v[122:123] op_sel_hi:[1,0]
	v_cvt_pk_bf16_f32 v89, v90, v91
	ds_write2_b64 v127, v[86:87], v[88:89] offset0:8 offset1:12
	v_mul_hi_i32 v86, v120, s90
	v_lshrrev_b32_e32 v87, 31, v86
	v_ashrrev_i32_e32 v86, 7, v86
	v_add_u32_e32 v86, v86, v87
	v_mul_lo_u32 v86, v86, s86
	v_sub_u32_e32 v90, v120, v86
	v_cvt_f32_i32_e32 v100, v90
	v_mov_b32_e32 v86, v133
	v_mov_b32_e32 v133, v124
	v_pk_mul_f32 v[88:89], v[122:123], v[132:133] op_sel_hi:[0,1]
; #define LAS __attribute__((address_space(3)))
; __device__ __forceinline__ unsigned cvt_pk(float lo, float hi) { unsigned r; asm("v_cvt_pk_bf16_f32 %0, %1, %2" : "=v"(r) : "v"(lo), "v"(hi)); return r; }
; __device__ __forceinline__ void qkv_head_unit(const Params& p, LAS unsigned char* lds, int h, int blk_begin, int blk_end) {
;     ...
;                     { kr1 = kr1 * rk * gvv[4]; kr2 = kr2 * rk * gvv[5];
;                       f32x4 o1, o2;
; #pragma unroll
;                       for (int i = 0; i < 4; ++i) { float sn, cs; sincos_rr((float)t * frq[i], sn, cs);
;                           o1[i] = kr1[i] * cs - kr2[i] * sn; o2[i] = kr1[i] * sn + kr2[i] * cs; }
;                       u32x2 wv; wv.x = cvt_pk(o1[0], o1[1]); wv.y = cvt_pk(o1[2], o1[3]); *(LAS u32x2*)(dstk + 64) = wv; wv.x = cvt_pk(o2[0], o2[1]); wv.y = cvt_pk(o2[2], o2[3]); *(LAS u32x2*)(dstk + 80) = wv; }
;                     asm volatile("s_waitcnt lgkmcnt(0)" ::: "memory");
; #pragma unroll
;                     for (int j = 0; j < 3; ++j) { const int c = lane + 64 * j, rw = c / 12, cc = c % 12; const int row2 = 16 * (mi ? blk1 : pb) + rw, b2 = row2 / TT, t2 = row2 % TT;
;                         const u32x4 v = *(const LAS u32x4*)(stg + rw * 104 + 8 * cc);
;                         if (valid) __builtin_nontemporal_store(v, (u32x4*)(Kb + (((size_t)(b2 * NH + h)) * TKP + t2) * QKH + 8 * cc)); }
	v_mul_f32_e32 v94, v154, v100
	v_mul_f32_e32 v95, 0.15915494, v94
	v_rndne_f32_e32 v95, v95
	v_fmac_f32_e32 v94, 0xc0c90fdb, v95
	v_fmac_f32_e32 v94, 0x343bbd2e, v95
	v_mul_f32_e32 v94, 0.15915494, v94
	v_sin_f32_e32 v95, v94
	v_cos_f32_e32 v94, v94
	v_mov_b32_e32 v96, v88
	v_mul_f32_e32 v88, v155, v100
	v_mov_b32_e32 v97, v92
	v_mul_f32_e32 v92, 0.15915494, v88
	v_rndne_f32_e32 v92, v92
	v_pk_mul_f32 v[96:97], v[118:119], v[96:97]
	v_fmac_f32_e32 v88, 0xc0c90fdb, v92
	v_pk_mul_f32 v[98:99], v[94:95], v[96:97]
	v_fmac_f32_e32 v88, 0x343bbd2e, v92
	v_sub_f32_e32 v101, v98, v99
	v_mov_b32_e32 v98, v95
	v_mov_b32_e32 v99, v94
	v_mul_f32_e32 v88, 0.15915494, v88
	v_pk_mul_f32 v[94:95], v[98:99], v[96:97]
	v_sin_f32_e32 v97, v88
	v_cos_f32_e32 v96, v88
	v_mov_b32_e32 v92, v89
	v_pk_mul_f32 v[88:89], v[2:3], v[92:93]
	v_mov_b32_e32 v87, v125
	v_pk_mul_f32 v[92:93], v[96:97], v[88:89]
	v_pk_mul_f32 v[86:87], v[122:123], v[86:87] op_sel_hi:[0,1]
	v_sub_f32_e32 v99, v92, v93
	v_mov_b32_e32 v92, v97
	v_mov_b32_e32 v93, v96
	v_pk_mul_f32 v[88:89], v[92:93], v[88:89]
	v_pk_mul_f32 v[90:91], v[128:129], v[122:123] op_sel_hi:[1,0]
	v_add_f32_e32 v96, v88, v89
	v_mul_f32_e32 v88, v156, v100
	v_mul_f32_e32 v89, 0.15915494, v88
	v_rndne_f32_e32 v89, v89
	v_fmac_f32_e32 v88, 0xc0c90fdb, v89
	v_fmac_f32_e32 v88, 0x343bbd2e, v89
	v_mul_f32_e32 v88, 0.15915494, v88
	v_sin_f32_e32 v89, v88
	v_cos_f32_e32 v88, v88
	v_mov_b32_e32 v92, v86
	v_mul_f32_e32 v86, v157, v100
	v_mov_b32_e32 v93, v90
	v_mul_f32_e32 v90, 0.15915494, v86
	v_rndne_f32_e32 v90, v90
	v_pk_mul_f32 v[92:93], v[116:117], v[92:93]
	v_fmac_f32_e32 v86, 0xc0c90fdb, v90
	v_add_f32_e32 v98, v94, v95
	v_pk_mul_f32 v[94:95], v[88:89], v[92:93]
	v_fmac_f32_e32 v86, 0x343bbd2e, v90
	v_sub_f32_e32 v97, v94, v95
	v_mov_b32_e32 v94, v89
	v_mov_b32_e32 v95, v88
	v_mul_f32_e32 v86, 0.15915494, v86
	v_pk_mul_f32 v[88:89], v[94:95], v[92:93]
	v_sin_f32_e32 v93, v86
	v_cos_f32_e32 v92, v86
	v_mov_b32_e32 v90, v87
	v_pk_mul_f32 v[86:87], v[4:5], v[90:91]
	v_add_f32_e32 v94, v88, v89
	v_pk_mul_f32 v[88:89], v[92:93], v[86:87]
	s_nop 0
	v_sub_f32_e32 v90, v88, v89
	v_mov_b32_e32 v88, v93
	v_mov_b32_e32 v89, v92
	v_pk_mul_f32 v[86:87], v[88:89], v[86:87]
	v_cvt_pk_bf16_f32 v88, v98, v96
	s_nop 0
	v_add_f32_e32 v89, v86, v87
	v_cvt_pk_bf16_f32 v86, v101, v99
	v_cvt_pk_bf16_f32 v87, v97, v90
	v_cvt_pk_bf16_f32 v89, v94, v89
	ds_write2_b64 v127, v[86:87], v[88:89] offset0:16 offset1:20
	s_waitcnt lgkmcnt(0)
	s_and_saveexec_b64 s[4:5], vcc
	s_cbranch_execz .LBB0_526
	v_or_b32_e32 v90, v178, v107
	v_mul_hi_i32 v91, v90, s90
	v_lshrrev_b32_e32 v92, 31, v91
	v_ashrrev_i32_e32 v91, 7, v91
	v_add_u32_e32 v91, v91, v92
	v_mul_i32_i24_e32 v92, 0x810, v91
	v_sub_u32_e32 v90, v90, v92
	v_lshl_or_b32 v91, v91, 3, s16
	v_mul_hi_i32_i24_e32 v93, 0x840, v91
	v_mul_i32_i24_e32 v92, 0x840, v91
	v_ashrrev_i32_e32 v91, 31, v90
	ds_read_b128 v[86:89], v173
	v_lshl_add_u64 v[90:91], v[92:93], 0, v[90:91]
	v_mad_u64_u32 v[94:95], s[8:9], v90, s91, v[108:109]
	v_mov_b32_e32 v90, v95
	v_mad_u64_u32 v[90:91], s[8:9], v91, s91, v[90:91]
	v_mov_b32_e32 v95, v90
	ds_read_b128 v[90:93], v174
	s_waitcnt lgkmcnt(1)
	global_store_dwordx4 v[94:95], v[86:89], off nt
	s_nop 1
	v_or_b32_e32 v86, v178, v170
	v_mul_hi_i32 v87, v86, s90
	v_lshrrev_b32_e32 v88, 31, v87
	v_ashrrev_i32_e32 v87, 7, v87
	v_add_u32_e32 v87, v87, v88
	v_mul_i32_i24_e32 v88, 0x810, v87
	v_sub_u32_e32 v86, v86, v88
	v_lshl_or_b32 v87, v87, 3, s16
	v_mul_hi_i32_i24_e32 v89, 0x840, v87
	v_mul_i32_i24_e32 v88, 0x840, v87
	v_ashrrev_i32_e32 v87, 31, v86
	v_lshl_add_u64 v[86:87], v[88:89], 0, v[86:87]
	v_mad_u64_u32 v[88:89], s[8:9], v86, s91, v[110:111]
	v_mov_b32_e32 v86, v89
	v_mad_u64_u32 v[86:87], s[8:9], v87, s91, v[86:87]
	v_mov_b32_e32 v89, v86
	s_waitcnt lgkmcnt(0)
	global_store_dwordx4 v[88:89], v[90:93], off nt
	ds_read_b128 v[86:89], v175
	s_nop 0
	v_or_b32_e32 v90, v178, v171
	v_mul_hi_i32 v91, v90, s90
	v_lshrrev_b32_e32 v92, 31, v91
	v_ashrrev_i32_e32 v91, 7, v91
	v_add_u32_e32 v91, v91, v92
	v_mul_i32_i24_e32 v92, 0x810, v91
	v_sub_u32_e32 v90, v90, v92
	v_lshl_or_b32 v91, v91, 3, s16
	v_mul_hi_i32_i24_e32 v93, 0x840, v91
	v_mul_i32_i24_e32 v92, 0x840, v91
	v_ashrrev_i32_e32 v91, 31, v90
	v_lshl_add_u64 v[90:91], v[92:93], 0, v[90:91]
	v_mad_u64_u32 v[92:93], s[8:9], v90, s91, v[112:113]
	v_mov_b32_e32 v90, v93
	v_mad_u64_u32 v[90:91], s[8:9], v91, s91, v[90:91]
	v_mov_b32_e32 v93, v90
	s_waitcnt lgkmcnt(0)
	global_store_dwordx4 v[92:93], v[86:89], off nt
; #define LAS __attribute__((address_space(3)))
; #define MFMA16(a, b, c) __builtin_amdgcn_mfma_f32_16x16x32_bf16((a), (b), (c), 0, 0, 0)
; __device__ __forceinline__ void qkv_head_unit(const Params& p, LAS unsigned char* lds, int h, int blk_begin, int blk_end) {
;     ...
;             {
;                 f32x4 acc[2][4];
; #pragma unroll
;                 for (int m = 0; m < 2; ++m)
; #pragma unroll
;                     for (int n = 0; n < 4; ++n) acc[m][n] = (f32x4){0.f, 0.f, 0.f, 0.f};
; #pragma unroll
;                 for (int ks = 0; ks < 8; ++ks)
; #pragma unroll
;                     for (int n = 0; n < 4; ++n) { const bf16x8 bw = *(const LAS bf16x8*)(wl + (64 + 16 * n + fr) * WKS + 32 * ks + 8 * fq);
;                         acc[0][n] = MFMA16(bw, af[0][ks], acc[0][n]); acc[1][n] = MFMA16(bw, af[1][ks], acc[1][n]); }
.LBB0_526:
	s_or_b64 exec, exec, s[4:5]
	s_waitcnt lgkmcnt(0)
	ds_read_b128 v[230:233], v165 offset:33792
	ds_read_b128 v[234:237], v165 offset:42240
	ds_read_b128 v[238:241], v165 offset:50688
	ds_read_b128 v[184:187], v165 offset:59136
	s_waitcnt lgkmcnt(3)
	v_mfma_f32_16x16x32_bf16 v[86:89], v[230:233], v[78:81], 0
	v_mfma_f32_16x16x32_bf16 v[90:93], v[230:233], v[82:85], 0
	ds_read_b128 v[230:233], v165 offset:33856
	s_waitcnt lgkmcnt(3)
	v_mfma_f32_16x16x32_bf16 v[94:97], v[234:237], v[78:81], 0
	v_mfma_f32_16x16x32_bf16 v[98:101], v[234:237], v[82:85], 0
	ds_read_b128 v[234:237], v165 offset:42304
	s_waitcnt lgkmcnt(3)
	v_mfma_f32_16x16x32_bf16 v[120:123], v[238:241], v[78:81], 0
	v_mfma_f32_16x16x32_bf16 v[128:131], v[238:241], v[82:85], 0
	ds_read_b128 v[238:241], v165 offset:50752
	s_waitcnt lgkmcnt(3)
	v_mfma_f32_16x16x32_bf16 v[132:135], v[184:187], v[78:81], 0
	v_mfma_f32_16x16x32_bf16 v[180:183], v[184:187], v[82:85], 0
	ds_read_b128 v[184:187], v165 offset:59200
	s_waitcnt lgkmcnt(3)
	v_mfma_f32_16x16x32_bf16 v[86:89], v[230:233], v[66:69], v[86:89]
	v_mfma_f32_16x16x32_bf16 v[90:93], v[230:233], v[74:77], v[90:93]
	ds_read_b128 v[230:233], v165 offset:33920
	s_waitcnt lgkmcnt(3)
	v_mfma_f32_16x16x32_bf16 v[94:97], v[234:237], v[66:69], v[94:97]
	v_mfma_f32_16x16x32_bf16 v[98:101], v[234:237], v[74:77], v[98:101]
	ds_read_b128 v[234:237], v165 offset:42368
	s_waitcnt lgkmcnt(3)
	v_mfma_f32_16x16x32_bf16 v[120:123], v[238:241], v[66:69], v[120:123]
	v_mfma_f32_16x16x32_bf16 v[128:131], v[238:241], v[74:77], v[128:131]
	ds_read_b128 v[238:241], v165 offset:50816
	s_waitcnt lgkmcnt(3)
	v_mfma_f32_16x16x32_bf16 v[132:135], v[184:187], v[66:69], v[132:135]
	v_mfma_f32_16x16x32_bf16 v[180:183], v[184:187], v[74:77], v[180:183]
	ds_read_b128 v[184:187], v165 offset:59264
	s_waitcnt lgkmcnt(3)
	v_mfma_f32_16x16x32_bf16 v[86:89], v[230:233], v[62:65], v[86:89]
	v_mfma_f32_16x16x32_bf16 v[90:93], v[230:233], v[70:73], v[90:93]
	ds_read_b128 v[230:233], v165 offset:33984
	s_waitcnt lgkmcnt(3)
	v_mfma_f32_16x16x32_bf16 v[94:97], v[234:237], v[62:65], v[94:97]
	v_mfma_f32_16x16x32_bf16 v[98:101], v[234:237], v[70:73], v[98:101]
	ds_read_b128 v[234:237], v165 offset:42432
	s_waitcnt lgkmcnt(3)
	v_mfma_f32_16x16x32_bf16 v[120:123], v[238:241], v[62:65], v[120:123]
	v_mfma_f32_16x16x32_bf16 v[128:131], v[238:241], v[70:73], v[128:131]
	ds_read_b128 v[238:241], v165 offset:50880
	s_waitcnt lgkmcnt(3)
	v_mfma_f32_16x16x32_bf16 v[132:135], v[184:187], v[62:65], v[132:135]
	v_mfma_f32_16x16x32_bf16 v[180:183], v[184:187], v[70:73], v[180:183]
	ds_read_b128 v[184:187], v165 offset:59328
	s_waitcnt lgkmcnt(3)
	v_mfma_f32_16x16x32_bf16 v[86:89], v[230:233], v[50:53], v[86:89]
	v_mfma_f32_16x16x32_bf16 v[90:93], v[230:233], v[58:61], v[90:93]
	ds_read_b128 v[230:233], v165 offset:34048
	s_waitcnt lgkmcnt(3)
	v_mfma_f32_16x16x32_bf16 v[94:97], v[234:237], v[50:53], v[94:97]
	v_mfma_f32_16x16x32_bf16 v[98:101], v[234:237], v[58:61], v[98:101]
	ds_read_b128 v[234:237], v165 offset:42496
	s_waitcnt lgkmcnt(3)
	v_mfma_f32_16x16x32_bf16 v[120:123], v[238:241], v[50:53], v[120:123]
	v_mfma_f32_16x16x32_bf16 v[128:131], v[238:241], v[58:61], v[128:131]
	ds_read_b128 v[238:241], v165 offset:50944
	s_waitcnt lgkmcnt(3)
	v_mfma_f32_16x16x32_bf16 v[132:135], v[184:187], v[50:53], v[132:135]
	v_mfma_f32_16x16x32_bf16 v[180:183], v[184:187], v[58:61], v[180:183]
	ds_read_b128 v[184:187], v165 offset:59392
	s_waitcnt lgkmcnt(3)
	v_mfma_f32_16x16x32_bf16 v[86:89], v[230:233], v[46:49], v[86:89]
	v_mfma_f32_16x16x32_bf16 v[90:93], v[230:233], v[54:57], v[90:93]
	ds_read_b128 v[230:233], v165 offset:34112
	s_waitcnt lgkmcnt(3)
	v_mfma_f32_16x16x32_bf16 v[94:97], v[234:237], v[46:49], v[94:97]
	v_mfma_f32_16x16x32_bf16 v[98:101], v[234:237], v[54:57], v[98:101]
	ds_read_b128 v[234:237], v165 offset:42560
	s_waitcnt lgkmcnt(3)
	v_mfma_f32_16x16x32_bf16 v[120:123], v[238:241], v[46:49], v[120:123]
	v_mfma_f32_16x16x32_bf16 v[128:131], v[238:241], v[54:57], v[128:131]
	ds_read_b128 v[238:241], v165 offset:51008
	s_waitcnt lgkmcnt(3)
	v_mfma_f32_16x16x32_bf16 v[132:135], v[184:187], v[46:49], v[132:135]
	v_mfma_f32_16x16x32_bf16 v[180:183], v[184:187], v[54:57], v[180:183]
	ds_read_b128 v[184:187], v165 offset:59456
	s_waitcnt lgkmcnt(3)
	v_mfma_f32_16x16x32_bf16 v[86:89], v[230:233], v[38:41], v[86:89]
	v_mfma_f32_16x16x32_bf16 v[90:93], v[230:233], v[42:45], v[90:93]
	ds_read_b128 v[230:233], v165 offset:34176
	s_waitcnt lgkmcnt(3)
	v_mfma_f32_16x16x32_bf16 v[94:97], v[234:237], v[38:41], v[94:97]
	v_mfma_f32_16x16x32_bf16 v[98:101], v[234:237], v[42:45], v[98:101]
	ds_read_b128 v[234:237], v165 offset:42624
	s_waitcnt lgkmcnt(3)
	v_mfma_f32_16x16x32_bf16 v[120:123], v[238:241], v[38:41], v[120:123]
	v_mfma_f32_16x16x32_bf16 v[128:131], v[238:241], v[42:45], v[128:131]
	ds_read_b128 v[238:241], v165 offset:51072
	s_waitcnt lgkmcnt(3)
	v_mfma_f32_16x16x32_bf16 v[132:135], v[184:187], v[38:41], v[132:135]
	v_mfma_f32_16x16x32_bf16 v[180:183], v[184:187], v[42:45], v[180:183]
	ds_read_b128 v[184:187], v165 offset:59520
	s_waitcnt lgkmcnt(3)
	v_mfma_f32_16x16x32_bf16 v[86:89], v[230:233], v[30:33], v[86:89]
	v_mfma_f32_16x16x32_bf16 v[90:93], v[230:233], v[34:37], v[90:93]
	ds_read_b128 v[230:233], v165 offset:34240
	s_waitcnt lgkmcnt(3)
	v_mfma_f32_16x16x32_bf16 v[94:97], v[234:237], v[30:33], v[94:97]
	v_mfma_f32_16x16x32_bf16 v[98:101], v[234:237], v[34:37], v[98:101]
	ds_read_b128 v[234:237], v165 offset:42688
	s_waitcnt lgkmcnt(3)
	v_mfma_f32_16x16x32_bf16 v[120:123], v[238:241], v[30:33], v[120:123]
	v_mfma_f32_16x16x32_bf16 v[128:131], v[238:241], v[34:37], v[128:131]
	ds_read_b128 v[238:241], v165 offset:51136
	s_waitcnt lgkmcnt(3)
; #define LAS __attribute__((address_space(3)))
; __device__ __forceinline__ unsigned cvt_pk(float lo, float hi) { unsigned r; asm("v_cvt_pk_bf16_f32 %0, %1, %2" : "=v"(r) : "v"(lo), "v"(hi)); return r; }
; __device__ __forceinline__ float frsq(float x) { return __builtin_amdgcn_rsqf(x); }
; #define MFMA16(a, b, c) __builtin_amdgcn_mfma_f32_16x16x32_bf16((a), (b), (c), 0, 0, 0)
; __device__ __forceinline__ void qkv_head_unit(const Params& p, LAS unsigned char* lds, int h, int blk_begin, int blk_end) {
;     ...
; #pragma unroll
;                 for (int ks = 0; ks < 8; ++ks)
; #pragma unroll
;                     for (int n = 0; n < 4; ++n) { const bf16x8 bw = *(const LAS bf16x8*)(wl + (64 + 16 * n + fr) * WKS + 32 * ks + 8 * fq);
;                         acc[0][n] = MFMA16(bw, af[0][ks], acc[0][n]); acc[1][n] = MFMA16(bw, af[1][ks], acc[1][n]); }
; #pragma unroll
;                 for (int mi = 0; mi < 2; ++mi) {
;                     const bool valid = (mi == 0) || two;
;                     const float sc = frsq(ssv[mi] * (1.0f / 256.0f) + EPS);
; #pragma unroll
;                     for (int n = 0; n < 4; ++n)
; #pragma unroll
;                         for (int i = 0; i < 4; ++i) { const int d = 16 * n + 4 * fq + i; stg[d * 16 + fr] = (bf16_t)(cvt_pk(acc[mi][n][i] * sc, 0.f) & 0xffffu); }
;                     asm volatile("s_waitcnt lgkmcnt(0)" ::: "memory");
;                     { const int row2 = 16 * (mi ? blk1 : pb), b2 = row2 / TT, t2 = row2 % TT;
;                       bf16_t* dstv = Vt + (((size_t)(b2 * NH + h)) * NKT + (t2 >> 6)) * 4096 + (t2 & 63);
; #pragma unroll
;                       for (int j = 0; j < 2; ++j) { const int c = lane + 64 * j, d = c >> 1, hf = c & 1; if (valid) __builtin_nontemporal_store(*(const LAS u32x4*)(stg + d * 16 + 8 * hf), (u32x4*)(dstv + d * 64 + 8 * hf)); } }
;                     asm volatile("s_waitcnt lgkmcnt(0)" ::: "memory"); __builtin_amdgcn_sched_barrier(0);
	v_mfma_f32_16x16x32_bf16 v[132:135], v[184:187], v[30:33], v[132:135]
	v_mfma_f32_16x16x32_bf16 v[180:183], v[184:187], v[34:37], v[180:183]
	ds_read_b128 v[184:187], v165 offset:59584
	s_waitcnt lgkmcnt(3)
	v_mfma_f32_16x16x32_bf16 v[50:53], v[230:233], v[22:25], v[86:89]
	v_mfma_f32_16x16x32_bf16 v[30:33], v[230:233], v[26:29], v[90:93]
	s_waitcnt lgkmcnt(2)
	v_mfma_f32_16x16x32_bf16 v[46:49], v[234:237], v[22:25], v[94:97]
	v_mfma_f32_16x16x32_bf16 v[34:37], v[234:237], v[26:29], v[98:101]
	s_waitcnt lgkmcnt(1)
	v_mfma_f32_16x16x32_bf16 v[54:57], v[238:241], v[22:25], v[120:123]
	v_mfma_f32_16x16x32_bf16 v[38:41], v[238:241], v[26:29], v[128:131]
	s_waitcnt lgkmcnt(0)
	v_mfma_f32_16x16x32_bf16 v[62:65], v[184:187], v[22:25], v[132:135]
	v_mfma_f32_16x16x32_bf16 v[22:25], v[184:187], v[26:29], v[180:183]
	s_nop 7
	v_mul_f32_e32 v26, v0, v50
	v_cvt_pk_bf16_f32 v26, v26, v1
	ds_write_b16 v166, v26
	v_mul_f32_e32 v26, v0, v51
	v_cvt_pk_bf16_f32 v26, v26, v1
	ds_write_b16 v167, v26
	v_mul_f32_e32 v26, v0, v52
	v_cvt_pk_bf16_f32 v26, v26, v1
	ds_write_b16 v168, v26
	v_mul_f32_e32 v26, v0, v53
	v_cvt_pk_bf16_f32 v26, v26, v1
	ds_write_b16 v169, v26
	v_mul_f32_e32 v26, v0, v46
	v_cvt_pk_bf16_f32 v26, v26, v1
	ds_write_b16 v166, v26 offset:512
	v_mul_f32_e32 v26, v0, v47
	v_cvt_pk_bf16_f32 v26, v26, v1
	ds_write_b16 v166, v26 offset:544
	v_mul_f32_e32 v26, v0, v48
	v_cvt_pk_bf16_f32 v26, v26, v1
	ds_write_b16 v166, v26 offset:576
	v_mul_f32_e32 v26, v0, v49
	v_cvt_pk_bf16_f32 v26, v26, v1
	ds_write_b16 v166, v26 offset:608
	v_mul_f32_e32 v26, v0, v54
	v_cvt_pk_bf16_f32 v26, v26, v1
	ds_write_b16 v166, v26 offset:1024
	v_mul_f32_e32 v26, v0, v55
	v_cvt_pk_bf16_f32 v26, v26, v1
	ds_write_b16 v166, v26 offset:1056
	v_mul_f32_e32 v26, v0, v56
	v_cvt_pk_bf16_f32 v26, v26, v1
	ds_write_b16 v166, v26 offset:1088
	v_mul_f32_e32 v26, v0, v57
	v_cvt_pk_bf16_f32 v26, v26, v1
	ds_write_b16 v166, v26 offset:1120
	v_mul_f32_e32 v26, v0, v62
	v_cvt_pk_bf16_f32 v26, v26, v1
	ds_write_b16 v166, v26 offset:1536
	v_mul_f32_e32 v26, v0, v63
	v_cvt_pk_bf16_f32 v26, v26, v1
	ds_write_b16 v166, v26 offset:1568
	v_mul_f32_e32 v26, v0, v64
	v_mul_f32_e32 v0, v0, v65
	v_cvt_pk_bf16_f32 v0, v0, v1
	v_cvt_pk_bf16_f32 v26, v26, v1
	ds_write_b16 v166, v0 offset:1632
	v_mul_hi_i32 v0, v159, s90
	ds_write_b16 v166, v26 offset:1600
	v_lshrrev_b32_e32 v26, 31, v0
	v_lshrrev_b32_e32 v0, 3, v0
	v_add_u32_e32 v0, v0, v26
	v_mul_hi_i32 v26, v161, s90
	v_lshrrev_b32_e32 v27, 31, v26
	v_ashrrev_i32_e32 v26, 7, v26
	v_add_u32_e32 v26, v26, v27
	v_mul_lo_u32 v26, v26, s86
	v_sub_u32_e32 v28, v161, v26
	v_ashrrev_i32_e32 v26, 6, v28
	v_lshl_or_b32 v0, v0, 3, s16
	v_ashrrev_i32_e32 v27, 31, v26
	s_waitcnt lgkmcnt(0)
	v_mad_i64_i32 v[26:27], s[4:5], v0, 33, v[26:27]
	v_lshlrev_b64 v[26:27], 13, v[26:27]
	v_and_b32_e32 v0, 48, v28
	ds_read_b128 v[42:45], v172
	v_lshl_add_u64 v[26:27], s[46:47], 0, v[26:27]
	v_lshlrev_b32_e32 v0, 1, v0
	v_lshl_add_u64 v[26:27], v[26:27], 0, v[0:1]
	v_lshlrev_b32_e32 v0, 1, v102
	v_lshl_add_u64 v[46:47], v[26:27], 0, v[0:1]
	v_lshlrev_b32_e32 v28, 1, v104
	v_mov_b32_e32 v29, v1
	v_lshl_add_u64 v[26:27], v[46:47], 0, v[28:29]
	s_waitcnt lgkmcnt(0)
	global_store_dwordx4 v[26:27], v[42:45], off nt
	ds_read_b128 v[42:45], v176
	v_lshlrev_b32_e32 v26, 1, v106
	v_mov_b32_e32 v27, v1
	v_lshl_add_u64 v[46:47], v[46:47], 0, v[26:27]
	s_waitcnt lgkmcnt(0)
	global_store_dwordx4 v[46:47], v[42:45], off nt
	s_waitcnt lgkmcnt(0)
	v_mul_f32_e32 v30, v126, v30
	v_cvt_pk_bf16_f32 v30, v30, v1
	ds_write_b16 v166, v30
	v_mul_f32_e32 v30, v126, v31
	v_cvt_pk_bf16_f32 v30, v30, v1
	ds_write_b16 v167, v30
	v_mul_f32_e32 v30, v126, v32
	v_cvt_pk_bf16_f32 v30, v30, v1
	ds_write_b16 v168, v30
	v_mul_f32_e32 v30, v126, v33
	v_cvt_pk_bf16_f32 v30, v30, v1
	ds_write_b16 v169, v30
	v_mul_f32_e32 v30, v126, v34
	v_cvt_pk_bf16_f32 v30, v30, v1
	ds_write_b16 v166, v30 offset:512
	v_mul_f32_e32 v30, v126, v35
	v_cvt_pk_bf16_f32 v30, v30, v1
	ds_write_b16 v166, v30 offset:544
	v_mul_f32_e32 v30, v126, v36
	v_cvt_pk_bf16_f32 v30, v30, v1
	ds_write_b16 v166, v30 offset:576
	v_mul_f32_e32 v30, v126, v37
	v_cvt_pk_bf16_f32 v30, v30, v1
	ds_write_b16 v166, v30 offset:608
	v_mul_f32_e32 v30, v126, v38
	v_mul_f32_e32 v22, v126, v22
	v_cvt_pk_bf16_f32 v30, v30, v1
	v_cvt_pk_bf16_f32 v22, v22, v1
	ds_write_b16 v166, v30 offset:1024
	v_mul_f32_e32 v30, v126, v39
	ds_write_b16 v166, v22 offset:1536
	v_mul_f32_e32 v22, v126, v23
	v_cvt_pk_bf16_f32 v30, v30, v1
	v_cvt_pk_bf16_f32 v22, v22, v1
	ds_write_b16 v166, v30 offset:1056
	v_mul_f32_e32 v30, v126, v40
	ds_write_b16 v166, v22 offset:1568
	v_mul_f32_e32 v22, v126, v24
	v_cvt_pk_bf16_f32 v30, v30, v1
	v_cvt_pk_bf16_f32 v22, v22, v1
	ds_write_b16 v166, v30 offset:1088
	v_mul_f32_e32 v30, v126, v41
	ds_write_b16 v166, v22 offset:1600
	v_mul_f32_e32 v22, v126, v25
	v_cvt_pk_bf16_f32 v30, v30, v1
	ds_write_b16 v166, v30 offset:1120
	v_cvt_pk_bf16_f32 v22, v22, v1
	ds_write_b16 v166, v22 offset:1632
	s_waitcnt lgkmcnt(0)
	s_and_saveexec_b64 s[4:5], vcc
	s_cbranch_execz .LBB0_523
	v_mul_hi_i32 v22, v177, s90
	v_lshrrev_b32_e32 v23, 31, v22
	v_lshrrev_b32_e32 v22, 3, v22
	v_add_u32_e32 v22, v22, v23
	v_lshl_or_b32 v24, v22, 3, s16
	v_mul_hi_i32 v22, v178, s90
	v_lshrrev_b32_e32 v23, 31, v22
	v_ashrrev_i32_e32 v22, 7, v22
	v_add_u32_e32 v22, v22, v23
	v_mul_lo_u32 v22, v22, s86
	v_sub_u32_e32 v25, v178, v22
	v_ashrrev_i32_e32 v22, 6, v25
	v_ashrrev_i32_e32 v23, 31, v22
	v_mad_i64_i32 v[22:23], s[8:9], v24, 33, v[22:23]
	v_lshlrev_b64 v[22:23], 13, v[22:23]
	v_and_b32_e32 v24, 48, v25
	v_lshl_add_u64 v[22:23], s[46:47], 0, v[22:23]
	v_lshlrev_b32_e32 v24, 1, v24
	v_mov_b32_e32 v25, v1
	v_lshl_add_u64 v[22:23], v[22:23], 0, v[24:25]
	v_lshl_add_u64 v[30:31], v[22:23], 0, v[0:1]
	ds_read_b128 v[22:25], v172
	v_lshl_add_u64 v[28:29], v[30:31], 0, v[28:29]
	v_lshl_add_u64 v[26:27], v[30:31], 0, v[26:27]
	s_waitcnt lgkmcnt(0)
	global_store_dwordx4 v[28:29], v[22:25], off nt
	ds_read_b128 v[22:25], v176
	s_waitcnt lgkmcnt(0)
	global_store_dwordx4 v[26:27], v[22:25], off nt
	s_branch .LBB0_523

; #define LAS __attribute__((address_space(3)))
; __device__ __forceinline__ unsigned cvt_pk(float lo, float hi) { unsigned r; asm("v_cvt_pk_bf16_f32 %0, %1, %2" : "=v"(r) : "v"(lo), "v"(hi)); return r; }
; #define LDS_BARRIER() asm volatile("s_waitcnt lgkmcnt(0)\n\ts_barrier" ::: "memory")
; template <int DIR>
; __device__ __forceinline__ void rnn_scan_unit(const Params& p, LAS unsigned char* lds, int b, int g) {
;     ...
;         asm volatile("s_waitcnt lgkmcnt(0)" ::: "memory");
;         LAS float* sgA = sg + (ci & 1) * 1024; LAS float* sgB = sgA + 512;
;         float av_[16], bv_[16];
;         { float A = 1.f, B = 0.f;
; #pragma unroll
;           for (int k = 0; k < 16; ++k) { const int tt = DIR == 0 ? k : 15 - k; av_[k] = al[tt * 64 + ch]; bv_[k] = bl[tt * 64 + ch]; B = av_[k] * B + bv_[k]; A *= av_[k]; }
;           sgA[seg * 64 + ch] = A; sgB[seg * 64 + ch] = B; }
;         LDS_BARRIER();
;         float h = hcar, hin = hcar;
; #pragma unroll
;         for (int s = 0; s < 8; ++s) { const int sx = DIR == 0 ? s : 7 - s; hin = (sx == seg) ? h : hin; h = sgA[sx * 64 + ch] * h + sgB[sx * 64 + ch]; }
;         hcar = h;
; #pragma unroll
;         for (int k = 0; k < 16; ++k) { const int tt = DIR == 0 ? k : 15 - k; hin = av_[k] * hin + bv_[k]; bl[tt * 64 + ch] = hin; }
;         asm volatile("s_waitcnt lgkmcnt(0)" ::: "memory");
;         { const int tk = lane >> 2, cq4 = lane & 3;
;           if (t0 + tk < TT) { const LAS float* src = bl + tk * 64 + 16 * cq4;
;               const f32x4 x0 = *(const LAS f32x4*)(src), x1 = *(const LAS f32x4*)(src + 4), x2 = *(const LAS f32x4*)(src + 8), x3 = *(const LAS f32x4*)(src + 12);
;               u32x4 w0, w1; w0.x = cvt_pk(x0[0], x0[1]); w0.y = cvt_pk(x0[2], x0[3]); w0.z = cvt_pk(x1[0], x1[1]); w0.w = cvt_pk(x1[2], x1[3]);
;               w1.x = cvt_pk(x2[0], x2[1]); w1.y = cvt_pk(x2[2], x2[3]); w1.z = cvt_pk(x3[0], x3[1]); w1.w = cvt_pk(x3[2], x3[3]);
;               bf16_t* hp = H + ((size_t)b * TT + t0 + tk) * 512 + 64 * g + 16 * cq4;
;               *(u32x4*)hp = w0; *(u32x4*)(hp + 8) = w1; } }
.Lgate_nomask_4:
	ds_write_b128 v130, v[96:99] offset:6976
	ds_write_b128 v130, v[104:107] offset:11072
	s_waitcnt lgkmcnt(0)
	v_add_u32_e32 v169, 0x80, v154
	ds_read2st64_b32 v[88:89], v169 offset0:41 offset1:42
	ds_read2st64_b32 v[90:91], v169 offset0:55 offset1:57
	v_add_u32_e32 v3, 0x80, v155
	ds_read2st64_b32 v[92:93], v3 offset0:41 offset1:57
	ds_read2st64_b32 v[94:95], v169 offset0:38 offset1:39
	ds_read2st64_b32 v[172:173], v169 offset0:43 offset1:44
	ds_read2st64_b32 v[98:99], v169 offset0:36 offset1:37
	ds_read2st64_b32 v[102:103], v169 offset0:34 offset1:35
	ds_read2st64_b32 v[96:97], v169 offset0:53 offset1:54
	s_waitcnt lgkmcnt(6)
	v_fma_f32 v0, 0, v88, v91
	ds_read2st64_b32 v[100:101], v169 offset0:51 offset1:52
	ds_read2st64_b32 v[104:105], v169 offset0:49 offset1:50
	ds_read2st64_b32 v[108:109], v169 offset0:47 offset1:48
	ds_read2st64_b32 v[114:115], v169 offset0:45 offset1:46
	s_waitcnt lgkmcnt(9)
	v_fma_f32 v0, v0, v92, v93
	v_mul_f32_e32 v3, v88, v92
	s_waitcnt lgkmcnt(8)
	v_fma_f32 v0, v0, v95, v90
	v_mul_f32_e32 v3, v3, v95
	s_waitcnt lgkmcnt(4)
	v_fma_f32 v0, v0, v94, v97
	v_mul_f32_e32 v3, v3, v94
	ds_read2st64_b32 v[106:107], v169 offset0:32 offset1:33
	ds_read2st64_b32 v[112:113], v169 offset0:30 offset1:31
	ds_read2st64_b32 v[170:171], v169 offset0:28 offset1:29
	ds_read2st64_b32 v[174:175], v169 offset0:26 offset1:27
	v_fma_f32 v0, v0, v99, v96
	v_mul_f32_e32 v3, v3, v99
	s_waitcnt lgkmcnt(7)
	v_fma_f32 v0, v0, v98, v101
	v_mul_f32_e32 v3, v3, v98
	v_fma_f32 v0, v0, v103, v100
	v_mul_f32_e32 v3, v3, v103
	s_waitcnt lgkmcnt(6)
	v_fma_f32 v0, v0, v102, v105
	v_mul_f32_e32 v3, v3, v102
	s_waitcnt lgkmcnt(3)
	v_fma_f32 v0, v0, v107, v104
	v_mul_f32_e32 v3, v3, v107
	v_fma_f32 v0, v0, v106, v109
	v_mul_f32_e32 v3, v3, v106
	s_waitcnt lgkmcnt(2)
	v_fma_f32 v0, v0, v113, v108
	v_mul_f32_e32 v3, v3, v113
	s_and_b32 s16, s34, 0x400
	v_fma_f32 v0, v0, v112, v115
	v_mul_f32_e32 v3, v3, v112
	s_lshl_b32 s16, s16, 2
	s_waitcnt lgkmcnt(1)
	v_fma_f32 v0, v0, v171, v114
	v_mul_f32_e32 v3, v3, v171
	s_add_i32 s16, s16, 0
	v_fma_f32 v0, v0, v170, v173
	v_mul_f32_e32 v3, v3, v170
	s_add_i32 s16, s16, 0x1d400
	s_waitcnt lgkmcnt(0)
	v_fma_f32 v0, v0, v175, v172
	v_mul_f32_e32 v3, v3, v175
	v_fma_f32 v0, v0, v174, v89
	v_mul_f32_e32 v3, v3, v174
	v_lshl_add_u32 v110, v116, 2, s16
	ds_write2st64_b32 v110, v3, v0 offset1:8
	s_waitcnt lgkmcnt(0)
	s_barrier
	v_lshl_add_u32 v0, v122, 2, s16
	ds_read2st64_b32 v[110:111], v0 offset0:6 offset1:7
	ds_read2st64_b32 v[176:177], v0 offset0:14 offset1:15
	s_waitcnt lgkmcnt(0)
	v_fma_f32 v3, v2, v111, v177
	v_cndmask_b32_e64 v2, v2, v3, s[0:1]
	v_fmac_f32_e32 v176, v3, v110
	v_cndmask_b32_e64 v177, v2, v176, s[2:3]
	ds_read2st64_b32 v[2:3], v0 offset0:4 offset1:5
	ds_read2st64_b32 v[110:111], v0 offset0:12 offset1:13
	s_waitcnt lgkmcnt(0)
	v_fma_f32 v3, v176, v3, v111
	v_cndmask_b32_e64 v111, v177, v3, s[4:5]
	v_fmac_f32_e32 v110, v3, v2
	ds_read2st64_b32 v[2:3], v0 offset0:2 offset1:3
	ds_read2st64_b32 v[176:177], v0 offset0:10 offset1:11
	v_cndmask_b32_e64 v111, v111, v110, s[8:9]
	s_waitcnt lgkmcnt(0)
	v_fma_f32 v3, v110, v3, v177
	v_cndmask_b32_e64 v110, v111, v3, s[10:11]
	v_fmac_f32_e32 v176, v3, v2
	v_cndmask_b32_e64 v177, v110, v176, s[12:13]
	ds_read2st64_b32 v[110:111], v0 offset1:1
	ds_read2st64_b32 v[2:3], v0 offset0:8 offset1:9
	s_waitcnt lgkmcnt(0)
	v_fma_f32 v0, v176, v111, v3
	v_cndmask_b32_e64 v3, v177, v0, s[14:15]
	v_fma_f32 v3, v88, v3, v91
	v_fmac_f32_e32 v93, v92, v3
	v_fmac_f32_e32 v90, v95, v93
	ds_write_b32 v154, v3 offset:14720
	v_fma_f32 v3, v94, v90, v97
	v_fmac_f32_e32 v96, v99, v3
	ds_write2st64_b32 v169, v3, v90 offset0:54 offset1:55
	v_fma_f32 v3, v98, v96, v101
	v_fmac_f32_e32 v100, v103, v3
	ds_write2st64_b32 v169, v3, v96 offset0:52 offset1:53
	v_fma_f32 v3, v102, v100, v105
	v_fmac_f32_e32 v104, v107, v3
	ds_write2st64_b32 v169, v3, v100 offset0:50 offset1:51
	v_fma_f32 v3, v106, v104, v109
	v_fmac_f32_e32 v108, v113, v3
	ds_write2st64_b32 v169, v3, v104 offset0:48 offset1:49
	v_fma_f32 v3, v112, v108, v115
	v_fmac_f32_e32 v114, v171, v3
	ds_write2st64_b32 v169, v3, v108 offset0:46 offset1:47
	v_fma_f32 v3, v170, v114, v173
	v_fmac_f32_e32 v172, v175, v3
	v_fmac_f32_e32 v89, v174, v172
	ds_write_b32 v155, v93 offset:14720
	ds_write2st64_b32 v169, v3, v114 offset0:44 offset1:45
	ds_write2st64_b32 v169, v89, v172 offset0:42 offset1:43
	s_waitcnt lgkmcnt(0)
	v_add_u32_e32 v3, s19, v159
	v_cmp_gt_i32_e64 s[16:17], s86, v3
	s_waitcnt vmcnt(0)
	s_and_saveexec_b64 s[76:77], s[16:17]
	s_cbranch_execz .LBB0_539
	ds_read_b128 v[88:91], v124 offset:10880
	ds_read_b128 v[92:95], v124 offset:10896
	ds_read_b128 v[96:99], v124 offset:10912
	ds_read_b128 v[100:103], v124 offset:10928
	s_waitcnt lgkmcnt(3)
	v_cvt_pk_bf16_f32 v88, v88, v89
	v_cvt_pk_bf16_f32 v89, v90, v91
	s_waitcnt lgkmcnt(2)
	v_cvt_pk_bf16_f32 v90, v92, v93
	v_cvt_pk_bf16_f32 v91, v94, v95
	s_waitcnt lgkmcnt(1)
	v_cvt_pk_bf16_f32 v92, v96, v97
	v_cvt_pk_bf16_f32 v93, v98, v99
	s_waitcnt lgkmcnt(0)
	v_cvt_pk_bf16_f32 v94, v100, v101
	v_cvt_pk_bf16_f32 v95, v102, v103
	global_store_dwordx4 v[120:121], v[88:91], off
	global_store_dwordx4 v[120:121], v[92:95], off offset:16
	s_branch .LBB0_539

; #define LAS __attribute__((address_space(3)))
; __device__ __forceinline__ unsigned cvt_pk(float lo, float hi) { unsigned r; asm("v_cvt_pk_bf16_f32 %0, %1, %2" : "=v"(r) : "v"(lo), "v"(hi)); return r; }
; #define LDS_BARRIER() asm volatile("s_waitcnt lgkmcnt(0)\n\ts_barrier" ::: "memory")
; template <int DIR>
; __device__ __forceinline__ void rnn_scan_unit(const Params& p, LAS unsigned char* lds, int b, int g) {
;     ...
;         asm volatile("s_waitcnt lgkmcnt(0)" ::: "memory");
;         LAS float* sgA = sg + (ci & 1) * 1024; LAS float* sgB = sgA + 512;
;         float av_[16], bv_[16];
;         { float A = 1.f, B = 0.f;
; #pragma unroll
;           for (int k = 0; k < 16; ++k) { const int tt = DIR == 0 ? k : 15 - k; av_[k] = al[tt * 64 + ch]; bv_[k] = bl[tt * 64 + ch]; B = av_[k] * B + bv_[k]; A *= av_[k]; }
;           sgA[seg * 64 + ch] = A; sgB[seg * 64 + ch] = B; }
;         LDS_BARRIER();
;         float h = hcar, hin = hcar;
; #pragma unroll
;         for (int s = 0; s < 8; ++s) { const int sx = DIR == 0 ? s : 7 - s; hin = (sx == seg) ? h : hin; h = sgA[sx * 64 + ch] * h + sgB[sx * 64 + ch]; }
;         hcar = h;
; #pragma unroll
;         for (int k = 0; k < 16; ++k) { const int tt = DIR == 0 ? k : 15 - k; hin = av_[k] * hin + bv_[k]; bl[tt * 64 + ch] = hin; }
;         asm volatile("s_waitcnt lgkmcnt(0)" ::: "memory");
;         { const int tk = lane >> 2, cq4 = lane & 3;
;           if (t0 + tk < TT) { const LAS float* src = bl + tk * 64 + 16 * cq4;
;               const f32x4 x0 = *(const LAS f32x4*)(src), x1 = *(const LAS f32x4*)(src + 4), x2 = *(const LAS f32x4*)(src + 8), x3 = *(const LAS f32x4*)(src + 12);
;               u32x4 w0, w1; w0.x = cvt_pk(x0[0], x0[1]); w0.y = cvt_pk(x0[2], x0[3]); w0.z = cvt_pk(x1[0], x1[1]); w0.w = cvt_pk(x1[2], x1[3]);
;               w1.x = cvt_pk(x2[0], x2[1]); w1.y = cvt_pk(x2[2], x2[3]); w1.z = cvt_pk(x3[0], x3[1]); w1.w = cvt_pk(x3[2], x3[3]);
;               bf16_t* hp = H + ((size_t)b * TT + t0 + tk) * 512 + 64 * g + 16 * cq4;
;               *(u32x4*)hp = w0; *(u32x4*)(hp + 8) = w1; } }
.Lgate_nomask_0:
	ds_write_b128 v131, v[96:99] offset:6976
	ds_write_b128 v131, v[104:107] offset:11072
	s_waitcnt lgkmcnt(0)
	v_add_u32_e32 v176, 0x80, v124
	ds_read2st64_b32 v[88:89], v176 offset0:26 offset1:27
	ds_read2st64_b32 v[90:91], v176 offset0:42 offset1:43
	ds_read2st64_b32 v[94:95], v176 offset0:28 offset1:29
	ds_read2st64_b32 v[92:93], v176 offset0:44 offset1:45
	ds_read2st64_b32 v[98:99], v176 offset0:30 offset1:31
	ds_read2st64_b32 v[96:97], v176 offset0:46 offset1:47
	ds_read2st64_b32 v[100:101], v176 offset0:32 offset1:33
	ds_read2st64_b32 v[102:103], v176 offset0:48 offset1:49
	s_waitcnt lgkmcnt(7)
	v_mul_f32_e32 v2, v88, v89
	s_waitcnt lgkmcnt(6)
	v_fma_f32 v0, 0, v88, v90
	v_fma_f32 v0, v0, v89, v91
	s_waitcnt lgkmcnt(4)
	v_fma_f32 v0, v0, v94, v92
	v_mul_f32_e32 v2, v2, v94
	v_fma_f32 v0, v0, v95, v93
	v_mul_f32_e32 v2, v2, v95
	ds_read2st64_b32 v[104:105], v176 offset0:34 offset1:35
	ds_read2st64_b32 v[106:107], v176 offset0:50 offset1:51
	s_waitcnt lgkmcnt(4)
	v_fma_f32 v0, v0, v98, v96
	v_mul_f32_e32 v2, v2, v98
	v_fma_f32 v0, v0, v99, v97
	v_mul_f32_e32 v2, v2, v99
	ds_read2st64_b32 v[110:111], v176 offset0:36 offset1:37
	ds_read2st64_b32 v[108:109], v176 offset0:52 offset1:53
	s_waitcnt lgkmcnt(4)
	v_fma_f32 v0, v0, v100, v102
	v_mul_f32_e32 v2, v2, v100
	v_fma_f32 v0, v0, v101, v103
	v_mul_f32_e32 v2, v2, v101
	ds_read2st64_b32 v[114:115], v176 offset0:38 offset1:39
	ds_read2st64_b32 v[168:169], v176 offset0:54 offset1:55
	s_waitcnt lgkmcnt(4)
	v_fma_f32 v0, v0, v104, v106
	v_mul_f32_e32 v2, v2, v104
	v_fma_f32 v0, v0, v105, v107
	v_mul_f32_e32 v2, v2, v105
	ds_read2st64_b32 v[170:171], v176 offset0:40 offset1:41
	ds_read2st64_b32 v[172:173], v176 offset0:56 offset1:57
	s_waitcnt lgkmcnt(4)
	v_fma_f32 v0, v0, v110, v108
	v_mul_f32_e32 v2, v2, v110
	s_and_b32 s16, s34, 0x400
	v_fma_f32 v0, v0, v111, v109
	v_mul_f32_e32 v2, v2, v111
	s_lshl_b32 s16, s16, 2
	s_waitcnt lgkmcnt(2)
	v_fma_f32 v0, v0, v114, v168
	v_mul_f32_e32 v2, v2, v114
	s_add_i32 s16, s16, 0
	v_fma_f32 v0, v0, v115, v169
	v_mul_f32_e32 v2, v2, v115
	s_add_i32 s16, s16, 0x1d400
	s_waitcnt lgkmcnt(0)
	v_fma_f32 v0, v0, v170, v172
	v_mul_f32_e32 v2, v2, v170
	v_fma_f32 v0, v0, v171, v173
	v_mul_f32_e32 v2, v2, v171
	v_lshl_add_u32 v112, v120, 2, s16
	ds_write2st64_b32 v112, v2, v0 offset1:8
	s_waitcnt lgkmcnt(0)
	s_barrier
	v_lshl_add_u32 v0, v121, 2, s16
	ds_read2st64_b32 v[112:113], v0 offset1:1
	ds_read2st64_b32 v[174:175], v0 offset0:8 offset1:9
	s_waitcnt lgkmcnt(0)
	v_fma_f32 v2, v3, v112, v174
	v_cndmask_b32_e64 v3, v3, v2, s[0:1]
	v_fmac_f32_e32 v175, v2, v113
	v_cndmask_b32_e64 v174, v3, v175, s[2:3]
	ds_read2st64_b32 v[2:3], v0 offset0:2 offset1:3
	ds_read2st64_b32 v[112:113], v0 offset0:10 offset1:11
	s_waitcnt lgkmcnt(0)
	v_fma_f32 v2, v175, v2, v112
	v_cndmask_b32_e64 v112, v174, v2, s[4:5]
	v_fmac_f32_e32 v113, v2, v3
	ds_read2st64_b32 v[2:3], v0 offset0:4 offset1:5
	ds_read2st64_b32 v[174:175], v0 offset0:12 offset1:13
	v_cndmask_b32_e64 v112, v112, v113, s[8:9]
	s_waitcnt lgkmcnt(0)
	v_fma_f32 v2, v113, v2, v174
	v_cndmask_b32_e64 v112, v112, v2, s[10:11]
	v_fmac_f32_e32 v175, v2, v3
	v_cndmask_b32_e64 v174, v112, v175, s[12:13]
	ds_read2st64_b32 v[112:113], v0 offset0:6 offset1:7
	ds_read2st64_b32 v[2:3], v0 offset0:14 offset1:15
	s_waitcnt lgkmcnt(0)
	v_fma_f32 v0, v175, v112, v2
	v_cndmask_b32_e64 v2, v174, v0, s[14:15]
	v_fma_f32 v2, v88, v2, v90
	v_fmac_f32_e32 v91, v89, v2
	ds_write2st64_b32 v176, v2, v91 offset0:42 offset1:43
	v_fma_f32 v2, v94, v91, v92
	v_fmac_f32_e32 v93, v95, v2
	ds_write2st64_b32 v176, v2, v93 offset0:44 offset1:45
	v_fma_f32 v2, v98, v93, v96
	v_fmac_f32_e32 v97, v99, v2
	ds_write2st64_b32 v176, v2, v97 offset0:46 offset1:47
	v_fma_f32 v2, v100, v97, v102
	v_fmac_f32_e32 v103, v101, v2
	ds_write2st64_b32 v176, v2, v103 offset0:48 offset1:49
	v_fma_f32 v2, v104, v103, v106
	v_fmac_f32_e32 v107, v105, v2
	ds_write2st64_b32 v176, v2, v107 offset0:50 offset1:51
	v_fma_f32 v2, v110, v107, v108
	v_fmac_f32_e32 v109, v111, v2
	ds_write2st64_b32 v176, v2, v109 offset0:52 offset1:53
	v_fma_f32 v2, v114, v109, v168
	v_fmac_f32_e32 v169, v115, v2
	ds_write2st64_b32 v176, v2, v169 offset0:54 offset1:55
	v_fma_f32 v2, v170, v169, v172
	v_fmac_f32_e32 v173, v171, v2
	ds_write2st64_b32 v176, v2, v173 offset0:56 offset1:57
	s_waitcnt lgkmcnt(0)
	v_add_u32_e32 v2, s19, v158
	v_cmp_gt_i32_e64 s[16:17], s86, v2
	s_waitcnt vmcnt(0)
	s_and_saveexec_b64 s[76:77], s[16:17]
	s_cbranch_execz .LBB0_595
	ds_read_b128 v[88:91], v125 offset:10880
	ds_read_b128 v[92:95], v125 offset:10896
	ds_read_b128 v[96:99], v125 offset:10912
	ds_read_b128 v[100:103], v125 offset:10928
	s_waitcnt lgkmcnt(3)
	v_cvt_pk_bf16_f32 v88, v88, v89
	v_cvt_pk_bf16_f32 v89, v90, v91
	s_waitcnt lgkmcnt(2)
	v_cvt_pk_bf16_f32 v90, v92, v93
	v_cvt_pk_bf16_f32 v91, v94, v95
	s_waitcnt lgkmcnt(1)
	v_cvt_pk_bf16_f32 v92, v96, v97
	v_cvt_pk_bf16_f32 v93, v98, v99
	s_waitcnt lgkmcnt(0)
	v_cvt_pk_bf16_f32 v94, v100, v101
	v_cvt_pk_bf16_f32 v95, v102, v103
	global_store_dwordx4 v[118:119], v[88:91], off
	global_store_dwordx4 v[118:119], v[92:95], off offset:16
	s_branch .LBB0_595

; template <class Epi, class Sched, bool ALIGN_EPI>
; __device__ __forceinline__ void gemm_phase(PG8_LAS unsigned char* lds, const Gemm g, const Sched& S, const Epi& E) {
;     ...
;     for (;;) {
;         const bool has_next = S.next(ui + 1, nxt);
;         const char* nA = has_next ? (const char*)g.A + (size_t)nxt.pm * tsA : cA; const char* nB = has_next ? (const char*)g.Bt + (size_t)nxt.pn * tsB : cB;
;     ...
; #pragma unroll
;         for (int a = 0; a < 2; ++a)
; #pragma unroll
;             for (int b = 0; b < 2; ++b)
; #pragma unroll
;                 for (int m = 0; m < 4; ++m)
; #pragma unroll
;                     for (int n = 0; n < 2; ++n) acc[a][b][m][n] = (f32x4){0.f, 0.f, 0.f, 0.f};
;         cur = nxt; cA = nA; cB = nB; ++ui;
.LBB0_939:
	s_ashr_i32 s31, s30, 31
	s_lshl_b64 s[34:35], s[30:31], 19
	s_add_u32 s34, s6, s34
	s_addc_u32 s35, s7, s35
	s_and_b64 s[36:37], s[0:1], exec
	s_cselect_b32 s31, s35, s43
	s_cselect_b32 s60, s34, s42
	s_ashr_i32 s17, s16, 31
	s_lshl_b64 s[36:37], s[16:17], 19
	s_add_u32 s36, s19, s36
	s_addc_u32 s37, s33, s37
	s_and_b64 s[62:63], s[0:1], exec
	s_cselect_b32 s17, s37, s41
	s_cselect_b32 s61, s36, s40
	v_lshl_add_u32 v157, s38, 8, v144
	s_add_u32 s38, s42, 0x40080
	s_addc_u32 s39, s43, 0
	s_add_u32 s62, s40, 0x100
	v_mov_b32_e32 v0, 0
	s_addc_u32 s63, s41, 0
	s_mov_b32 s64, -2
	v_mov_b32_e32 v1, v0
	v_mov_b32_e32 v2, v0
	v_mov_b32_e32 v3, v0
	v_mov_b32_e32 v8, v0
	v_mov_b32_e32 v9, v0
	v_mov_b32_e32 v10, v0
	v_mov_b32_e32 v11, v0
	v_mov_b32_e32 v16, v0
	v_mov_b32_e32 v17, v0
	v_mov_b32_e32 v18, v0
	v_mov_b32_e32 v19, v0
	v_mov_b32_e32 v24, v0
	v_mov_b32_e32 v25, v0
	v_mov_b32_e32 v26, v0
	v_mov_b32_e32 v27, v0
	v_mov_b32_e32 v32, v0
	v_mov_b32_e32 v33, v0
	v_mov_b32_e32 v34, v0
	v_mov_b32_e32 v35, v0
	v_mov_b32_e32 v40, v0
	v_mov_b32_e32 v41, v0
	v_mov_b32_e32 v42, v0
	v_mov_b32_e32 v43, v0
	v_mov_b32_e32 v48, v0
	v_mov_b32_e32 v49, v0
	v_mov_b32_e32 v50, v0
	v_mov_b32_e32 v51, v0
	v_mov_b32_e32 v56, v0
	v_mov_b32_e32 v57, v0
	v_mov_b32_e32 v58, v0
	v_mov_b32_e32 v59, v0
	v_mov_b32_e32 v4, v0
	v_mov_b32_e32 v5, v0
	v_mov_b32_e32 v6, v0
	v_mov_b32_e32 v7, v0
	v_mov_b32_e32 v12, v0
	v_mov_b32_e32 v13, v0
	v_mov_b32_e32 v14, v0
	v_mov_b32_e32 v15, v0
	v_mov_b32_e32 v20, v0
	v_mov_b32_e32 v21, v0
	v_mov_b32_e32 v22, v0
	v_mov_b32_e32 v23, v0
	v_mov_b32_e32 v28, v0
	v_mov_b32_e32 v29, v0
	v_mov_b32_e32 v30, v0
	v_mov_b32_e32 v31, v0
	v_mov_b32_e32 v36, v0
	v_mov_b32_e32 v37, v0
	v_mov_b32_e32 v38, v0
	v_mov_b32_e32 v39, v0
	v_mov_b32_e32 v44, v0
	v_mov_b32_e32 v45, v0
	v_mov_b32_e32 v46, v0
	v_mov_b32_e32 v47, v0
	v_mov_b32_e32 v52, v0
	v_mov_b32_e32 v53, v0
	v_mov_b32_e32 v54, v0
	v_mov_b32_e32 v55, v0
	v_mov_b32_e32 v60, v0
	v_mov_b32_e32 v61, v0
	v_mov_b32_e32 v62, v0
	v_mov_b32_e32 v63, v0
	v_mov_b32_e32 v64, v0
	v_mov_b32_e32 v65, v0
	v_mov_b32_e32 v66, v0
	v_mov_b32_e32 v67, v0
	v_mov_b32_e32 v72, v0
	v_mov_b32_e32 v73, v0
	v_mov_b32_e32 v74, v0
	v_mov_b32_e32 v75, v0
	s_waitcnt vmcnt(16)
	v_mov_b32_e32 v80, v0
	v_mov_b32_e32 v81, v0
	v_mov_b32_e32 v82, v0
	v_mov_b32_e32 v83, v0
	v_mov_b32_e32 v88, v0
	v_mov_b32_e32 v89, v0
	v_mov_b32_e32 v90, v0
	v_mov_b32_e32 v91, v0
	v_mov_b32_e32 v96, v0
	v_mov_b32_e32 v97, v0
	v_mov_b32_e32 v98, v0
	v_mov_b32_e32 v99, v0
	v_mov_b32_e32 v104, v0
	v_mov_b32_e32 v105, v0
	v_mov_b32_e32 v106, v0
	v_mov_b32_e32 v107, v0
	v_mov_b32_e32 v112, v0
	v_mov_b32_e32 v113, v0
	v_mov_b32_e32 v114, v0
	v_mov_b32_e32 v115, v0
	v_mov_b32_e32 v120, v0
	v_mov_b32_e32 v121, v0
	v_mov_b32_e32 v122, v0
	v_mov_b32_e32 v123, v0
	v_mov_b32_e32 v68, v0
	v_mov_b32_e32 v69, v0
	v_mov_b32_e32 v70, v0
	v_mov_b32_e32 v71, v0
	v_mov_b32_e32 v76, v0
	v_mov_b32_e32 v77, v0
	v_mov_b32_e32 v78, v0
	v_mov_b32_e32 v79, v0
	v_mov_b32_e32 v84, v0
	v_mov_b32_e32 v85, v0
	v_mov_b32_e32 v86, v0
	v_mov_b32_e32 v87, v0
	v_mov_b32_e32 v92, v0
	v_mov_b32_e32 v93, v0
	v_mov_b32_e32 v94, v0
	v_mov_b32_e32 v95, v0
	v_mov_b32_e32 v100, v0
	v_mov_b32_e32 v101, v0
	v_mov_b32_e32 v102, v0
	v_mov_b32_e32 v103, v0
	v_mov_b32_e32 v108, v0
	v_mov_b32_e32 v109, v0
	v_mov_b32_e32 v110, v0
	v_mov_b32_e32 v111, v0
	v_mov_b32_e32 v116, v0
	v_mov_b32_e32 v117, v0
	v_mov_b32_e32 v118, v0
	v_mov_b32_e32 v119, v0
	v_mov_b32_e32 v124, v0
	v_mov_b32_e32 v125, v0
	v_mov_b32_e32 v126, v0
	v_mov_b32_e32 v127, v0
	s_branch .LBB0_941

;     __device__ __forceinline__ void mid(f32x4 (&)[2][2][4][2], const Unit& u, int wr, int fr) const {
;         int row0 = u.pm * BM + wr * 64 + fr; asm volatile("" : "+v"(row0));
; #pragma unroll
;         for (int ai = 0; ai < 2; ++ai)
; #pragma unroll
;             for (int m = 0; m < 4; ++m) pre[ai * 4 + m] = ss2[row0 + ai * HALF + m * 16];
;     }
.LBB0_941:
	s_cmp_eq_u32 s64, 12
	s_cselect_b64 s[40:41], -1, 0
	s_cmp_lg_u32 s64, 12
	s_cbranch_scc1 .LBB0_940
	s_waitcnt vmcnt(8)
	v_mov_b32_e32 v150, v157
	s_nop 0
	v_ashrrev_i32_e32 v151, 31, v150
	v_lshl_add_u64 v[158:159], v[150:151], 2, s[10:11]
	global_load_dword v156, v[158:159], off
	global_load_dword v155, v[158:159], off offset:64
	global_load_dword v154, v[158:159], off offset:128
	global_load_dword v153, v[158:159], off offset:192
	global_load_dword v152, v[158:159], off offset:512
	global_load_dword v151, v[158:159], off offset:576
	global_load_dword v150, v[158:159], off offset:640
	global_load_dword v149, v[158:159], off offset:704
	s_branch .LBB0_940

; __device__ __forceinline__ unsigned cvt_pk(float lo, float hi) { unsigned r; asm("v_cvt_pk_bf16_f32 %0, %1, %2" : "=v"(r) : "v"(lo), "v"(hi)); return r; }
; __device__ __forceinline__ float frsq(float x) { return __builtin_amdgcn_rsqf(x); }
;     __device__ __forceinline__ void operator()(const f32x4 (&acc)[2][2][4][2], const Unit& u, int wr, int wc, int fr, int fq) const {
;         int row0 = u.pm * BM + wr * 64 + fr; asm volatile("" : "+v"(row0)); const int col = u.pn * HALF + wc * 32 + 8 * fq;
; #pragma unroll
;         for (int ai = 0; ai < 2; ++ai)
; #pragma unroll
;             for (int m = 0; m < 4; ++m) { const int row = row0 + ai * HALF + m * 16; const float s = frsq(pre[ai * 4 + m] * (1.0f / 1024.0f) + EPS);
;                 const float c = -1.4426950408889634f * s, s2 = s * s;
;                 f32x4 r[2];
; #pragma unroll
;                 for (int n = 0; n < 2; ++n) { const f32x4 g = acc[ai][0][m][n], uu = acc[ai][1][m][n];
;                     f32x4 e = g * c;
; #pragma unroll
;                     for (int i = 0; i < 4; ++i) e[i] = __builtin_amdgcn_exp2f(e[i]);
;                     f32x4 d = e + 1.0f;
; #pragma unroll
;                     for (int i = 0; i < 4; ++i) d[i] = __builtin_amdgcn_rcpf(d[i]);
;                     r[n] = (g * uu) * (d * s2); }
;                 u32x4 w; w.x = cvt_pk(r[0][0], r[0][1]); w.y = cvt_pk(r[0][2], r[0][3]); w.z = cvt_pk(r[1][0], r[1][1]); w.w = cvt_pk(r[1][2], r[1][3]);
;                 *(u32x4*)(ACT + (size_t)row * DFF + col) = w; }
.LBB0_945:
	s_waitcnt vmcnt(8)
	v_fmamk_f32 v158, v156, 0x3a800000, v148
	v_rsq_f32_e32 v161, v158
	v_pk_mul_f32 v[122:123], v[126:127], v[122:123]
	v_pk_mul_f32 v[120:121], v[124:125], v[120:121]
	v_pk_mul_f32 v[114:115], v[118:119], v[114:115]
	v_mul_f32_e32 v160, 0xbfb8aa3b, v161
	v_pk_mul_f32 v[164:165], v[160:161], v[126:127] op_sel_hi:[0,1]
	v_exp_f32_e32 v164, v164
	v_exp_f32_e32 v165, v165
	v_pk_mul_f32 v[166:167], v[160:161], v[124:125] op_sel_hi:[0,1]
	v_exp_f32_e32 v166, v166
	v_exp_f32_e32 v167, v167
	v_pk_add_f32 v[164:165], v[164:165], 1.0 op_sel_hi:[1,0]
	v_mul_f32_e32 v162, v161, v161
	v_rcp_f32_e32 v164, v164
	v_rcp_f32_e32 v165, v165
	v_pk_add_f32 v[166:167], v[166:167], 1.0 op_sel_hi:[1,0]
	v_pk_mul_f32 v[112:113], v[116:117], v[112:113]
	v_rcp_f32_e32 v166, v166
	v_rcp_f32_e32 v167, v167
	v_pk_mul_f32 v[126:127], v[162:163], v[164:165] op_sel_hi:[0,1]
	v_pk_mul_f32 v[164:165], v[160:161], v[118:119] op_sel_hi:[0,1]
	v_exp_f32_e32 v164, v164
	v_exp_f32_e32 v165, v165
	v_pk_mul_f32 v[160:161], v[160:161], v[116:117] op_sel_hi:[0,1]
	v_exp_f32_e32 v160, v160
	v_exp_f32_e32 v161, v161
	v_pk_mul_f32 v[124:125], v[162:163], v[166:167] op_sel_hi:[0,1]
	v_pk_mul_f32 v[120:121], v[124:125], v[120:121]
	v_pk_add_f32 v[124:125], v[164:165], 1.0 op_sel_hi:[1,0]
	v_pk_mul_f32 v[122:123], v[126:127], v[122:123]
	v_rcp_f32_e32 v124, v124
	v_rcp_f32_e32 v125, v125
	v_pk_add_f32 v[126:127], v[160:161], 1.0 op_sel_hi:[1,0]
	v_lshl_or_b32 v158, s59, 7, v146
	v_rcp_f32_e32 v126, v126
	v_rcp_f32_e32 v127, v127
	v_pk_mul_f32 v[118:119], v[162:163], v[124:125] op_sel_hi:[0,1]
	v_pk_mul_f32 v[114:115], v[118:119], v[114:115]
	v_ashrrev_i32_e32 v159, 31, v158
	v_pk_mul_f32 v[116:117], v[162:163], v[126:127] op_sel_hi:[0,1]
	v_cvt_pk_bf16_f32 v119, v114, v115
	v_fmamk_f32 v114, v155, 0x3a800000, v148
	v_pk_mul_f32 v[112:113], v[116:117], v[112:113]
	v_cvt_pk_bf16_f32 v117, v122, v123
	v_rsq_f32_e32 v123, v114
	v_cvt_pk_bf16_f32 v118, v112, v113
	v_mov_b64_e32 v[112:113], s[8:9]
	v_mul_f32_e32 v122, 0xbfb8aa3b, v123
	v_pk_mul_f32 v[124:125], v[122:123], v[110:111] op_sel_hi:[0,1]
	v_pk_mul_f32 v[126:127], v[122:123], v[108:109] op_sel_hi:[0,1]
	v_exp_f32_e32 v126, v126
	v_exp_f32_e32 v124, v124
	v_exp_f32_e32 v125, v125
	v_exp_f32_e32 v127, v127
	v_cvt_pk_bf16_f32 v116, v120, v121
	v_mad_i64_i32 v[120:121], s[38:39], v157, s58, v[112:113]
	v_lshlrev_b64 v[114:115], 1, v[158:159]
	v_lshl_add_u64 v[120:121], v[120:121], 0, v[114:115]
	global_store_dwordx4 v[120:121], v[116:119], off
	v_pk_add_f32 v[120:121], v[126:127], 1.0 op_sel_hi:[1,0]
	v_pk_mul_f32 v[106:107], v[110:111], v[106:107]
	v_pk_add_f32 v[118:119], v[124:125], 1.0 op_sel_hi:[1,0]
	v_rcp_f32_e32 v120, v120
	v_rcp_f32_e32 v121, v121
	v_rcp_f32_e32 v118, v118
	v_rcp_f32_e32 v119, v119
	v_mul_f32_e32 v116, v123, v123
	v_pk_mul_f32 v[104:105], v[108:109], v[104:105]
	v_pk_mul_f32 v[108:109], v[116:117], v[120:121] op_sel_hi:[0,1]
	v_pk_mul_f32 v[110:111], v[116:117], v[118:119] op_sel_hi:[0,1]
	v_pk_mul_f32 v[118:119], v[122:123], v[102:103] op_sel_hi:[0,1]
	v_pk_mul_f32 v[120:121], v[122:123], v[100:101] op_sel_hi:[0,1]
	v_exp_f32_e32 v120, v120
	v_exp_f32_e32 v118, v118
	v_exp_f32_e32 v119, v119
	v_exp_f32_e32 v121, v121
	v_pk_mul_f32 v[106:107], v[110:111], v[106:107]
	v_pk_mul_f32 v[104:105], v[108:109], v[104:105]
	v_pk_add_f32 v[108:109], v[118:119], 1.0 op_sel_hi:[1,0]
	v_pk_add_f32 v[110:111], v[120:121], 1.0 op_sel_hi:[1,0]
	v_rcp_f32_e32 v108, v108
	v_rcp_f32_e32 v110, v110
	v_rcp_f32_e32 v111, v111
	v_rcp_f32_e32 v109, v109
	v_pk_mul_f32 v[98:99], v[102:103], v[98:99]
	v_pk_mul_f32 v[96:97], v[100:101], v[96:97]
	v_pk_mul_f32 v[100:101], v[116:117], v[110:111] op_sel_hi:[0,1]
	v_pk_mul_f32 v[102:103], v[116:117], v[108:109] op_sel_hi:[0,1]
	v_pk_mul_f32 v[102:103], v[102:103], v[98:99]
	v_pk_mul_f32 v[98:99], v[100:101], v[96:97]
	v_fmamk_f32 v101, v154, 0x3a800000, v148
	v_cvt_pk_bf16_f32 v98, v98, v99
	v_cvt_pk_bf16_f32 v99, v102, v103
	v_rsq_f32_e32 v103, v101
	v_cvt_pk_bf16_f32 v96, v104, v105
	v_cvt_pk_bf16_f32 v97, v106, v107
	v_add_u32_e32 v100, 16, v157
	v_mul_f32_e32 v102, 0xbfb8aa3b, v103
	v_pk_mul_f32 v[104:105], v[102:103], v[94:95] op_sel_hi:[0,1]
	v_pk_mul_f32 v[106:107], v[102:103], v[92:93] op_sel_hi:[0,1]
	v_exp_f32_e32 v106, v106
	v_exp_f32_e32 v104, v104
	v_exp_f32_e32 v105, v105
	v_exp_f32_e32 v107, v107
	v_mad_i64_i32 v[100:101], s[38:39], v100, s58, v[112:113]
	v_lshl_add_u64 v[100:101], v[100:101], 0, v[114:115]
	global_store_dwordx4 v[100:101], v[96:99], off
	v_pk_add_f32 v[100:101], v[106:107], 1.0 op_sel_hi:[1,0]
	v_pk_mul_f32 v[90:91], v[94:95], v[90:91]
	v_pk_add_f32 v[98:99], v[104:105], 1.0 op_sel_hi:[1,0]
	v_rcp_f32_e32 v100, v100
	v_rcp_f32_e32 v101, v101
	v_rcp_f32_e32 v98, v98
	v_rcp_f32_e32 v99, v99
	v_mul_f32_e32 v96, v103, v103
	v_pk_mul_f32 v[88:89], v[92:93], v[88:89]
	v_pk_mul_f32 v[92:93], v[96:97], v[100:101] op_sel_hi:[0,1]
	v_pk_mul_f32 v[94:95], v[96:97], v[98:99] op_sel_hi:[0,1]
	v_pk_mul_f32 v[98:99], v[102:103], v[86:87] op_sel_hi:[0,1]
	v_pk_mul_f32 v[100:101], v[102:103], v[84:85] op_sel_hi:[0,1]
	v_exp_f32_e32 v100, v100
	v_exp_f32_e32 v98, v98
	v_exp_f32_e32 v99, v99
	v_exp_f32_e32 v101, v101
	v_pk_mul_f32 v[90:91], v[94:95], v[90:91]
	v_pk_mul_f32 v[88:89], v[92:93], v[88:89]
	v_pk_add_f32 v[92:93], v[98:99], 1.0 op_sel_hi:[1,0]
	v_pk_add_f32 v[94:95], v[100:101], 1.0 op_sel_hi:[1,0]
	v_rcp_f32_e32 v92, v92
	v_rcp_f32_e32 v94, v94
	v_rcp_f32_e32 v95, v95
	v_rcp_f32_e32 v93, v93
	v_pk_mul_f32 v[82:83], v[86:87], v[82:83]
	v_pk_mul_f32 v[80:81], v[84:85], v[80:81]
	v_pk_mul_f32 v[84:85], v[96:97], v[94:95] op_sel_hi:[0,1]
; __device__ __forceinline__ unsigned cvt_pk(float lo, float hi) { unsigned r; asm("v_cvt_pk_bf16_f32 %0, %1, %2" : "=v"(r) : "v"(lo), "v"(hi)); return r; }
; __device__ __forceinline__ float frsq(float x) { return __builtin_amdgcn_rsqf(x); }
;     __device__ __forceinline__ void operator()(const f32x4 (&acc)[2][2][4][2], const Unit& u, int wr, int wc, int fr, int fq) const {
;     ...
;             for (int m = 0; m < 4; ++m) { const int row = row0 + ai * HALF + m * 16; const float s = frsq(pre[ai * 4 + m] * (1.0f / 1024.0f) + EPS);
;                 const float c = -1.4426950408889634f * s, s2 = s * s;
;                 f32x4 r[2];
; #pragma unroll
;                 for (int n = 0; n < 2; ++n) { const f32x4 g = acc[ai][0][m][n], uu = acc[ai][1][m][n];
;                     f32x4 e = g * c;
; #pragma unroll
;                     for (int i = 0; i < 4; ++i) e[i] = __builtin_amdgcn_exp2f(e[i]);
;                     f32x4 d = e + 1.0f;
; #pragma unroll
;                     for (int i = 0; i < 4; ++i) d[i] = __builtin_amdgcn_rcpf(d[i]);
;                     r[n] = (g * uu) * (d * s2); }
;                 u32x4 w; w.x = cvt_pk(r[0][0], r[0][1]); w.y = cvt_pk(r[0][2], r[0][3]); w.z = cvt_pk(r[1][0], r[1][1]); w.w = cvt_pk(r[1][2], r[1][3]);
;                 *(u32x4*)(ACT + (size_t)row * DFF + col) = w; }
	v_pk_mul_f32 v[86:87], v[96:97], v[92:93] op_sel_hi:[0,1]
	v_pk_mul_f32 v[86:87], v[86:87], v[82:83]
	v_pk_mul_f32 v[82:83], v[84:85], v[80:81]
	v_fmamk_f32 v85, v153, 0x3a800000, v148
	v_cvt_pk_bf16_f32 v82, v82, v83
	v_cvt_pk_bf16_f32 v83, v86, v87
	v_rsq_f32_e32 v87, v85
	v_cvt_pk_bf16_f32 v80, v88, v89
	v_cvt_pk_bf16_f32 v81, v90, v91
	v_add_u32_e32 v84, 32, v157
	v_mul_f32_e32 v86, 0xbfb8aa3b, v87
	v_pk_mul_f32 v[88:89], v[86:87], v[78:79] op_sel_hi:[0,1]
	v_pk_mul_f32 v[90:91], v[86:87], v[76:77] op_sel_hi:[0,1]
	v_exp_f32_e32 v90, v90
	v_exp_f32_e32 v88, v88
	v_exp_f32_e32 v89, v89
	v_exp_f32_e32 v91, v91
	v_mad_i64_i32 v[84:85], s[38:39], v84, s58, v[112:113]
	v_lshl_add_u64 v[84:85], v[84:85], 0, v[114:115]
	global_store_dwordx4 v[84:85], v[80:83], off
	v_pk_add_f32 v[84:85], v[90:91], 1.0 op_sel_hi:[1,0]
	v_pk_mul_f32 v[74:75], v[78:79], v[74:75]
	v_pk_add_f32 v[82:83], v[88:89], 1.0 op_sel_hi:[1,0]
	v_rcp_f32_e32 v84, v84
	v_rcp_f32_e32 v85, v85
	v_rcp_f32_e32 v82, v82
	v_rcp_f32_e32 v83, v83
	v_mul_f32_e32 v80, v87, v87
	v_pk_mul_f32 v[72:73], v[76:77], v[72:73]
	v_pk_mul_f32 v[76:77], v[80:81], v[84:85] op_sel_hi:[0,1]
	v_pk_mul_f32 v[78:79], v[80:81], v[82:83] op_sel_hi:[0,1]
	v_pk_mul_f32 v[82:83], v[86:87], v[70:71] op_sel_hi:[0,1]
	v_pk_mul_f32 v[84:85], v[86:87], v[68:69] op_sel_hi:[0,1]
	v_exp_f32_e32 v84, v84
	v_exp_f32_e32 v82, v82
	v_exp_f32_e32 v83, v83
	v_exp_f32_e32 v85, v85
	v_pk_mul_f32 v[74:75], v[78:79], v[74:75]
	v_pk_mul_f32 v[72:73], v[76:77], v[72:73]
	v_pk_add_f32 v[76:77], v[82:83], 1.0 op_sel_hi:[1,0]
	v_pk_add_f32 v[78:79], v[84:85], 1.0 op_sel_hi:[1,0]
	v_rcp_f32_e32 v76, v76
	v_rcp_f32_e32 v78, v78
	v_rcp_f32_e32 v79, v79
	v_rcp_f32_e32 v77, v77
	v_pk_mul_f32 v[66:67], v[70:71], v[66:67]
	v_pk_mul_f32 v[64:65], v[68:69], v[64:65]
	v_pk_mul_f32 v[68:69], v[80:81], v[78:79] op_sel_hi:[0,1]
	v_pk_mul_f32 v[70:71], v[80:81], v[76:77] op_sel_hi:[0,1]
	v_pk_mul_f32 v[70:71], v[70:71], v[66:67]
	v_pk_mul_f32 v[66:67], v[68:69], v[64:65]
	v_fmamk_f32 v69, v152, 0x3a800000, v148
	v_cvt_pk_bf16_f32 v66, v66, v67
	v_cvt_pk_bf16_f32 v67, v70, v71
	v_rsq_f32_e32 v70, v69
	v_add_u32_e32 v68, 48, v157
	v_mad_i64_i32 v[68:69], s[38:39], v68, s58, v[112:113]
	v_cvt_pk_bf16_f32 v64, v72, v73
	v_lshl_add_u64 v[68:69], v[68:69], 0, v[114:115]
	v_cvt_pk_bf16_f32 v65, v74, v75
	global_store_dwordx4 v[68:69], v[64:67], off
	v_add_u32_e32 v71, 0x80, v157
	v_pk_mul_f32 v[58:59], v[62:63], v[58:59]
	v_mul_f32_e32 v64, 0xbfb8aa3b, v70
	v_pk_mul_f32 v[66:67], v[64:65], v[62:63] op_sel_hi:[0,1]
	v_exp_f32_e32 v66, v66
	v_exp_f32_e32 v67, v67
	v_pk_mul_f32 v[68:69], v[64:65], v[60:61] op_sel_hi:[0,1]
	v_exp_f32_e32 v68, v68
	v_exp_f32_e32 v69, v69
	v_pk_add_f32 v[66:67], v[66:67], 1.0 op_sel_hi:[1,0]
	v_mul_f32_e32 v70, v70, v70
	v_rcp_f32_e32 v66, v66
	v_rcp_f32_e32 v67, v67
	v_pk_add_f32 v[68:69], v[68:69], 1.0 op_sel_hi:[1,0]
	v_pk_mul_f32 v[56:57], v[60:61], v[56:57]
	v_rcp_f32_e32 v68, v68
	v_rcp_f32_e32 v69, v69
	v_pk_mul_f32 v[62:63], v[70:71], v[66:67] op_sel_hi:[0,1]
	v_pk_mul_f32 v[66:67], v[64:65], v[54:55] op_sel_hi:[0,1]
	v_pk_mul_f32 v[64:65], v[64:65], v[52:53] op_sel_hi:[0,1]
	v_exp_f32_e32 v64, v64
	v_exp_f32_e32 v66, v66
	v_exp_f32_e32 v67, v67
	v_exp_f32_e32 v65, v65
	v_pk_mul_f32 v[60:61], v[70:71], v[68:69] op_sel_hi:[0,1]
	v_pk_mul_f32 v[58:59], v[62:63], v[58:59]
	v_pk_mul_f32 v[56:57], v[60:61], v[56:57]
	v_pk_add_f32 v[60:61], v[66:67], 1.0 op_sel_hi:[1,0]
	v_pk_add_f32 v[62:63], v[64:65], 1.0 op_sel_hi:[1,0]
	v_rcp_f32_e32 v60, v60
	v_rcp_f32_e32 v62, v62
	v_rcp_f32_e32 v63, v63
	v_rcp_f32_e32 v61, v61
	v_pk_mul_f32 v[50:51], v[54:55], v[50:51]
	v_pk_mul_f32 v[48:49], v[52:53], v[48:49]
	v_pk_mul_f32 v[52:53], v[70:71], v[62:63] op_sel_hi:[0,1]
	v_pk_mul_f32 v[54:55], v[70:71], v[60:61] op_sel_hi:[0,1]
	v_pk_mul_f32 v[54:55], v[54:55], v[50:51]
	v_pk_mul_f32 v[50:51], v[52:53], v[48:49]
	v_fmamk_f32 v52, v151, 0x3a800000, v148
	v_cvt_pk_bf16_f32 v50, v50, v51
	v_cvt_pk_bf16_f32 v51, v54, v55
	v_rsq_f32_e32 v55, v52
	v_cvt_pk_bf16_f32 v48, v56, v57
	v_cvt_pk_bf16_f32 v49, v58, v59
	v_mad_i64_i32 v[52:53], s[38:39], v71, s58, v[112:113]
	v_mul_f32_e32 v54, 0xbfb8aa3b, v55
	v_pk_mul_f32 v[56:57], v[54:55], v[46:47] op_sel_hi:[0,1]
	v_pk_mul_f32 v[58:59], v[54:55], v[44:45] op_sel_hi:[0,1]
	v_exp_f32_e32 v58, v58
	v_exp_f32_e32 v56, v56
	v_exp_f32_e32 v57, v57
	v_exp_f32_e32 v59, v59
	v_lshl_add_u64 v[52:53], v[52:53], 0, v[114:115]
	global_store_dwordx4 v[52:53], v[48:51], off
	v_pk_mul_f32 v[42:43], v[46:47], v[42:43]
	v_pk_add_f32 v[52:53], v[58:59], 1.0 op_sel_hi:[1,0]
	v_pk_add_f32 v[50:51], v[56:57], 1.0 op_sel_hi:[1,0]
	v_rcp_f32_e32 v52, v52
	v_rcp_f32_e32 v53, v53
	v_rcp_f32_e32 v50, v50
	v_rcp_f32_e32 v51, v51
	v_mul_f32_e32 v48, v55, v55
	v_pk_mul_f32 v[40:41], v[44:45], v[40:41]
	v_pk_mul_f32 v[44:45], v[48:49], v[52:53] op_sel_hi:[0,1]
	v_pk_mul_f32 v[46:47], v[48:49], v[50:51] op_sel_hi:[0,1]
; __device__ __forceinline__ unsigned cvt_pk(float lo, float hi) { unsigned r; asm("v_cvt_pk_bf16_f32 %0, %1, %2" : "=v"(r) : "v"(lo), "v"(hi)); return r; }
; __device__ __forceinline__ float frsq(float x) { return __builtin_amdgcn_rsqf(x); }
;     __device__ __forceinline__ void operator()(const f32x4 (&acc)[2][2][4][2], const Unit& u, int wr, int wc, int fr, int fq) const {
;     ...
;             for (int m = 0; m < 4; ++m) { const int row = row0 + ai * HALF + m * 16; const float s = frsq(pre[ai * 4 + m] * (1.0f / 1024.0f) + EPS);
;                 const float c = -1.4426950408889634f * s, s2 = s * s;
;                 f32x4 r[2];
; #pragma unroll
;                 for (int n = 0; n < 2; ++n) { const f32x4 g = acc[ai][0][m][n], uu = acc[ai][1][m][n];
;                     f32x4 e = g * c;
; #pragma unroll
;                     for (int i = 0; i < 4; ++i) e[i] = __builtin_amdgcn_exp2f(e[i]);
;                     f32x4 d = e + 1.0f;
; #pragma unroll
;                     for (int i = 0; i < 4; ++i) d[i] = __builtin_amdgcn_rcpf(d[i]);
;                     r[n] = (g * uu) * (d * s2); }
;                 u32x4 w; w.x = cvt_pk(r[0][0], r[0][1]); w.y = cvt_pk(r[0][2], r[0][3]); w.z = cvt_pk(r[1][0], r[1][1]); w.w = cvt_pk(r[1][2], r[1][3]);
;                 *(u32x4*)(ACT + (size_t)row * DFF + col) = w; }
	v_pk_mul_f32 v[50:51], v[54:55], v[38:39] op_sel_hi:[0,1]
	v_pk_mul_f32 v[52:53], v[54:55], v[36:37] op_sel_hi:[0,1]
	v_exp_f32_e32 v52, v52
	v_exp_f32_e32 v50, v50
	v_exp_f32_e32 v51, v51
	v_exp_f32_e32 v53, v53
	v_pk_mul_f32 v[42:43], v[46:47], v[42:43]
	v_pk_mul_f32 v[40:41], v[44:45], v[40:41]
	v_pk_add_f32 v[44:45], v[50:51], 1.0 op_sel_hi:[1,0]
	v_pk_add_f32 v[46:47], v[52:53], 1.0 op_sel_hi:[1,0]
	v_rcp_f32_e32 v44, v44
	v_rcp_f32_e32 v46, v46
	v_rcp_f32_e32 v47, v47
	v_rcp_f32_e32 v45, v45
	v_pk_mul_f32 v[34:35], v[38:39], v[34:35]
	v_pk_mul_f32 v[32:33], v[36:37], v[32:33]
	v_pk_mul_f32 v[36:37], v[48:49], v[46:47] op_sel_hi:[0,1]
	v_pk_mul_f32 v[38:39], v[48:49], v[44:45] op_sel_hi:[0,1]
	v_pk_mul_f32 v[38:39], v[38:39], v[34:35]
	v_pk_mul_f32 v[34:35], v[36:37], v[32:33]
	v_fmamk_f32 v37, v150, 0x3a800000, v148
	v_cvt_pk_bf16_f32 v34, v34, v35
	v_cvt_pk_bf16_f32 v35, v38, v39
	v_rsq_f32_e32 v39, v37
	v_cvt_pk_bf16_f32 v32, v40, v41
	v_cvt_pk_bf16_f32 v33, v42, v43
	v_add_u32_e32 v36, 0x90, v157
	v_mul_f32_e32 v38, 0xbfb8aa3b, v39
	v_pk_mul_f32 v[40:41], v[38:39], v[30:31] op_sel_hi:[0,1]
	v_pk_mul_f32 v[42:43], v[38:39], v[28:29] op_sel_hi:[0,1]
	v_exp_f32_e32 v42, v42
	v_exp_f32_e32 v40, v40
	v_exp_f32_e32 v41, v41
	v_exp_f32_e32 v43, v43
	v_mad_i64_i32 v[36:37], s[38:39], v36, s58, v[112:113]
	v_lshl_add_u64 v[36:37], v[36:37], 0, v[114:115]
	global_store_dwordx4 v[36:37], v[32:35], off
	v_pk_add_f32 v[36:37], v[42:43], 1.0 op_sel_hi:[1,0]
	v_pk_mul_f32 v[26:27], v[30:31], v[26:27]
	v_pk_add_f32 v[34:35], v[40:41], 1.0 op_sel_hi:[1,0]
	v_rcp_f32_e32 v36, v36
	v_rcp_f32_e32 v37, v37
	v_rcp_f32_e32 v34, v34
	v_rcp_f32_e32 v35, v35
	v_mul_f32_e32 v32, v39, v39
	v_pk_mul_f32 v[24:25], v[28:29], v[24:25]
	v_pk_mul_f32 v[28:29], v[32:33], v[36:37] op_sel_hi:[0,1]
	v_pk_mul_f32 v[30:31], v[32:33], v[34:35] op_sel_hi:[0,1]
	v_pk_mul_f32 v[34:35], v[38:39], v[22:23] op_sel_hi:[0,1]
	v_pk_mul_f32 v[36:37], v[38:39], v[20:21] op_sel_hi:[0,1]
	v_exp_f32_e32 v36, v36
	v_exp_f32_e32 v34, v34
	v_exp_f32_e32 v35, v35
	v_exp_f32_e32 v37, v37
	v_pk_mul_f32 v[26:27], v[30:31], v[26:27]
	v_pk_mul_f32 v[24:25], v[28:29], v[24:25]
	v_pk_add_f32 v[28:29], v[34:35], 1.0 op_sel_hi:[1,0]
	v_pk_add_f32 v[30:31], v[36:37], 1.0 op_sel_hi:[1,0]
	v_rcp_f32_e32 v28, v28
	v_rcp_f32_e32 v30, v30
	v_rcp_f32_e32 v31, v31
	v_rcp_f32_e32 v29, v29
	v_pk_mul_f32 v[18:19], v[22:23], v[18:19]
	v_pk_mul_f32 v[16:17], v[20:21], v[16:17]
	v_pk_mul_f32 v[20:21], v[32:33], v[30:31] op_sel_hi:[0,1]
	v_pk_mul_f32 v[22:23], v[32:33], v[28:29] op_sel_hi:[0,1]
	v_pk_mul_f32 v[22:23], v[22:23], v[18:19]
	v_pk_mul_f32 v[18:19], v[20:21], v[16:17]
	v_fmamk_f32 v21, v149, 0x3a800000, v148
	v_cvt_pk_bf16_f32 v18, v18, v19
	v_cvt_pk_bf16_f32 v19, v22, v23
	v_rsq_f32_e32 v23, v21
	v_cvt_pk_bf16_f32 v16, v24, v25
	v_cvt_pk_bf16_f32 v17, v26, v27
	v_add_u32_e32 v20, 0xa0, v157
	v_mul_f32_e32 v22, 0xbfb8aa3b, v23
	v_pk_mul_f32 v[24:25], v[22:23], v[14:15] op_sel_hi:[0,1]
	v_pk_mul_f32 v[26:27], v[22:23], v[12:13] op_sel_hi:[0,1]
	v_exp_f32_e32 v26, v26
	v_exp_f32_e32 v24, v24
	v_exp_f32_e32 v25, v25
	v_exp_f32_e32 v27, v27
	v_mad_i64_i32 v[20:21], s[38:39], v20, s58, v[112:113]
	v_lshl_add_u64 v[20:21], v[20:21], 0, v[114:115]
	global_store_dwordx4 v[20:21], v[16:19], off
	v_pk_add_f32 v[20:21], v[26:27], 1.0 op_sel_hi:[1,0]
	v_pk_mul_f32 v[10:11], v[14:15], v[10:11]
	v_pk_add_f32 v[18:19], v[24:25], 1.0 op_sel_hi:[1,0]
	v_rcp_f32_e32 v20, v20
	v_rcp_f32_e32 v21, v21
	v_rcp_f32_e32 v18, v18
	v_rcp_f32_e32 v19, v19
	v_mul_f32_e32 v16, v23, v23
	v_pk_mul_f32 v[8:9], v[12:13], v[8:9]
	v_pk_mul_f32 v[12:13], v[16:17], v[20:21] op_sel_hi:[0,1]
	v_pk_mul_f32 v[14:15], v[16:17], v[18:19] op_sel_hi:[0,1]
	v_pk_mul_f32 v[18:19], v[22:23], v[6:7] op_sel_hi:[0,1]
	v_pk_mul_f32 v[20:21], v[22:23], v[4:5] op_sel_hi:[0,1]
	v_exp_f32_e32 v20, v20
	v_exp_f32_e32 v18, v18
	v_exp_f32_e32 v19, v19
	v_exp_f32_e32 v21, v21
	v_pk_mul_f32 v[10:11], v[14:15], v[10:11]
	v_pk_mul_f32 v[8:9], v[12:13], v[8:9]
	v_pk_add_f32 v[12:13], v[18:19], 1.0 op_sel_hi:[1,0]
	v_pk_add_f32 v[14:15], v[20:21], 1.0 op_sel_hi:[1,0]
	v_rcp_f32_e32 v12, v12
	v_rcp_f32_e32 v14, v14
	v_rcp_f32_e32 v15, v15
	v_rcp_f32_e32 v13, v13
	v_pk_mul_f32 v[2:3], v[6:7], v[2:3]
	v_pk_mul_f32 v[0:1], v[4:5], v[0:1]
	v_pk_mul_f32 v[4:5], v[16:17], v[14:15] op_sel_hi:[0,1]
	v_pk_mul_f32 v[6:7], v[16:17], v[12:13] op_sel_hi:[0,1]
	v_pk_mul_f32 v[6:7], v[6:7], v[2:3]
	v_pk_mul_f32 v[2:3], v[4:5], v[0:1]
	v_add_u32_e32 v4, 0xb0, v157
	v_mad_i64_i32 v[4:5], s[38:39], v4, s58, v[112:113]
	v_lshl_add_u64 v[4:5], v[4:5], 0, v[114:115]
	s_andn2_b64 vcc, exec, s[0:1]
	s_mov_b64 s[0:1], -1
	v_cvt_pk_bf16_f32 v0, v8, v9
	v_cvt_pk_bf16_f32 v1, v10, v11
	v_cvt_pk_bf16_f32 v2, v2, v3
	v_cvt_pk_bf16_f32 v3, v6, v7
	global_store_dwordx4 v[4:5], v[0:3], off
	s_cbranch_vccnz .LBB0_936
	s_andn2_b64 vcc, exec, s[4:5]
	s_cbranch_vccnz .LBB0_935
	s_barrier
	s_branch .LBB0_935

; __device__ __forceinline__ float bflo(unsigned w) { return __uint_as_float(w << 16); }
; __device__ __forceinline__ float bfhi(unsigned w) { return __uint_as_float(w & 0xffff0000u); }
;     __device__ __forceinline__ void operator()(const f32x4 (&acc)[2][2][4][2], const Unit& u, int wr, int wc, int fr, int fq) const {
;         int row0 = u.pm * BM + wr * 64 + fr; asm volatile("" : "+v"(row0));
; #pragma unroll
;         for (int ai = 0; ai < 2; ++ai)
; #pragma unroll
;             for (int m = 0; m < 4; ++m) { const int row = row0 + ai * HALF + m * 16;
; #pragma unroll
;                 for (int bj = 0; bj < 2; ++bj) { const size_t off = (size_t)row * DM + u.pn * BM + bj * HALF + wc * 32 + 8 * fq;
;                     const u32x4 hw = *(const u32x4*)(H1B + off), lw = *(const u32x4*)(LO + off);
;                     f32x4 o0, o1;
;                     o0[0] = (bflo(hw.x) + bflo(lw.x)) + acc[ai][bj][m][0][0]; o0[1] = (bfhi(hw.x) + bfhi(lw.x)) + acc[ai][bj][m][0][1];
;                     o0[2] = (bflo(hw.y) + bflo(lw.y)) + acc[ai][bj][m][0][2]; o0[3] = (bfhi(hw.y) + bfhi(lw.y)) + acc[ai][bj][m][0][3];
;                     o1[0] = (bflo(hw.z) + bflo(lw.z)) + acc[ai][bj][m][1][0]; o1[1] = (bfhi(hw.z) + bfhi(lw.z)) + acc[ai][bj][m][1][1];
;                     o1[2] = (bflo(hw.w) + bflo(lw.w)) + acc[ai][bj][m][1][2]; o1[3] = (bfhi(hw.w) + bfhi(lw.w)) + acc[ai][bj][m][1][3];
;                     *(f32x4*)(out + off) = o0; *(f32x4*)(out + off + 4) = o1; } }
.LBB0_1028:
	v_lshl_add_u32 v146, s59, 8, v137
	s_lshl_b32 s38, s60, 8
	v_or_b32_e32 v147, s38, v136
	v_lshl_add_u32 v146, v146, 10, v147
	v_lshlrev_b32_e32 v147, 2, v146
	v_lshlrev_b32_e32 v146, 1, v146
	s_mov_b64 s[98:99], s[6:7]
	s_mov_b64 s[100:101], s[8:9]
	global_load_dwordx4 v[152:155], v146, s[98:99]
	global_load_dwordx4 v[156:159], v146, s[100:101]
	global_load_dwordx4 v[160:163], v146, s[98:99] offset:256
	global_load_dwordx4 v[164:167], v146, s[100:101] offset:256
	s_add_u32 s98, s6, 0x8000
	s_addc_u32 s99, s7, 0
	s_add_u32 s100, s8, 0x8000
	s_addc_u32 s101, s9, 0
	global_load_dwordx4 v[168:171], v146, s[98:99]
	global_load_dwordx4 v[172:175], v146, s[100:101]
	global_load_dwordx4 v[176:179], v146, s[98:99] offset:256
	global_load_dwordx4 v[180:183], v146, s[100:101] offset:256
	s_add_u32 s98, s6, 0x10000
	s_addc_u32 s99, s7, 0
	s_add_u32 s100, s8, 0x10000
	s_addc_u32 s101, s9, 0
	global_load_dwordx4 v[184:187], v146, s[98:99]
	global_load_dwordx4 v[188:191], v146, s[100:101]
	global_load_dwordx4 v[192:195], v146, s[98:99] offset:256
	global_load_dwordx4 v[196:199], v146, s[100:101] offset:256
	s_add_u32 s98, s6, 0x18000
	s_addc_u32 s99, s7, 0
	s_add_u32 s100, s8, 0x18000
	s_addc_u32 s101, s9, 0
	global_load_dwordx4 v[200:203], v146, s[98:99]
	global_load_dwordx4 v[204:207], v146, s[100:101]
	global_load_dwordx4 v[208:211], v146, s[98:99] offset:256
	global_load_dwordx4 v[212:215], v146, s[100:101] offset:256
	s_add_u32 s98, s6, 0x40000
	s_addc_u32 s99, s7, 0
	s_add_u32 s100, s8, 0x40000
	s_addc_u32 s101, s9, 0
	global_load_dwordx4 v[216:219], v146, s[98:99]
	global_load_dwordx4 v[220:223], v146, s[100:101]
	global_load_dwordx4 v[224:227], v146, s[98:99] offset:256
	global_load_dwordx4 v[228:231], v146, s[100:101] offset:256
	s_waitcnt vmcnt(18)
	v_lshlrev_b32_e32 v232, 16, v152
	v_and_b32_e32 v233, 0xffff0000, v152
	v_lshlrev_b32_e32 v234, 16, v156
	v_and_b32_e32 v235, 0xffff0000, v156
	v_pk_add_f32 v[232:233], v[232:233], v[234:235]
	v_pk_add_f32 v[124:125], v[124:125], v[232:233]
	v_lshlrev_b32_e32 v236, 16, v153
	v_and_b32_e32 v237, 0xffff0000, v153
	v_lshlrev_b32_e32 v238, 16, v157
	v_and_b32_e32 v239, 0xffff0000, v157
	v_pk_add_f32 v[236:237], v[236:237], v[238:239]
	v_pk_add_f32 v[126:127], v[126:127], v[236:237]
	v_lshlrev_b32_e32 v240, 16, v154
	v_and_b32_e32 v241, 0xffff0000, v154
	v_lshlrev_b32_e32 v242, 16, v158
	v_and_b32_e32 v243, 0xffff0000, v158
	v_pk_add_f32 v[240:241], v[240:241], v[242:243]
	v_pk_add_f32 v[120:121], v[120:121], v[240:241]
	v_lshlrev_b32_e32 v232, 16, v155
	v_and_b32_e32 v233, 0xffff0000, v155
	v_lshlrev_b32_e32 v234, 16, v159
	v_and_b32_e32 v235, 0xffff0000, v159
	v_pk_add_f32 v[232:233], v[232:233], v[234:235]
	v_pk_add_f32 v[122:123], v[122:123], v[232:233]
	s_mov_b64 s[14:15], s[20:21]
	global_store_dwordx4 v147, v[124:127], s[14:15]
	global_store_dwordx4 v147, v[120:123], s[14:15] offset:16
	s_add_u32 s98, s6, 0x48000
	s_addc_u32 s99, s7, 0
	s_add_u32 s100, s8, 0x48000
	s_addc_u32 s101, s9, 0
	global_load_dwordx4 v[152:155], v146, s[98:99]
	global_load_dwordx4 v[156:159], v146, s[100:101]
	s_waitcnt vmcnt(20)
	v_lshlrev_b32_e32 v232, 16, v160
	v_and_b32_e32 v233, 0xffff0000, v160
	v_lshlrev_b32_e32 v234, 16, v164
	v_and_b32_e32 v235, 0xffff0000, v164
	v_pk_add_f32 v[232:233], v[232:233], v[234:235]
	v_pk_add_f32 v[116:117], v[116:117], v[232:233]
	v_lshlrev_b32_e32 v236, 16, v161
	v_and_b32_e32 v237, 0xffff0000, v161
	v_lshlrev_b32_e32 v238, 16, v165
	v_and_b32_e32 v239, 0xffff0000, v165
	v_pk_add_f32 v[236:237], v[236:237], v[238:239]
	v_pk_add_f32 v[118:119], v[118:119], v[236:237]
	v_lshlrev_b32_e32 v240, 16, v162
	v_and_b32_e32 v241, 0xffff0000, v162
	v_lshlrev_b32_e32 v242, 16, v166
	v_and_b32_e32 v243, 0xffff0000, v166
	v_pk_add_f32 v[240:241], v[240:241], v[242:243]
	v_pk_add_f32 v[112:113], v[112:113], v[240:241]
	v_lshlrev_b32_e32 v232, 16, v163
	v_and_b32_e32 v233, 0xffff0000, v163
	v_lshlrev_b32_e32 v234, 16, v167
	v_and_b32_e32 v235, 0xffff0000, v167
	v_pk_add_f32 v[232:233], v[232:233], v[234:235]
	v_pk_add_f32 v[114:115], v[114:115], v[232:233]
	global_store_dwordx4 v147, v[116:119], s[14:15] offset:512
	global_store_dwordx4 v147, v[112:115], s[14:15] offset:528
	global_load_dwordx4 v[160:163], v146, s[98:99] offset:256
	global_load_dwordx4 v[164:167], v146, s[100:101] offset:256
	s_waitcnt vmcnt(22)
	v_lshlrev_b32_e32 v232, 16, v168
	v_and_b32_e32 v233, 0xffff0000, v168
	v_lshlrev_b32_e32 v234, 16, v172
	v_and_b32_e32 v235, 0xffff0000, v172
	v_pk_add_f32 v[232:233], v[232:233], v[234:235]
	v_pk_add_f32 v[108:109], v[108:109], v[232:233]
	v_lshlrev_b32_e32 v236, 16, v169
	v_and_b32_e32 v237, 0xffff0000, v169
	v_lshlrev_b32_e32 v238, 16, v173
	v_and_b32_e32 v239, 0xffff0000, v173
	v_pk_add_f32 v[236:237], v[236:237], v[238:239]
	v_pk_add_f32 v[110:111], v[110:111], v[236:237]
	v_lshlrev_b32_e32 v240, 16, v170
	v_and_b32_e32 v241, 0xffff0000, v170
	v_lshlrev_b32_e32 v242, 16, v174
	v_and_b32_e32 v243, 0xffff0000, v174
	v_pk_add_f32 v[240:241], v[240:241], v[242:243]
	v_pk_add_f32 v[104:105], v[104:105], v[240:241]
	v_lshlrev_b32_e32 v232, 16, v171
	v_and_b32_e32 v233, 0xffff0000, v171
	v_lshlrev_b32_e32 v234, 16, v175
	v_and_b32_e32 v235, 0xffff0000, v175
	v_pk_add_f32 v[232:233], v[232:233], v[234:235]
	v_pk_add_f32 v[106:107], v[106:107], v[232:233]
	s_add_u32 s14, s20, 0x10000
	s_addc_u32 s15, s21, 0
	global_store_dwordx4 v147, v[108:111], s[14:15]
	global_store_dwordx4 v147, v[104:107], s[14:15] offset:16
	s_add_u32 s98, s6, 0x50000
	s_addc_u32 s99, s7, 0
	s_add_u32 s100, s8, 0x50000
	s_addc_u32 s101, s9, 0
	global_load_dwordx4 v[168:171], v146, s[98:99]
	global_load_dwordx4 v[172:175], v146, s[100:101]
	s_waitcnt vmcnt(24)
; __device__ __forceinline__ float bflo(unsigned w) { return __uint_as_float(w << 16); }
; __device__ __forceinline__ float bfhi(unsigned w) { return __uint_as_float(w & 0xffff0000u); }
;     __device__ __forceinline__ void operator()(const f32x4 (&acc)[2][2][4][2], const Unit& u, int wr, int wc, int fr, int fq) const {
;         int row0 = u.pm * BM + wr * 64 + fr; asm volatile("" : "+v"(row0));
; #pragma unroll
;         for (int ai = 0; ai < 2; ++ai)
; #pragma unroll
;             for (int m = 0; m < 4; ++m) { const int row = row0 + ai * HALF + m * 16;
; #pragma unroll
;                 for (int bj = 0; bj < 2; ++bj) { const size_t off = (size_t)row * DM + u.pn * BM + bj * HALF + wc * 32 + 8 * fq;
;                     const u32x4 hw = *(const u32x4*)(H1B + off), lw = *(const u32x4*)(LO + off);
;                     f32x4 o0, o1;
;                     o0[0] = (bflo(hw.x) + bflo(lw.x)) + acc[ai][bj][m][0][0]; o0[1] = (bfhi(hw.x) + bfhi(lw.x)) + acc[ai][bj][m][0][1];
;                     o0[2] = (bflo(hw.y) + bflo(lw.y)) + acc[ai][bj][m][0][2]; o0[3] = (bfhi(hw.y) + bfhi(lw.y)) + acc[ai][bj][m][0][3];
;                     o1[0] = (bflo(hw.z) + bflo(lw.z)) + acc[ai][bj][m][1][0]; o1[1] = (bfhi(hw.z) + bfhi(lw.z)) + acc[ai][bj][m][1][1];
;                     o1[2] = (bflo(hw.w) + bflo(lw.w)) + acc[ai][bj][m][1][2]; o1[3] = (bfhi(hw.w) + bfhi(lw.w)) + acc[ai][bj][m][1][3];
;                     *(f32x4*)(out + off) = o0; *(f32x4*)(out + off + 4) = o1; } }
	v_lshlrev_b32_e32 v232, 16, v176
	v_and_b32_e32 v233, 0xffff0000, v176
	v_lshlrev_b32_e32 v234, 16, v180
	v_and_b32_e32 v235, 0xffff0000, v180
	v_pk_add_f32 v[232:233], v[232:233], v[234:235]
	v_pk_add_f32 v[100:101], v[100:101], v[232:233]
	v_lshlrev_b32_e32 v236, 16, v177
	v_and_b32_e32 v237, 0xffff0000, v177
	v_lshlrev_b32_e32 v238, 16, v181
	v_and_b32_e32 v239, 0xffff0000, v181
	v_pk_add_f32 v[236:237], v[236:237], v[238:239]
	v_pk_add_f32 v[102:103], v[102:103], v[236:237]
	v_lshlrev_b32_e32 v240, 16, v178
	v_and_b32_e32 v241, 0xffff0000, v178
	v_lshlrev_b32_e32 v242, 16, v182
	v_and_b32_e32 v243, 0xffff0000, v182
	v_pk_add_f32 v[240:241], v[240:241], v[242:243]
	v_pk_add_f32 v[96:97], v[96:97], v[240:241]
	v_lshlrev_b32_e32 v232, 16, v179
	v_and_b32_e32 v233, 0xffff0000, v179
	v_lshlrev_b32_e32 v234, 16, v183
	v_and_b32_e32 v235, 0xffff0000, v183
	v_pk_add_f32 v[232:233], v[232:233], v[234:235]
	v_pk_add_f32 v[98:99], v[98:99], v[232:233]
	global_store_dwordx4 v147, v[100:103], s[14:15] offset:512
	global_store_dwordx4 v147, v[96:99], s[14:15] offset:528
	global_load_dwordx4 v[176:179], v146, s[98:99] offset:256
	global_load_dwordx4 v[180:183], v146, s[100:101] offset:256
	s_waitcnt vmcnt(26)
	v_lshlrev_b32_e32 v232, 16, v184
	v_and_b32_e32 v233, 0xffff0000, v184
	v_lshlrev_b32_e32 v234, 16, v188
	v_and_b32_e32 v235, 0xffff0000, v188
	v_pk_add_f32 v[232:233], v[232:233], v[234:235]
	v_pk_add_f32 v[92:93], v[92:93], v[232:233]
	v_lshlrev_b32_e32 v236, 16, v185
	v_and_b32_e32 v237, 0xffff0000, v185
	v_lshlrev_b32_e32 v238, 16, v189
	v_and_b32_e32 v239, 0xffff0000, v189
	v_pk_add_f32 v[236:237], v[236:237], v[238:239]
	v_pk_add_f32 v[94:95], v[94:95], v[236:237]
	v_lshlrev_b32_e32 v240, 16, v186
	v_and_b32_e32 v241, 0xffff0000, v186
	v_lshlrev_b32_e32 v242, 16, v190
	v_and_b32_e32 v243, 0xffff0000, v190
	v_pk_add_f32 v[240:241], v[240:241], v[242:243]
	v_pk_add_f32 v[88:89], v[88:89], v[240:241]
	v_lshlrev_b32_e32 v232, 16, v187
	v_and_b32_e32 v233, 0xffff0000, v187
	v_lshlrev_b32_e32 v234, 16, v191
	v_and_b32_e32 v235, 0xffff0000, v191
	v_pk_add_f32 v[232:233], v[232:233], v[234:235]
	v_pk_add_f32 v[90:91], v[90:91], v[232:233]
	s_add_u32 s14, s20, 0x20000
	s_addc_u32 s15, s21, 0
	global_store_dwordx4 v147, v[92:95], s[14:15]
	global_store_dwordx4 v147, v[88:91], s[14:15] offset:16
	s_add_u32 s98, s6, 0x58000
	s_addc_u32 s99, s7, 0
	s_add_u32 s100, s8, 0x58000
	s_addc_u32 s101, s9, 0
	global_load_dwordx4 v[184:187], v146, s[98:99]
	global_load_dwordx4 v[188:191], v146, s[100:101]
	s_waitcnt vmcnt(28)
	v_lshlrev_b32_e32 v232, 16, v192
	v_and_b32_e32 v233, 0xffff0000, v192
	v_lshlrev_b32_e32 v234, 16, v196
	v_and_b32_e32 v235, 0xffff0000, v196
	v_pk_add_f32 v[232:233], v[232:233], v[234:235]
	v_pk_add_f32 v[84:85], v[84:85], v[232:233]
	v_lshlrev_b32_e32 v236, 16, v193
	v_and_b32_e32 v237, 0xffff0000, v193
	v_lshlrev_b32_e32 v238, 16, v197
	v_and_b32_e32 v239, 0xffff0000, v197
	v_pk_add_f32 v[236:237], v[236:237], v[238:239]
	v_pk_add_f32 v[86:87], v[86:87], v[236:237]
	v_lshlrev_b32_e32 v240, 16, v194
	v_and_b32_e32 v241, 0xffff0000, v194
	v_lshlrev_b32_e32 v242, 16, v198
	v_and_b32_e32 v243, 0xffff0000, v198
	v_pk_add_f32 v[240:241], v[240:241], v[242:243]
	v_pk_add_f32 v[80:81], v[80:81], v[240:241]
	v_lshlrev_b32_e32 v232, 16, v195
	v_and_b32_e32 v233, 0xffff0000, v195
	v_lshlrev_b32_e32 v234, 16, v199
	v_and_b32_e32 v235, 0xffff0000, v199
	v_pk_add_f32 v[232:233], v[232:233], v[234:235]
	v_pk_add_f32 v[82:83], v[82:83], v[232:233]
	global_store_dwordx4 v147, v[84:87], s[14:15] offset:512
	global_store_dwordx4 v147, v[80:83], s[14:15] offset:528
	global_load_dwordx4 v[192:195], v146, s[98:99] offset:256
	global_load_dwordx4 v[196:199], v146, s[100:101] offset:256
	s_waitcnt vmcnt(30)
	v_lshlrev_b32_e32 v232, 16, v200
	v_and_b32_e32 v233, 0xffff0000, v200
	v_lshlrev_b32_e32 v234, 16, v204
	v_and_b32_e32 v235, 0xffff0000, v204
	v_pk_add_f32 v[232:233], v[232:233], v[234:235]
	v_pk_add_f32 v[76:77], v[76:77], v[232:233]
	v_lshlrev_b32_e32 v236, 16, v201
	v_and_b32_e32 v237, 0xffff0000, v201
	v_lshlrev_b32_e32 v238, 16, v205
	v_and_b32_e32 v239, 0xffff0000, v205
	v_pk_add_f32 v[236:237], v[236:237], v[238:239]
	v_pk_add_f32 v[78:79], v[78:79], v[236:237]
	v_lshlrev_b32_e32 v240, 16, v202
	v_and_b32_e32 v241, 0xffff0000, v202
	v_lshlrev_b32_e32 v242, 16, v206
	v_and_b32_e32 v243, 0xffff0000, v206
	v_pk_add_f32 v[240:241], v[240:241], v[242:243]
	v_pk_add_f32 v[72:73], v[72:73], v[240:241]
	v_lshlrev_b32_e32 v232, 16, v203
	v_and_b32_e32 v233, 0xffff0000, v203
	v_lshlrev_b32_e32 v234, 16, v207
	v_and_b32_e32 v235, 0xffff0000, v207
	v_pk_add_f32 v[232:233], v[232:233], v[234:235]
	v_pk_add_f32 v[74:75], v[74:75], v[232:233]
	s_add_u32 s14, s20, 0x30000
	s_addc_u32 s15, s21, 0
	global_store_dwordx4 v147, v[76:79], s[14:15]
	global_store_dwordx4 v147, v[72:75], s[14:15] offset:16
	s_waitcnt vmcnt(30)
	v_lshlrev_b32_e32 v232, 16, v208
	v_and_b32_e32 v233, 0xffff0000, v208
	v_lshlrev_b32_e32 v234, 16, v212
	v_and_b32_e32 v235, 0xffff0000, v212
	v_pk_add_f32 v[232:233], v[232:233], v[234:235]
	v_pk_add_f32 v[68:69], v[68:69], v[232:233]
	v_lshlrev_b32_e32 v236, 16, v209
	v_and_b32_e32 v237, 0xffff0000, v209
	v_lshlrev_b32_e32 v238, 16, v213
	v_and_b32_e32 v239, 0xffff0000, v213
	v_pk_add_f32 v[236:237], v[236:237], v[238:239]
	v_pk_add_f32 v[70:71], v[70:71], v[236:237]
	v_lshlrev_b32_e32 v240, 16, v210
	v_and_b32_e32 v241, 0xffff0000, v210
	v_lshlrev_b32_e32 v242, 16, v214
	v_and_b32_e32 v243, 0xffff0000, v214
	v_pk_add_f32 v[240:241], v[240:241], v[242:243]
	v_pk_add_f32 v[64:65], v[64:65], v[240:241]
	v_lshlrev_b32_e32 v232, 16, v211
	v_and_b32_e32 v233, 0xffff0000, v211
	v_lshlrev_b32_e32 v234, 16, v215
	v_and_b32_e32 v235, 0xffff0000, v215
	v_pk_add_f32 v[232:233], v[232:233], v[234:235]
	v_pk_add_f32 v[66:67], v[66:67], v[232:233]
	global_store_dwordx4 v147, v[68:71], s[14:15] offset:512
	global_store_dwordx4 v147, v[64:67], s[14:15] offset:528
	s_waitcnt vmcnt(30)
; __device__ __forceinline__ float bflo(unsigned w) { return __uint_as_float(w << 16); }
; __device__ __forceinline__ float bfhi(unsigned w) { return __uint_as_float(w & 0xffff0000u); }
;     __device__ __forceinline__ void operator()(const f32x4 (&acc)[2][2][4][2], const Unit& u, int wr, int wc, int fr, int fq) const {
;         int row0 = u.pm * BM + wr * 64 + fr; asm volatile("" : "+v"(row0));
; #pragma unroll
;         for (int ai = 0; ai < 2; ++ai)
; #pragma unroll
;             for (int m = 0; m < 4; ++m) { const int row = row0 + ai * HALF + m * 16;
; #pragma unroll
;                 for (int bj = 0; bj < 2; ++bj) { const size_t off = (size_t)row * DM + u.pn * BM + bj * HALF + wc * 32 + 8 * fq;
;                     const u32x4 hw = *(const u32x4*)(H1B + off), lw = *(const u32x4*)(LO + off);
;                     f32x4 o0, o1;
;                     o0[0] = (bflo(hw.x) + bflo(lw.x)) + acc[ai][bj][m][0][0]; o0[1] = (bfhi(hw.x) + bfhi(lw.x)) + acc[ai][bj][m][0][1];
;                     o0[2] = (bflo(hw.y) + bflo(lw.y)) + acc[ai][bj][m][0][2]; o0[3] = (bfhi(hw.y) + bfhi(lw.y)) + acc[ai][bj][m][0][3];
;                     o1[0] = (bflo(hw.z) + bflo(lw.z)) + acc[ai][bj][m][1][0]; o1[1] = (bfhi(hw.z) + bfhi(lw.z)) + acc[ai][bj][m][1][1];
;                     o1[2] = (bflo(hw.w) + bflo(lw.w)) + acc[ai][bj][m][1][2]; o1[3] = (bfhi(hw.w) + bfhi(lw.w)) + acc[ai][bj][m][1][3];
;                     *(f32x4*)(out + off) = o0; *(f32x4*)(out + off + 4) = o1; } }
	v_lshlrev_b32_e32 v232, 16, v216
	v_and_b32_e32 v233, 0xffff0000, v216
	v_lshlrev_b32_e32 v234, 16, v220
	v_and_b32_e32 v235, 0xffff0000, v220
	v_pk_add_f32 v[232:233], v[232:233], v[234:235]
	v_pk_add_f32 v[60:61], v[60:61], v[232:233]
	v_lshlrev_b32_e32 v236, 16, v217
	v_and_b32_e32 v237, 0xffff0000, v217
	v_lshlrev_b32_e32 v238, 16, v221
	v_and_b32_e32 v239, 0xffff0000, v221
	v_pk_add_f32 v[236:237], v[236:237], v[238:239]
	v_pk_add_f32 v[62:63], v[62:63], v[236:237]
	v_lshlrev_b32_e32 v240, 16, v218
	v_and_b32_e32 v241, 0xffff0000, v218
	v_lshlrev_b32_e32 v242, 16, v222
	v_and_b32_e32 v243, 0xffff0000, v222
	v_pk_add_f32 v[240:241], v[240:241], v[242:243]
	v_pk_add_f32 v[56:57], v[56:57], v[240:241]
	v_lshlrev_b32_e32 v232, 16, v219
	v_and_b32_e32 v233, 0xffff0000, v219
	v_lshlrev_b32_e32 v234, 16, v223
	v_and_b32_e32 v235, 0xffff0000, v223
	v_pk_add_f32 v[232:233], v[232:233], v[234:235]
	v_pk_add_f32 v[58:59], v[58:59], v[232:233]
	s_add_u32 s14, s20, 0x80000
	s_addc_u32 s15, s21, 0
	global_store_dwordx4 v147, v[60:63], s[14:15]
	global_store_dwordx4 v147, v[56:59], s[14:15] offset:16
	s_waitcnt vmcnt(30)
	v_lshlrev_b32_e32 v232, 16, v224
	v_and_b32_e32 v233, 0xffff0000, v224
	v_lshlrev_b32_e32 v234, 16, v228
	v_and_b32_e32 v235, 0xffff0000, v228
	v_pk_add_f32 v[232:233], v[232:233], v[234:235]
	v_pk_add_f32 v[52:53], v[52:53], v[232:233]
	v_lshlrev_b32_e32 v236, 16, v225
	v_and_b32_e32 v237, 0xffff0000, v225
	v_lshlrev_b32_e32 v238, 16, v229
	v_and_b32_e32 v239, 0xffff0000, v229
	v_pk_add_f32 v[236:237], v[236:237], v[238:239]
	v_pk_add_f32 v[54:55], v[54:55], v[236:237]
	v_lshlrev_b32_e32 v240, 16, v226
	v_and_b32_e32 v241, 0xffff0000, v226
	v_lshlrev_b32_e32 v242, 16, v230
	v_and_b32_e32 v243, 0xffff0000, v230
	v_pk_add_f32 v[240:241], v[240:241], v[242:243]
	v_pk_add_f32 v[48:49], v[48:49], v[240:241]
	v_lshlrev_b32_e32 v232, 16, v227
	v_and_b32_e32 v233, 0xffff0000, v227
	v_lshlrev_b32_e32 v234, 16, v231
	v_and_b32_e32 v235, 0xffff0000, v231
	v_pk_add_f32 v[232:233], v[232:233], v[234:235]
	v_pk_add_f32 v[50:51], v[50:51], v[232:233]
	global_store_dwordx4 v147, v[52:55], s[14:15] offset:512
	global_store_dwordx4 v147, v[48:51], s[14:15] offset:528
	s_waitcnt vmcnt(28)
	v_lshlrev_b32_e32 v232, 16, v152
	v_and_b32_e32 v233, 0xffff0000, v152
	v_lshlrev_b32_e32 v234, 16, v156
	v_and_b32_e32 v235, 0xffff0000, v156
	v_pk_add_f32 v[232:233], v[232:233], v[234:235]
	v_pk_add_f32 v[44:45], v[44:45], v[232:233]
	v_lshlrev_b32_e32 v236, 16, v153
	v_and_b32_e32 v237, 0xffff0000, v153
	v_lshlrev_b32_e32 v238, 16, v157
	v_and_b32_e32 v239, 0xffff0000, v157
	v_pk_add_f32 v[236:237], v[236:237], v[238:239]
	v_pk_add_f32 v[46:47], v[46:47], v[236:237]
	v_lshlrev_b32_e32 v240, 16, v154
	v_and_b32_e32 v241, 0xffff0000, v154
	v_lshlrev_b32_e32 v242, 16, v158
	v_and_b32_e32 v243, 0xffff0000, v158
	v_pk_add_f32 v[240:241], v[240:241], v[242:243]
	v_pk_add_f32 v[40:41], v[40:41], v[240:241]
	v_lshlrev_b32_e32 v232, 16, v155
	v_and_b32_e32 v233, 0xffff0000, v155
	v_lshlrev_b32_e32 v234, 16, v159
	v_and_b32_e32 v235, 0xffff0000, v159
	v_pk_add_f32 v[232:233], v[232:233], v[234:235]
	v_pk_add_f32 v[42:43], v[42:43], v[232:233]
	s_add_u32 s14, s20, 0x90000
	s_addc_u32 s15, s21, 0
	global_store_dwordx4 v147, v[44:47], s[14:15]
	global_store_dwordx4 v147, v[40:43], s[14:15] offset:16
	s_waitcnt vmcnt(26)
	v_lshlrev_b32_e32 v232, 16, v160
	v_and_b32_e32 v233, 0xffff0000, v160
	v_lshlrev_b32_e32 v234, 16, v164
	v_and_b32_e32 v235, 0xffff0000, v164
	v_pk_add_f32 v[232:233], v[232:233], v[234:235]
	v_pk_add_f32 v[36:37], v[36:37], v[232:233]
	v_lshlrev_b32_e32 v236, 16, v161
	v_and_b32_e32 v237, 0xffff0000, v161
	v_lshlrev_b32_e32 v238, 16, v165
	v_and_b32_e32 v239, 0xffff0000, v165
	v_pk_add_f32 v[236:237], v[236:237], v[238:239]
	v_pk_add_f32 v[38:39], v[38:39], v[236:237]
	v_lshlrev_b32_e32 v240, 16, v162
	v_and_b32_e32 v241, 0xffff0000, v162
	v_lshlrev_b32_e32 v242, 16, v166
	v_and_b32_e32 v243, 0xffff0000, v166
	v_pk_add_f32 v[240:241], v[240:241], v[242:243]
	v_pk_add_f32 v[32:33], v[32:33], v[240:241]
	v_lshlrev_b32_e32 v232, 16, v163
	v_and_b32_e32 v233, 0xffff0000, v163
	v_lshlrev_b32_e32 v234, 16, v167
	v_and_b32_e32 v235, 0xffff0000, v167
	v_pk_add_f32 v[232:233], v[232:233], v[234:235]
	v_pk_add_f32 v[34:35], v[34:35], v[232:233]
	global_store_dwordx4 v147, v[36:39], s[14:15] offset:512
	global_store_dwordx4 v147, v[32:35], s[14:15] offset:528
	s_waitcnt vmcnt(24)
; __device__ __forceinline__ float bflo(unsigned w) { return __uint_as_float(w << 16); }
; __device__ __forceinline__ float bfhi(unsigned w) { return __uint_as_float(w & 0xffff0000u); }
;     __device__ __forceinline__ void operator()(const f32x4 (&acc)[2][2][4][2], const Unit& u, int wr, int wc, int fr, int fq) const {
;         int row0 = u.pm * BM + wr * 64 + fr; asm volatile("" : "+v"(row0));
; #pragma unroll
;         for (int ai = 0; ai < 2; ++ai)
; #pragma unroll
;             for (int m = 0; m < 4; ++m) { const int row = row0 + ai * HALF + m * 16;
; #pragma unroll
;                 for (int bj = 0; bj < 2; ++bj) { const size_t off = (size_t)row * DM + u.pn * BM + bj * HALF + wc * 32 + 8 * fq;
;                     const u32x4 hw = *(const u32x4*)(H1B + off), lw = *(const u32x4*)(LO + off);
;                     f32x4 o0, o1;
;                     o0[0] = (bflo(hw.x) + bflo(lw.x)) + acc[ai][bj][m][0][0]; o0[1] = (bfhi(hw.x) + bfhi(lw.x)) + acc[ai][bj][m][0][1];
;                     o0[2] = (bflo(hw.y) + bflo(lw.y)) + acc[ai][bj][m][0][2]; o0[3] = (bfhi(hw.y) + bfhi(lw.y)) + acc[ai][bj][m][0][3];
;                     o1[0] = (bflo(hw.z) + bflo(lw.z)) + acc[ai][bj][m][1][0]; o1[1] = (bfhi(hw.z) + bfhi(lw.z)) + acc[ai][bj][m][1][1];
;                     o1[2] = (bflo(hw.w) + bflo(lw.w)) + acc[ai][bj][m][1][2]; o1[3] = (bfhi(hw.w) + bfhi(lw.w)) + acc[ai][bj][m][1][3];
;                     *(f32x4*)(out + off) = o0; *(f32x4*)(out + off + 4) = o1; } }
	v_lshlrev_b32_e32 v232, 16, v168
	v_and_b32_e32 v233, 0xffff0000, v168
	v_lshlrev_b32_e32 v234, 16, v172
	v_and_b32_e32 v235, 0xffff0000, v172
	v_pk_add_f32 v[232:233], v[232:233], v[234:235]
	v_pk_add_f32 v[28:29], v[28:29], v[232:233]
	v_lshlrev_b32_e32 v236, 16, v169
	v_and_b32_e32 v237, 0xffff0000, v169
	v_lshlrev_b32_e32 v238, 16, v173
	v_and_b32_e32 v239, 0xffff0000, v173
	v_pk_add_f32 v[236:237], v[236:237], v[238:239]
	v_pk_add_f32 v[30:31], v[30:31], v[236:237]
	v_lshlrev_b32_e32 v240, 16, v170
	v_and_b32_e32 v241, 0xffff0000, v170
	v_lshlrev_b32_e32 v242, 16, v174
	v_and_b32_e32 v243, 0xffff0000, v174
	v_pk_add_f32 v[240:241], v[240:241], v[242:243]
	v_pk_add_f32 v[24:25], v[24:25], v[240:241]
	v_lshlrev_b32_e32 v232, 16, v171
	v_and_b32_e32 v233, 0xffff0000, v171
	v_lshlrev_b32_e32 v234, 16, v175
	v_and_b32_e32 v235, 0xffff0000, v175
	v_pk_add_f32 v[232:233], v[232:233], v[234:235]
	v_pk_add_f32 v[26:27], v[26:27], v[232:233]
	s_add_u32 s14, s20, 0xa0000
	s_addc_u32 s15, s21, 0
	global_store_dwordx4 v147, v[28:31], s[14:15]
	global_store_dwordx4 v147, v[24:27], s[14:15] offset:16
	s_waitcnt vmcnt(22)
	v_lshlrev_b32_e32 v232, 16, v176
	v_and_b32_e32 v233, 0xffff0000, v176
	v_lshlrev_b32_e32 v234, 16, v180
	v_and_b32_e32 v235, 0xffff0000, v180
	v_pk_add_f32 v[232:233], v[232:233], v[234:235]
	v_pk_add_f32 v[20:21], v[20:21], v[232:233]
	v_lshlrev_b32_e32 v236, 16, v177
	v_and_b32_e32 v237, 0xffff0000, v177
	v_lshlrev_b32_e32 v238, 16, v181
	v_and_b32_e32 v239, 0xffff0000, v181
	v_pk_add_f32 v[236:237], v[236:237], v[238:239]
	v_pk_add_f32 v[22:23], v[22:23], v[236:237]
	v_lshlrev_b32_e32 v240, 16, v178
	v_and_b32_e32 v241, 0xffff0000, v178
	v_lshlrev_b32_e32 v242, 16, v182
	v_and_b32_e32 v243, 0xffff0000, v182
	v_pk_add_f32 v[240:241], v[240:241], v[242:243]
	v_pk_add_f32 v[16:17], v[16:17], v[240:241]
	v_lshlrev_b32_e32 v232, 16, v179
	v_and_b32_e32 v233, 0xffff0000, v179
	v_lshlrev_b32_e32 v234, 16, v183
	v_and_b32_e32 v235, 0xffff0000, v183
	v_pk_add_f32 v[232:233], v[232:233], v[234:235]
	v_pk_add_f32 v[18:19], v[18:19], v[232:233]
	global_store_dwordx4 v147, v[20:23], s[14:15] offset:512
	global_store_dwordx4 v147, v[16:19], s[14:15] offset:528
	s_waitcnt vmcnt(20)
	v_lshlrev_b32_e32 v232, 16, v184
	v_and_b32_e32 v233, 0xffff0000, v184
	v_lshlrev_b32_e32 v234, 16, v188
	v_and_b32_e32 v235, 0xffff0000, v188
	v_pk_add_f32 v[232:233], v[232:233], v[234:235]
	v_pk_add_f32 v[12:13], v[12:13], v[232:233]
	v_lshlrev_b32_e32 v236, 16, v185
	v_and_b32_e32 v237, 0xffff0000, v185
	v_lshlrev_b32_e32 v238, 16, v189
	v_and_b32_e32 v239, 0xffff0000, v189
	v_pk_add_f32 v[236:237], v[236:237], v[238:239]
	v_pk_add_f32 v[14:15], v[14:15], v[236:237]
	v_lshlrev_b32_e32 v240, 16, v186
	v_and_b32_e32 v241, 0xffff0000, v186
	v_lshlrev_b32_e32 v242, 16, v190
	v_and_b32_e32 v243, 0xffff0000, v190
	v_pk_add_f32 v[240:241], v[240:241], v[242:243]
	v_pk_add_f32 v[8:9], v[8:9], v[240:241]
	v_lshlrev_b32_e32 v232, 16, v187
	v_and_b32_e32 v233, 0xffff0000, v187
	v_lshlrev_b32_e32 v234, 16, v191
	v_and_b32_e32 v235, 0xffff0000, v191
	v_pk_add_f32 v[232:233], v[232:233], v[234:235]
	v_pk_add_f32 v[10:11], v[10:11], v[232:233]
	s_add_u32 s14, s20, 0xb0000
	s_addc_u32 s15, s21, 0
	global_store_dwordx4 v147, v[12:15], s[14:15]
	global_store_dwordx4 v147, v[8:11], s[14:15] offset:16
	s_waitcnt vmcnt(18)
	v_lshlrev_b32_e32 v232, 16, v192
	v_and_b32_e32 v233, 0xffff0000, v192
	v_lshlrev_b32_e32 v234, 16, v196
	v_and_b32_e32 v235, 0xffff0000, v196
	v_pk_add_f32 v[232:233], v[232:233], v[234:235]
	v_pk_add_f32 v[4:5], v[4:5], v[232:233]
	v_lshlrev_b32_e32 v236, 16, v193
	v_and_b32_e32 v237, 0xffff0000, v193
	v_lshlrev_b32_e32 v238, 16, v197
	v_and_b32_e32 v239, 0xffff0000, v197
	v_pk_add_f32 v[236:237], v[236:237], v[238:239]
	v_pk_add_f32 v[6:7], v[6:7], v[236:237]
	v_lshlrev_b32_e32 v240, 16, v194
	v_and_b32_e32 v241, 0xffff0000, v194
	v_lshlrev_b32_e32 v242, 16, v198
	v_and_b32_e32 v243, 0xffff0000, v198
	v_pk_add_f32 v[240:241], v[240:241], v[242:243]
	v_pk_add_f32 v[0:1], v[0:1], v[240:241]
	v_lshlrev_b32_e32 v232, 16, v195
	v_and_b32_e32 v233, 0xffff0000, v195
	v_lshlrev_b32_e32 v234, 16, v199
	v_and_b32_e32 v235, 0xffff0000, v199
	v_pk_add_f32 v[232:233], v[232:233], v[234:235]
	v_pk_add_f32 v[2:3], v[2:3], v[232:233]
	global_store_dwordx4 v147, v[4:7], s[14:15] offset:512
	global_store_dwordx4 v147, v[0:3], s[14:15] offset:528
	s_and_b64 vcc, exec, s[0:1]
	s_mov_b64 s[0:1], -1
	s_cbranch_vccnz .LBB0_1013
	s_andn2_b64 vcc, exec, s[4:5]
	s_cbranch_vccnz .LBB0_1012
	s_barrier
	s_branch .LBB0_1012
